# E12 + MFMA issue order within each 16-group changed so the weight fragment operand is stationary for 4 consecutive MFMAs (all 8 K-loops)
# speedup vs baseline: 1.0010x; 1.0010x over previous
; #define PG8_STAGE(bufoff, gbase, voff) do { _Pragma("unroll") for (int _i = 0; _i < 2; ++_i) \
;         __builtin_amdgcn_global_load_lds((const unsigned*)((const char*)(gbase) + (voff)[_i]), (LAS unsigned*)(lds + (bufoff) + ldsw + _i * 8192), 16, 0, 0); } while (0)
; #define PG8_LDA(dst, b, h) do { _Pragma("unroll") for (int m = 0; m < 4; ++m) _Pragma("unroll") for (int k = 0; k < 2; ++k) dst[m][k] = *(const LAS bf16x8*)(pA + PG8_SA(b, h) + m * 2048 + k * 1024); } while (0)
; #define PG8_LDB(dst, b, h) do { _Pragma("unroll") for (int n = 0; n < 2; ++n) _Pragma("unroll") for (int k = 0; k < 2; ++k) dst[n][k] = *(const LAS bf16x8*)(pB + (PG8_SB(b, h) - 4 * HTB) + n * 2048 + k * 1024); } while (0)
; #define PG8_MMA(ai, bj, At, Bt) do { __builtin_amdgcn_s_setprio(1); _Pragma("unroll") for (int m = 0; m < 4; ++m) _Pragma("unroll") for (int n = 0; n < 2; ++n) _Pragma("unroll") for (int k = 0; k < 2; ++k) \
;         acc[ai][bj][m][n] = __builtin_amdgcn_mfma_f32_16x16x32_bf16(Bt[n][k], At[m][k], acc[ai][bj][m][n], 0, 0, 0); __builtin_amdgcn_s_setprio(0); } while (0)
; #define PG8_WAIT_V(n) asm volatile("s_waitcnt vmcnt(" #n ")" ::: "memory")
; #define PG8_WAIT_L(n) asm volatile("s_waitcnt lgkmcnt(" #n ")" ::: "memory")
; #define PG8_BAR __builtin_amdgcn_s_barrier()
; #define PG8_SCHED __builtin_amdgcn_sched_barrier(0)
; template <class Desc, class Epi, bool ALIGN_EPI>
; __device__ __forceinline__ void gemm_phase(LAS unsigned char* lds, const Desc& D, const Epi& E, int G, int c) {
;     ...
;             PG8_LDB(B0, 0, 0); PG8_LDB(B1, 0, 1); PG8_SCHED; PG8_LDA(At, 0, 0); PG8_STAGE(PG8_SA(1, 1), a1 + hstepA, voffA);
;             PG8_WAIT_V(8); PG8_WAIT_L(0); PG8_BAR; PG8_MMA(0, 0, At, B0); PG8_MMA(0, 1, At, B1); PG8_BAR; PG8_SCHED;
;             PG8_LDA(At, 0, 1); PG8_STAGE(PG8_SB(0, 0), b2, voffB); PG8_STAGE(PG8_SB(0, 1), b2 + hstepB, voffB); PG8_STAGE(PG8_SA(0, 0), a2, voffA);
;             PG8_WAIT_V(8); PG8_WAIT_L(0); PG8_BAR; PG8_MMA(1, 0, At, B0); PG8_MMA(1, 1, At, B1); PG8_BAR; PG8_SCHED;
.LBB0_172:
	s_or_b32 s14, s17, 1
	s_lshl_b64 s[26:27], s[14:15], 7
	s_add_i32 s14, s17, 2
	s_lshl_b64 s[40:41], s[14:15], 7
	s_add_u32 s17, s12, s40
	ds_read_b128 v[134:137], v169
	ds_read_b128 v[138:141], v169 offset:1024
	ds_read_b128 v[142:145], v169 offset:2048
	ds_read_b128 v[146:149], v169 offset:3072
	ds_read_b128 v[160:163], v169 offset:16384
	ds_read_b128 v[164:167], v169 offset:17408
	ds_read_b128 v[174:177], v169 offset:18432
	ds_read_b128 v[178:181], v169 offset:19456
	s_addc_u32 s21, s13, s41
	s_and_b64 s[38:39], s[30:31], exec
	s_cselect_b32 s39, s61, s21
	s_cselect_b32 s38, s60, s17
	s_add_u32 s17, s18, s40
	s_addc_u32 s21, s19, s41
	s_and_b64 s[30:31], s[30:31], exec
	s_cselect_b32 s31, s63, s21
	s_cselect_b32 s30, s62, s17
	s_add_u32 s17, s12, s26
	s_addc_u32 s21, s13, s27
	s_add_u32 s26, s17, 0x100000
	s_addc_u32 s27, s21, 0
	s_mov_b32 m0, s50
	v_lshl_add_u64 v[150:151], s[26:27], 0, v[152:153]
	ds_read_b128 v[182:185], v168
	ds_read_b128 v[186:189], v168 offset:1024
	ds_read_b128 v[190:193], v168 offset:2048
	ds_read_b128 v[194:197], v168 offset:3072
	ds_read_b128 v[198:201], v168 offset:4096
	ds_read_b128 v[202:205], v168 offset:5120
	ds_read_b128 v[206:209], v168 offset:6144
	ds_read_b128 v[210:213], v168 offset:7168
	global_load_lds_dwordx4 v[150:151], off
	v_lshl_add_u64 v[150:151], s[26:27], 0, v[156:157]
	s_mov_b32 m0, s51
	s_nop 0
	global_load_lds_dwordx4 v[150:151], off
	s_waitcnt vmcnt(8)
	s_waitcnt lgkmcnt(0)
	s_barrier
	v_mfma_f32_16x16x32_bf16 v[128:131], v[134:137], v[182:185], v[128:131]
	v_mfma_f32_16x16x32_bf16 v[120:123], v[134:137], v[190:193], v[120:123]
	v_mfma_f32_16x16x32_bf16 v[112:115], v[134:137], v[198:201], v[112:115]
	v_mfma_f32_16x16x32_bf16 v[104:107], v[134:137], v[206:209], v[104:107]
	v_mfma_f32_16x16x32_bf16 v[124:127], v[142:145], v[182:185], v[124:127]
	v_mfma_f32_16x16x32_bf16 v[116:119], v[142:145], v[190:193], v[116:119]
	v_mfma_f32_16x16x32_bf16 v[108:111], v[142:145], v[198:201], v[108:111]
	v_mfma_f32_16x16x32_bf16 v[100:103], v[142:145], v[206:209], v[100:103]
	v_mfma_f32_16x16x32_bf16 v[128:131], v[138:141], v[186:189], v[128:131]
	v_mfma_f32_16x16x32_bf16 v[120:123], v[138:141], v[194:197], v[120:123]
	v_mfma_f32_16x16x32_bf16 v[112:115], v[138:141], v[202:205], v[112:115]
	v_mfma_f32_16x16x32_bf16 v[104:107], v[138:141], v[210:213], v[104:107]
	v_mfma_f32_16x16x32_bf16 v[124:127], v[146:149], v[186:189], v[124:127]
	v_mfma_f32_16x16x32_bf16 v[116:119], v[146:149], v[194:197], v[116:119]
	v_mfma_f32_16x16x32_bf16 v[108:111], v[146:149], v[202:205], v[108:111]
	v_mfma_f32_16x16x32_bf16 v[100:103], v[146:149], v[210:213], v[100:103]
	v_mfma_f32_16x16x32_bf16 v[96:99], v[160:163], v[182:185], v[96:99]
	v_mfma_f32_16x16x32_bf16 v[88:91], v[160:163], v[190:193], v[88:91]
	v_mfma_f32_16x16x32_bf16 v[80:83], v[160:163], v[198:201], v[80:83]
	v_mfma_f32_16x16x32_bf16 v[72:75], v[160:163], v[206:209], v[72:75]
	v_mfma_f32_16x16x32_bf16 v[92:95], v[174:177], v[182:185], v[92:95]
	v_mfma_f32_16x16x32_bf16 v[84:87], v[174:177], v[190:193], v[84:87]
	v_mfma_f32_16x16x32_bf16 v[76:79], v[174:177], v[198:201], v[76:79]
	v_mfma_f32_16x16x32_bf16 v[68:71], v[174:177], v[206:209], v[68:71]
	v_mfma_f32_16x16x32_bf16 v[96:99], v[164:167], v[186:189], v[96:99]
	v_mfma_f32_16x16x32_bf16 v[88:91], v[164:167], v[194:197], v[88:91]
	v_mfma_f32_16x16x32_bf16 v[80:83], v[164:167], v[202:205], v[80:83]
	v_mfma_f32_16x16x32_bf16 v[72:75], v[164:167], v[210:213], v[72:75]
	v_mfma_f32_16x16x32_bf16 v[92:95], v[178:181], v[186:189], v[92:95]
	v_mfma_f32_16x16x32_bf16 v[84:87], v[178:181], v[194:197], v[84:87]
	v_mfma_f32_16x16x32_bf16 v[76:79], v[178:181], v[202:205], v[76:79]
	v_mfma_f32_16x16x32_bf16 v[68:71], v[178:181], v[210:213], v[68:71]
	s_barrier
	s_mov_b32 m0, s84
	v_lshl_add_u64 v[150:151], s[30:31], 0, v[154:155]
	s_add_u32 s26, s30, 0x100000
	ds_read_b128 v[182:185], v168 offset:16384
	ds_read_b128 v[186:189], v168 offset:17408
	ds_read_b128 v[190:193], v168 offset:18432
	ds_read_b128 v[194:197], v168 offset:19456
	ds_read_b128 v[198:201], v168 offset:20480
	ds_read_b128 v[202:205], v168 offset:21504
	ds_read_b128 v[206:209], v168 offset:22528
	ds_read_b128 v[210:213], v168 offset:23552
	global_load_lds_dwordx4 v[150:151], off
	v_lshl_add_u64 v[214:215], s[30:31], 0, v[158:159]
	s_mov_b32 m0, s85
	s_addc_u32 s27, s31, 0
	global_load_lds_dwordx4 v[214:215], off
	v_lshl_add_u64 v[216:217], s[26:27], 0, v[154:155]
	s_mov_b32 m0, s86
	v_lshl_add_u64 v[218:219], s[38:39], 0, v[156:157]
	global_load_lds_dwordx4 v[216:217], off
	v_lshl_add_u64 v[216:217], s[26:27], 0, v[158:159]
	s_mov_b32 m0, s87
	s_nop 0
	global_load_lds_dwordx4 v[216:217], off
	v_lshl_add_u64 v[216:217], s[38:39], 0, v[152:153]
	s_mov_b32 m0, s83
	s_nop 0
	global_load_lds_dwordx4 v[216:217], off
	s_mov_b32 m0, s88
	s_nop 0
	global_load_lds_dwordx4 v[218:219], off
	s_waitcnt vmcnt(8)
	s_waitcnt lgkmcnt(0)
	s_barrier
; #define PG8_STAGE(bufoff, gbase, voff) do { _Pragma("unroll") for (int _i = 0; _i < 2; ++_i) \
;         __builtin_amdgcn_global_load_lds((const unsigned*)((const char*)(gbase) + (voff)[_i]), (LAS unsigned*)(lds + (bufoff) + ldsw + _i * 8192), 16, 0, 0); } while (0)
; #define PG8_LDA(dst, b, h) do { _Pragma("unroll") for (int m = 0; m < 4; ++m) _Pragma("unroll") for (int k = 0; k < 2; ++k) dst[m][k] = *(const LAS bf16x8*)(pA + PG8_SA(b, h) + m * 2048 + k * 1024); } while (0)
; #define PG8_LDB(dst, b, h) do { _Pragma("unroll") for (int n = 0; n < 2; ++n) _Pragma("unroll") for (int k = 0; k < 2; ++k) dst[n][k] = *(const LAS bf16x8*)(pB + (PG8_SB(b, h) - 4 * HTB) + n * 2048 + k * 1024); } while (0)
; #define PG8_MMA(ai, bj, At, Bt) do { __builtin_amdgcn_s_setprio(1); _Pragma("unroll") for (int m = 0; m < 4; ++m) _Pragma("unroll") for (int n = 0; n < 2; ++n) _Pragma("unroll") for (int k = 0; k < 2; ++k) \
;         acc[ai][bj][m][n] = __builtin_amdgcn_mfma_f32_16x16x32_bf16(Bt[n][k], At[m][k], acc[ai][bj][m][n], 0, 0, 0); __builtin_amdgcn_s_setprio(0); } while (0)
; #define PG8_WAIT_V(n) asm volatile("s_waitcnt vmcnt(" #n ")" ::: "memory")
; #define PG8_WAIT_L(n) asm volatile("s_waitcnt lgkmcnt(" #n ")" ::: "memory")
; #define PG8_BAR __builtin_amdgcn_s_barrier()
; #define PG8_SCHED __builtin_amdgcn_sched_barrier(0)
; template <class Desc, class Epi, bool ALIGN_EPI>
; __device__ __forceinline__ void gemm_phase(LAS unsigned char* lds, const Desc& D, const Epi& E, int G, int c) {
;     ...
;             PG8_WAIT_V(8); PG8_WAIT_L(0); PG8_BAR; PG8_MMA(1, 0, At, B0); PG8_MMA(1, 1, At, B1); PG8_BAR; PG8_SCHED;
;             PG8_LDB(B0, 1, 0); PG8_LDB(B1, 1, 1); PG8_SCHED; PG8_LDA(At, 1, 0); PG8_STAGE(PG8_SA(0, 1), a2 + hstepA, voffA);
;             PG8_WAIT_V(8); PG8_WAIT_L(0); PG8_BAR; PG8_MMA(0, 0, At, B0); PG8_MMA(0, 1, At, B1); PG8_BAR; PG8_SCHED;
	v_mfma_f32_16x16x32_bf16 v[64:67], v[134:137], v[182:185], v[64:67]
	v_mfma_f32_16x16x32_bf16 v[32:35], v[134:137], v[190:193], v[32:35]
	v_mfma_f32_16x16x32_bf16 v[16:19], v[134:137], v[198:201], v[16:19]
	v_mfma_f32_16x16x32_bf16 v[8:11], v[134:137], v[206:209], v[8:11]
	v_mfma_f32_16x16x32_bf16 v[52:55], v[142:145], v[182:185], v[52:55]
	v_mfma_f32_16x16x32_bf16 v[20:23], v[142:145], v[190:193], v[20:23]
	v_mfma_f32_16x16x32_bf16 v[12:15], v[142:145], v[198:201], v[12:15]
	v_mfma_f32_16x16x32_bf16 v[4:7], v[142:145], v[206:209], v[4:7]
	v_mfma_f32_16x16x32_bf16 v[64:67], v[138:141], v[186:189], v[64:67]
	v_mfma_f32_16x16x32_bf16 v[32:35], v[138:141], v[194:197], v[32:35]
	v_mfma_f32_16x16x32_bf16 v[16:19], v[138:141], v[202:205], v[16:19]
	v_mfma_f32_16x16x32_bf16 v[8:11], v[138:141], v[210:213], v[8:11]
	v_mfma_f32_16x16x32_bf16 v[52:55], v[146:149], v[186:189], v[52:55]
	v_mfma_f32_16x16x32_bf16 v[20:23], v[146:149], v[194:197], v[20:23]
	v_mfma_f32_16x16x32_bf16 v[12:15], v[146:149], v[202:205], v[12:15]
	v_mfma_f32_16x16x32_bf16 v[4:7], v[146:149], v[210:213], v[4:7]
	v_mfma_f32_16x16x32_bf16 v[60:63], v[160:163], v[182:185], v[60:63]
	v_mfma_f32_16x16x32_bf16 v[48:51], v[160:163], v[190:193], v[48:51]
	v_mfma_f32_16x16x32_bf16 v[40:43], v[160:163], v[198:201], v[40:43]
	v_mfma_f32_16x16x32_bf16 v[28:31], v[160:163], v[206:209], v[28:31]
	v_mfma_f32_16x16x32_bf16 v[56:59], v[174:177], v[182:185], v[56:59]
	v_mfma_f32_16x16x32_bf16 v[44:47], v[174:177], v[190:193], v[44:47]
	v_mfma_f32_16x16x32_bf16 v[36:39], v[174:177], v[198:201], v[36:39]
	v_mfma_f32_16x16x32_bf16 v[24:27], v[174:177], v[206:209], v[24:27]
	v_mfma_f32_16x16x32_bf16 v[60:63], v[164:167], v[186:189], v[60:63]
	v_mfma_f32_16x16x32_bf16 v[48:51], v[164:167], v[194:197], v[48:51]
	v_mfma_f32_16x16x32_bf16 v[40:43], v[164:167], v[202:205], v[40:43]
	v_mfma_f32_16x16x32_bf16 v[28:31], v[164:167], v[210:213], v[28:31]
	v_mfma_f32_16x16x32_bf16 v[56:59], v[178:181], v[186:189], v[56:59]
	v_mfma_f32_16x16x32_bf16 v[44:47], v[178:181], v[194:197], v[44:47]
	v_mfma_f32_16x16x32_bf16 v[36:39], v[178:181], v[202:205], v[36:39]
	v_mfma_f32_16x16x32_bf16 v[24:27], v[178:181], v[210:213], v[24:27]
	s_barrier
	ds_read_b128 v[134:137], v169 offset:32768
	ds_read_b128 v[138:141], v169 offset:33792
	ds_read_b128 v[142:145], v169 offset:34816
	ds_read_b128 v[146:149], v169 offset:35840
	ds_read_b128 v[160:163], v169 offset:49152
	ds_read_b128 v[164:167], v169 offset:50176
	ds_read_b128 v[174:177], v169 offset:51200
	ds_read_b128 v[178:181], v169 offset:52224
	s_add_u32 s26, s38, 0x100000
	s_addc_u32 s27, s39, 0
	s_mov_b32 m0, s89
	v_lshl_add_u64 v[220:221], s[26:27], 0, v[152:153]
	ds_read_b128 v[182:185], v168 offset:32768
	ds_read_b128 v[186:189], v168 offset:33792
	ds_read_b128 v[190:193], v168 offset:34816
	ds_read_b128 v[194:197], v168 offset:35840
	ds_read_b128 v[198:201], v168 offset:36864
	ds_read_b128 v[202:205], v168 offset:37888
	ds_read_b128 v[206:209], v168 offset:38912
	ds_read_b128 v[210:213], v168 offset:39936
	global_load_lds_dwordx4 v[220:221], off
	v_lshl_add_u64 v[220:221], s[26:27], 0, v[156:157]
	s_mov_b32 m0, s90
	s_nop 0
	global_load_lds_dwordx4 v[220:221], off
	s_waitcnt vmcnt(8)
	s_waitcnt lgkmcnt(0)
	s_barrier
	v_mfma_f32_16x16x32_bf16 v[128:131], v[134:137], v[182:185], v[128:131]
	v_mfma_f32_16x16x32_bf16 v[120:123], v[134:137], v[190:193], v[120:123]
	v_mfma_f32_16x16x32_bf16 v[112:115], v[134:137], v[198:201], v[112:115]
	v_mfma_f32_16x16x32_bf16 v[104:107], v[134:137], v[206:209], v[104:107]
	v_mfma_f32_16x16x32_bf16 v[124:127], v[142:145], v[182:185], v[124:127]
	v_mfma_f32_16x16x32_bf16 v[116:119], v[142:145], v[190:193], v[116:119]
	v_mfma_f32_16x16x32_bf16 v[108:111], v[142:145], v[198:201], v[108:111]
	v_mfma_f32_16x16x32_bf16 v[100:103], v[142:145], v[206:209], v[100:103]
	v_mfma_f32_16x16x32_bf16 v[128:131], v[138:141], v[186:189], v[128:131]
	v_mfma_f32_16x16x32_bf16 v[120:123], v[138:141], v[194:197], v[120:123]
	v_mfma_f32_16x16x32_bf16 v[112:115], v[138:141], v[202:205], v[112:115]
	v_mfma_f32_16x16x32_bf16 v[104:107], v[138:141], v[210:213], v[104:107]
	v_mfma_f32_16x16x32_bf16 v[124:127], v[146:149], v[186:189], v[124:127]
	v_mfma_f32_16x16x32_bf16 v[116:119], v[146:149], v[194:197], v[116:119]
	v_mfma_f32_16x16x32_bf16 v[108:111], v[146:149], v[202:205], v[108:111]
	v_mfma_f32_16x16x32_bf16 v[100:103], v[146:149], v[210:213], v[100:103]
	v_mfma_f32_16x16x32_bf16 v[96:99], v[160:163], v[182:185], v[96:99]
	v_mfma_f32_16x16x32_bf16 v[88:91], v[160:163], v[190:193], v[88:91]
	v_mfma_f32_16x16x32_bf16 v[80:83], v[160:163], v[198:201], v[80:83]
	v_mfma_f32_16x16x32_bf16 v[72:75], v[160:163], v[206:209], v[72:75]
	v_mfma_f32_16x16x32_bf16 v[92:95], v[174:177], v[182:185], v[92:95]
	v_mfma_f32_16x16x32_bf16 v[84:87], v[174:177], v[190:193], v[84:87]
	v_mfma_f32_16x16x32_bf16 v[76:79], v[174:177], v[198:201], v[76:79]
	v_mfma_f32_16x16x32_bf16 v[68:71], v[174:177], v[206:209], v[68:71]
	v_mfma_f32_16x16x32_bf16 v[96:99], v[164:167], v[186:189], v[96:99]
	v_mfma_f32_16x16x32_bf16 v[88:91], v[164:167], v[194:197], v[88:91]
	v_mfma_f32_16x16x32_bf16 v[80:83], v[164:167], v[202:205], v[80:83]
	v_mfma_f32_16x16x32_bf16 v[72:75], v[164:167], v[210:213], v[72:75]
	v_mfma_f32_16x16x32_bf16 v[92:95], v[178:181], v[186:189], v[92:95]
	v_mfma_f32_16x16x32_bf16 v[84:87], v[178:181], v[194:197], v[84:87]
	v_mfma_f32_16x16x32_bf16 v[76:79], v[178:181], v[202:205], v[76:79]
	v_mfma_f32_16x16x32_bf16 v[68:71], v[178:181], v[210:213], v[68:71]
	s_barrier
; #define PG8_STAGE(bufoff, gbase, voff) do { _Pragma("unroll") for (int _i = 0; _i < 2; ++_i) \
;         __builtin_amdgcn_global_load_lds((const unsigned*)((const char*)(gbase) + (voff)[_i]), (LAS unsigned*)(lds + (bufoff) + ldsw + _i * 8192), 16, 0, 0); } while (0)
; #define PG8_LDA(dst, b, h) do { _Pragma("unroll") for (int m = 0; m < 4; ++m) _Pragma("unroll") for (int k = 0; k < 2; ++k) dst[m][k] = *(const LAS bf16x8*)(pA + PG8_SA(b, h) + m * 2048 + k * 1024); } while (0)
; #define PG8_MMA(ai, bj, At, Bt) do { __builtin_amdgcn_s_setprio(1); _Pragma("unroll") for (int m = 0; m < 4; ++m) _Pragma("unroll") for (int n = 0; n < 2; ++n) _Pragma("unroll") for (int k = 0; k < 2; ++k) \
;         acc[ai][bj][m][n] = __builtin_amdgcn_mfma_f32_16x16x32_bf16(Bt[n][k], At[m][k], acc[ai][bj][m][n], 0, 0, 0); __builtin_amdgcn_s_setprio(0); } while (0)
; #define PG8_WAIT_V(n) asm volatile("s_waitcnt vmcnt(" #n ")" ::: "memory")
; #define PG8_WAIT_L(n) asm volatile("s_waitcnt lgkmcnt(" #n ")" ::: "memory")
; #define PG8_BAR __builtin_amdgcn_s_barrier()
; #define PG8_SCHED __builtin_amdgcn_sched_barrier(0)
; template <class Desc, class Epi, bool ALIGN_EPI>
; __device__ __forceinline__ void gemm_phase(LAS unsigned char* lds, const Desc& D, const Epi& E, int G, int c) {
;     ...
;             PG8_LDA(At, 1, 1); PG8_STAGE(PG8_SB(1, 0), b3, voffB); PG8_STAGE(PG8_SB(1, 1), b3 + hstepB, voffB); PG8_STAGE(PG8_SA(1, 0), a3, voffA);
;             PG8_WAIT_V(8); PG8_WAIT_L(0); PG8_BAR; PG8_MMA(1, 0, At, B0); PG8_MMA(1, 1, At, B1); PG8_BAR; PG8_SCHED;
;         }
	s_mov_b32 m0, s92
	v_lshl_add_u64 v[150:151], v[150:151], 0, s[76:77]
	s_add_u32 s26, s30, 0x100080
	ds_read_b128 v[182:185], v168 offset:49152
	ds_read_b128 v[186:189], v168 offset:50176
	ds_read_b128 v[190:193], v168 offset:51200
	ds_read_b128 v[194:197], v168 offset:52224
	ds_read_b128 v[198:201], v168 offset:53248
	ds_read_b128 v[202:205], v168 offset:54272
	ds_read_b128 v[206:209], v168 offset:55296
	ds_read_b128 v[210:213], v168 offset:56320
	global_load_lds_dwordx4 v[150:151], off
	v_lshl_add_u64 v[150:151], v[214:215], 0, s[76:77]
	s_mov_b32 m0, s93
	s_addc_u32 s27, s31, 0
	global_load_lds_dwordx4 v[150:151], off
	v_lshl_add_u64 v[150:151], s[26:27], 0, v[154:155]
	s_mov_b32 m0, s97
	s_nop 0
	global_load_lds_dwordx4 v[150:151], off
	v_lshl_add_u64 v[150:151], s[26:27], 0, v[158:159]
	s_mov_b32 m0, s82
	s_nop 0
	global_load_lds_dwordx4 v[150:151], off
	v_lshl_add_u64 v[150:151], v[216:217], 0, s[76:77]
	s_mov_b32 m0, s94
	s_nop 0
	global_load_lds_dwordx4 v[150:151], off
	v_lshl_add_u64 v[150:151], v[218:219], 0, s[76:77]
	s_mov_b32 m0, s95
	s_nop 0
	global_load_lds_dwordx4 v[150:151], off
	s_waitcnt vmcnt(8)
	s_waitcnt lgkmcnt(0)
	s_barrier
	v_mfma_f32_16x16x32_bf16 v[64:67], v[134:137], v[182:185], v[64:67]
	v_mfma_f32_16x16x32_bf16 v[32:35], v[134:137], v[190:193], v[32:35]
	v_mfma_f32_16x16x32_bf16 v[16:19], v[134:137], v[198:201], v[16:19]
	v_mfma_f32_16x16x32_bf16 v[8:11], v[134:137], v[206:209], v[8:11]
	v_mfma_f32_16x16x32_bf16 v[52:55], v[142:145], v[182:185], v[52:55]
	v_mfma_f32_16x16x32_bf16 v[20:23], v[142:145], v[190:193], v[20:23]
	v_mfma_f32_16x16x32_bf16 v[12:15], v[142:145], v[198:201], v[12:15]
	v_mfma_f32_16x16x32_bf16 v[4:7], v[142:145], v[206:209], v[4:7]
	v_mfma_f32_16x16x32_bf16 v[64:67], v[138:141], v[186:189], v[64:67]
	v_mfma_f32_16x16x32_bf16 v[32:35], v[138:141], v[194:197], v[32:35]
	v_mfma_f32_16x16x32_bf16 v[16:19], v[138:141], v[202:205], v[16:19]
	v_mfma_f32_16x16x32_bf16 v[8:11], v[138:141], v[210:213], v[8:11]
	v_mfma_f32_16x16x32_bf16 v[52:55], v[146:149], v[186:189], v[52:55]
	v_mfma_f32_16x16x32_bf16 v[20:23], v[146:149], v[194:197], v[20:23]
	v_mfma_f32_16x16x32_bf16 v[12:15], v[146:149], v[202:205], v[12:15]
	v_mfma_f32_16x16x32_bf16 v[4:7], v[146:149], v[210:213], v[4:7]
	v_mfma_f32_16x16x32_bf16 v[60:63], v[160:163], v[182:185], v[60:63]
	v_mfma_f32_16x16x32_bf16 v[48:51], v[160:163], v[190:193], v[48:51]
	v_mfma_f32_16x16x32_bf16 v[40:43], v[160:163], v[198:201], v[40:43]
	v_mfma_f32_16x16x32_bf16 v[28:31], v[160:163], v[206:209], v[28:31]
	v_mfma_f32_16x16x32_bf16 v[56:59], v[174:177], v[182:185], v[56:59]
	v_mfma_f32_16x16x32_bf16 v[44:47], v[174:177], v[190:193], v[44:47]
	v_mfma_f32_16x16x32_bf16 v[36:39], v[174:177], v[198:201], v[36:39]
	v_mfma_f32_16x16x32_bf16 v[24:27], v[174:177], v[206:209], v[24:27]
	v_mfma_f32_16x16x32_bf16 v[60:63], v[164:167], v[186:189], v[60:63]
	v_mfma_f32_16x16x32_bf16 v[48:51], v[164:167], v[194:197], v[48:51]
	v_mfma_f32_16x16x32_bf16 v[40:43], v[164:167], v[202:205], v[40:43]
	v_mfma_f32_16x16x32_bf16 v[28:31], v[164:167], v[210:213], v[28:31]
	v_mfma_f32_16x16x32_bf16 v[56:59], v[178:181], v[186:189], v[56:59]
	v_mfma_f32_16x16x32_bf16 v[44:47], v[178:181], v[194:197], v[44:47]
	v_mfma_f32_16x16x32_bf16 v[36:39], v[178:181], v[202:205], v[36:39]
	v_mfma_f32_16x16x32_bf16 v[24:27], v[178:181], v[210:213], v[24:27]
	s_barrier
	s_cmp_ge_u32 s14, s3
	s_mov_b32 s17, s14
	s_cbranch_scc1 .LBB0_183

; #define PG8_STAGE(bufoff, gbase, voff) do { _Pragma("unroll") for (int _i = 0; _i < 2; ++_i) \
;         __builtin_amdgcn_global_load_lds((const unsigned*)((const char*)(gbase) + (voff)[_i]), (LAS unsigned*)(lds + (bufoff) + ldsw + _i * 8192), 16, 0, 0); } while (0)
; #define PG8_LDA(dst, b, h) do { _Pragma("unroll") for (int m = 0; m < 4; ++m) _Pragma("unroll") for (int k = 0; k < 2; ++k) dst[m][k] = *(const LAS bf16x8*)(pA + PG8_SA(b, h) + m * 2048 + k * 1024); } while (0)
; #define PG8_LDB(dst, b, h) do { _Pragma("unroll") for (int n = 0; n < 2; ++n) _Pragma("unroll") for (int k = 0; k < 2; ++k) dst[n][k] = *(const LAS bf16x8*)(pB + (PG8_SB(b, h) - 4 * HTB) + n * 2048 + k * 1024); } while (0)
; #define PG8_MMA(ai, bj, At, Bt) do { __builtin_amdgcn_s_setprio(1); _Pragma("unroll") for (int m = 0; m < 4; ++m) _Pragma("unroll") for (int n = 0; n < 2; ++n) _Pragma("unroll") for (int k = 0; k < 2; ++k) \
;         acc[ai][bj][m][n] = __builtin_amdgcn_mfma_f32_16x16x32_bf16(Bt[n][k], At[m][k], acc[ai][bj][m][n], 0, 0, 0); __builtin_amdgcn_s_setprio(0); } while (0)
; #define PG8_WAIT_V(n) asm volatile("s_waitcnt vmcnt(" #n ")" ::: "memory")
; #define PG8_WAIT_L(n) asm volatile("s_waitcnt lgkmcnt(" #n ")" ::: "memory")
; #define PG8_BAR __builtin_amdgcn_s_barrier()
; #define PG8_SCHED __builtin_amdgcn_sched_barrier(0)
; template <class Desc, class Epi, bool ALIGN_EPI>
; __device__ __forceinline__ void gemm_phase(LAS unsigned char* lds, const Desc& D, const Epi& E, int G, int c) {
;     ...
;             PG8_LDB(B0, 0, 0); PG8_LDB(B1, 0, 1); PG8_SCHED; PG8_LDA(At, 0, 0); PG8_STAGE(PG8_SA(1, 1), a1 + hstepA, voffA);
;             PG8_WAIT_V(8); PG8_WAIT_L(0); PG8_BAR; PG8_MMA(0, 0, At, B0); PG8_MMA(0, 1, At, B1); PG8_BAR; PG8_SCHED;
;             PG8_LDA(At, 0, 1); PG8_STAGE(PG8_SB(0, 0), b2, voffB); PG8_STAGE(PG8_SB(0, 1), b2 + hstepB, voffB); PG8_STAGE(PG8_SA(0, 0), a2, voffA);
;             PG8_WAIT_V(8); PG8_WAIT_L(0); PG8_BAR; PG8_MMA(1, 0, At, B0); PG8_MMA(1, 1, At, B1); PG8_BAR; PG8_SCHED;
.LBB0_603:
	ds_read_b128 v[144:147], v149
	ds_read_b128 v[152:155], v149 offset:1024
	ds_read_b128 v[156:159], v149 offset:2048
	ds_read_b128 v[160:163], v149 offset:3072
	ds_read_b128 v[164:167], v149 offset:16384
	ds_read_b128 v[168:171], v149 offset:17408
	ds_read_b128 v[172:175], v149 offset:18432
	ds_read_b128 v[176:179], v149 offset:19456
	s_add_u32 s16, s12, 0xfff80080
	s_addc_u32 s17, s13, -1
	s_cmp_eq_u32 s46, 4
	s_cselect_b32 s19, s9, s17
	s_cselect_b32 s18, s8, s16
	s_cselect_b32 s17, s11, s45
	s_cselect_b32 s16, s10, s7
	v_lshl_add_u64 v[212:213], s[12:13], 0, v[140:141]
	s_add_i32 m0, s20, 0xc000
	ds_read_b128 v[180:183], v148
	ds_read_b128 v[184:187], v148 offset:1024
	ds_read_b128 v[188:191], v148 offset:2048
	ds_read_b128 v[192:195], v148 offset:3072
	ds_read_b128 v[196:199], v148 offset:4096
	ds_read_b128 v[200:203], v148 offset:5120
	ds_read_b128 v[204:207], v148 offset:6144
	ds_read_b128 v[208:211], v148 offset:7168
	global_load_lds_dwordx4 v[212:213], off
	v_lshl_add_u64 v[212:213], s[12:13], 0, v[142:143]
	s_add_i32 m0, s20, 0xe000
	s_nop 0
	global_load_lds_dwordx4 v[212:213], off
	s_waitcnt vmcnt(8)
	s_waitcnt lgkmcnt(0)
	s_barrier
	v_mfma_f32_16x16x32_bf16 v[128:131], v[144:147], v[180:183], v[128:131]
	v_mfma_f32_16x16x32_bf16 v[116:119], v[144:147], v[188:191], v[116:119]
	v_mfma_f32_16x16x32_bf16 v[100:103], v[144:147], v[196:199], v[100:103]
	v_mfma_f32_16x16x32_bf16 v[84:87], v[144:147], v[204:207], v[84:87]
	v_mfma_f32_16x16x32_bf16 v[124:127], v[156:159], v[180:183], v[124:127]
	v_mfma_f32_16x16x32_bf16 v[108:111], v[156:159], v[188:191], v[108:111]
	v_mfma_f32_16x16x32_bf16 v[92:95], v[156:159], v[196:199], v[92:95]
	v_mfma_f32_16x16x32_bf16 v[76:79], v[156:159], v[204:207], v[76:79]
	v_mfma_f32_16x16x32_bf16 v[128:131], v[152:155], v[184:187], v[128:131]
	v_mfma_f32_16x16x32_bf16 v[116:119], v[152:155], v[192:195], v[116:119]
	v_mfma_f32_16x16x32_bf16 v[100:103], v[152:155], v[200:203], v[100:103]
	v_mfma_f32_16x16x32_bf16 v[84:87], v[152:155], v[208:211], v[84:87]
	v_mfma_f32_16x16x32_bf16 v[124:127], v[160:163], v[184:187], v[124:127]
	v_mfma_f32_16x16x32_bf16 v[108:111], v[160:163], v[192:195], v[108:111]
	v_mfma_f32_16x16x32_bf16 v[92:95], v[160:163], v[200:203], v[92:95]
	v_mfma_f32_16x16x32_bf16 v[76:79], v[160:163], v[208:211], v[76:79]
	v_mfma_f32_16x16x32_bf16 v[120:123], v[164:167], v[180:183], v[120:123]
	v_mfma_f32_16x16x32_bf16 v[104:107], v[164:167], v[188:191], v[104:107]
	v_mfma_f32_16x16x32_bf16 v[88:91], v[164:167], v[196:199], v[88:91]
	v_mfma_f32_16x16x32_bf16 v[72:75], v[164:167], v[204:207], v[72:75]
	v_mfma_f32_16x16x32_bf16 v[112:115], v[172:175], v[180:183], v[112:115]
	v_mfma_f32_16x16x32_bf16 v[96:99], v[172:175], v[188:191], v[96:99]
	v_mfma_f32_16x16x32_bf16 v[80:83], v[172:175], v[196:199], v[80:83]
	v_mfma_f32_16x16x32_bf16 v[68:71], v[172:175], v[204:207], v[68:71]
	v_mfma_f32_16x16x32_bf16 v[120:123], v[168:171], v[184:187], v[120:123]
	v_mfma_f32_16x16x32_bf16 v[104:107], v[168:171], v[192:195], v[104:107]
	v_mfma_f32_16x16x32_bf16 v[88:91], v[168:171], v[200:203], v[88:91]
	v_mfma_f32_16x16x32_bf16 v[72:75], v[168:171], v[208:211], v[72:75]
	v_mfma_f32_16x16x32_bf16 v[112:115], v[176:179], v[184:187], v[112:115]
	v_mfma_f32_16x16x32_bf16 v[96:99], v[176:179], v[192:195], v[96:99]
	v_mfma_f32_16x16x32_bf16 v[80:83], v[176:179], v[200:203], v[80:83]
	v_mfma_f32_16x16x32_bf16 v[68:71], v[176:179], v[208:211], v[68:71]
	s_barrier
	s_mov_b32 m0, s21
	v_lshl_add_u64 v[212:213], s[16:17], 0, v[136:137]
	s_add_u32 s48, s16, 0x20000
	ds_read_b128 v[180:183], v148 offset:16384
	ds_read_b128 v[184:187], v148 offset:17408
	ds_read_b128 v[188:191], v148 offset:18432
	ds_read_b128 v[192:195], v148 offset:19456
	ds_read_b128 v[196:199], v148 offset:20480
	ds_read_b128 v[200:203], v148 offset:21504
	ds_read_b128 v[204:207], v148 offset:22528
	ds_read_b128 v[208:211], v148 offset:23552
	global_load_lds_dwordx4 v[212:213], off
	v_lshl_add_u64 v[214:215], s[16:17], 0, v[132:133]
	s_mov_b32 m0, s23
	s_addc_u32 s49, s17, 0
	global_load_lds_dwordx4 v[214:215], off
	v_lshl_add_u64 v[216:217], s[48:49], 0, v[136:137]
	s_mov_b32 m0, s24
	v_lshl_add_u64 v[218:219], s[18:19], 0, v[134:135]
	global_load_lds_dwordx4 v[216:217], off
	v_lshl_add_u64 v[216:217], s[48:49], 0, v[132:133]
	s_mov_b32 m0, s25
	s_nop 0
	global_load_lds_dwordx4 v[216:217], off
	v_lshl_add_u64 v[216:217], s[18:19], 0, v[138:139]
	s_mov_b32 m0, s20
	s_nop 0
	global_load_lds_dwordx4 v[216:217], off
	s_mov_b32 m0, s26
	s_nop 0
	global_load_lds_dwordx4 v[218:219], off
	s_waitcnt vmcnt(8)
	s_waitcnt lgkmcnt(0)
	s_barrier
; #define PG8_STAGE(bufoff, gbase, voff) do { _Pragma("unroll") for (int _i = 0; _i < 2; ++_i) \
;         __builtin_amdgcn_global_load_lds((const unsigned*)((const char*)(gbase) + (voff)[_i]), (LAS unsigned*)(lds + (bufoff) + ldsw + _i * 8192), 16, 0, 0); } while (0)
; #define PG8_LDA(dst, b, h) do { _Pragma("unroll") for (int m = 0; m < 4; ++m) _Pragma("unroll") for (int k = 0; k < 2; ++k) dst[m][k] = *(const LAS bf16x8*)(pA + PG8_SA(b, h) + m * 2048 + k * 1024); } while (0)
; #define PG8_LDB(dst, b, h) do { _Pragma("unroll") for (int n = 0; n < 2; ++n) _Pragma("unroll") for (int k = 0; k < 2; ++k) dst[n][k] = *(const LAS bf16x8*)(pB + (PG8_SB(b, h) - 4 * HTB) + n * 2048 + k * 1024); } while (0)
; #define PG8_MMA(ai, bj, At, Bt) do { __builtin_amdgcn_s_setprio(1); _Pragma("unroll") for (int m = 0; m < 4; ++m) _Pragma("unroll") for (int n = 0; n < 2; ++n) _Pragma("unroll") for (int k = 0; k < 2; ++k) \
;         acc[ai][bj][m][n] = __builtin_amdgcn_mfma_f32_16x16x32_bf16(Bt[n][k], At[m][k], acc[ai][bj][m][n], 0, 0, 0); __builtin_amdgcn_s_setprio(0); } while (0)
; #define PG8_WAIT_V(n) asm volatile("s_waitcnt vmcnt(" #n ")" ::: "memory")
; #define PG8_WAIT_L(n) asm volatile("s_waitcnt lgkmcnt(" #n ")" ::: "memory")
; #define PG8_BAR __builtin_amdgcn_s_barrier()
; #define PG8_SCHED __builtin_amdgcn_sched_barrier(0)
; template <class Desc, class Epi, bool ALIGN_EPI>
; __device__ __forceinline__ void gemm_phase(LAS unsigned char* lds, const Desc& D, const Epi& E, int G, int c) {
;     ...
;             PG8_WAIT_V(8); PG8_WAIT_L(0); PG8_BAR; PG8_MMA(1, 0, At, B0); PG8_MMA(1, 1, At, B1); PG8_BAR; PG8_SCHED;
;             PG8_LDB(B0, 1, 0); PG8_LDB(B1, 1, 1); PG8_SCHED; PG8_LDA(At, 1, 0); PG8_STAGE(PG8_SA(0, 1), a2 + hstepA, voffA);
;             PG8_WAIT_V(8); PG8_WAIT_L(0); PG8_BAR; PG8_MMA(0, 0, At, B0); PG8_MMA(0, 1, At, B1); PG8_BAR; PG8_SCHED;
	v_mfma_f32_16x16x32_bf16 v[64:67], v[144:147], v[180:183], v[64:67]
	v_mfma_f32_16x16x32_bf16 v[52:55], v[144:147], v[188:191], v[52:55]
	v_mfma_f32_16x16x32_bf16 v[36:39], v[144:147], v[196:199], v[36:39]
	v_mfma_f32_16x16x32_bf16 v[20:23], v[144:147], v[204:207], v[20:23]
	v_mfma_f32_16x16x32_bf16 v[60:63], v[156:159], v[180:183], v[60:63]
	v_mfma_f32_16x16x32_bf16 v[44:47], v[156:159], v[188:191], v[44:47]
	v_mfma_f32_16x16x32_bf16 v[28:31], v[156:159], v[196:199], v[28:31]
	v_mfma_f32_16x16x32_bf16 v[12:15], v[156:159], v[204:207], v[12:15]
	v_mfma_f32_16x16x32_bf16 v[64:67], v[152:155], v[184:187], v[64:67]
	v_mfma_f32_16x16x32_bf16 v[52:55], v[152:155], v[192:195], v[52:55]
	v_mfma_f32_16x16x32_bf16 v[36:39], v[152:155], v[200:203], v[36:39]
	v_mfma_f32_16x16x32_bf16 v[20:23], v[152:155], v[208:211], v[20:23]
	v_mfma_f32_16x16x32_bf16 v[60:63], v[160:163], v[184:187], v[60:63]
	v_mfma_f32_16x16x32_bf16 v[44:47], v[160:163], v[192:195], v[44:47]
	v_mfma_f32_16x16x32_bf16 v[28:31], v[160:163], v[200:203], v[28:31]
	v_mfma_f32_16x16x32_bf16 v[12:15], v[160:163], v[208:211], v[12:15]
	v_mfma_f32_16x16x32_bf16 v[56:59], v[164:167], v[180:183], v[56:59]
	v_mfma_f32_16x16x32_bf16 v[40:43], v[164:167], v[188:191], v[40:43]
	v_mfma_f32_16x16x32_bf16 v[24:27], v[164:167], v[196:199], v[24:27]
	v_mfma_f32_16x16x32_bf16 v[8:11], v[164:167], v[204:207], v[8:11]
	v_mfma_f32_16x16x32_bf16 v[48:51], v[172:175], v[180:183], v[48:51]
	v_mfma_f32_16x16x32_bf16 v[32:35], v[172:175], v[188:191], v[32:35]
	v_mfma_f32_16x16x32_bf16 v[16:19], v[172:175], v[196:199], v[16:19]
	v_mfma_f32_16x16x32_bf16 v[4:7], v[172:175], v[204:207], v[4:7]
	v_mfma_f32_16x16x32_bf16 v[56:59], v[168:171], v[184:187], v[56:59]
	v_mfma_f32_16x16x32_bf16 v[40:43], v[168:171], v[192:195], v[40:43]
	v_mfma_f32_16x16x32_bf16 v[24:27], v[168:171], v[200:203], v[24:27]
	v_mfma_f32_16x16x32_bf16 v[8:11], v[168:171], v[208:211], v[8:11]
	v_mfma_f32_16x16x32_bf16 v[48:51], v[176:179], v[184:187], v[48:51]
	v_mfma_f32_16x16x32_bf16 v[32:35], v[176:179], v[192:195], v[32:35]
	v_mfma_f32_16x16x32_bf16 v[16:19], v[176:179], v[200:203], v[16:19]
	v_mfma_f32_16x16x32_bf16 v[4:7], v[176:179], v[208:211], v[4:7]
	s_barrier
	ds_read_b128 v[144:147], v149 offset:32768
	ds_read_b128 v[152:155], v149 offset:33792
	ds_read_b128 v[156:159], v149 offset:34816
	ds_read_b128 v[160:163], v149 offset:35840
	ds_read_b128 v[164:167], v149 offset:49152
	ds_read_b128 v[168:171], v149 offset:50176
	ds_read_b128 v[172:175], v149 offset:51200
	ds_read_b128 v[176:179], v149 offset:52224
	s_add_u32 s18, s18, 0x80000
	s_addc_u32 s19, s19, 0
	s_mov_b32 m0, s27
	v_lshl_add_u64 v[220:221], s[18:19], 0, v[138:139]
	ds_read_b128 v[180:183], v148 offset:32768
	ds_read_b128 v[184:187], v148 offset:33792
	ds_read_b128 v[188:191], v148 offset:34816
	ds_read_b128 v[192:195], v148 offset:35840
	ds_read_b128 v[196:199], v148 offset:36864
	ds_read_b128 v[200:203], v148 offset:37888
	ds_read_b128 v[204:207], v148 offset:38912
	ds_read_b128 v[208:211], v148 offset:39936
	global_load_lds_dwordx4 v[220:221], off
	v_lshl_add_u64 v[220:221], s[18:19], 0, v[134:135]
	s_mov_b32 m0, s30
	s_nop 0
	global_load_lds_dwordx4 v[220:221], off
	s_waitcnt vmcnt(8)
	s_waitcnt lgkmcnt(0)
	s_barrier
	v_mfma_f32_16x16x32_bf16 v[128:131], v[144:147], v[180:183], v[128:131]
	v_mfma_f32_16x16x32_bf16 v[116:119], v[144:147], v[188:191], v[116:119]
	v_mfma_f32_16x16x32_bf16 v[100:103], v[144:147], v[196:199], v[100:103]
	v_mfma_f32_16x16x32_bf16 v[84:87], v[144:147], v[204:207], v[84:87]
	v_mfma_f32_16x16x32_bf16 v[124:127], v[156:159], v[180:183], v[124:127]
	v_mfma_f32_16x16x32_bf16 v[108:111], v[156:159], v[188:191], v[108:111]
	v_mfma_f32_16x16x32_bf16 v[92:95], v[156:159], v[196:199], v[92:95]
	v_mfma_f32_16x16x32_bf16 v[76:79], v[156:159], v[204:207], v[76:79]
	v_mfma_f32_16x16x32_bf16 v[128:131], v[152:155], v[184:187], v[128:131]
	v_mfma_f32_16x16x32_bf16 v[116:119], v[152:155], v[192:195], v[116:119]
	v_mfma_f32_16x16x32_bf16 v[100:103], v[152:155], v[200:203], v[100:103]
	v_mfma_f32_16x16x32_bf16 v[84:87], v[152:155], v[208:211], v[84:87]
	v_mfma_f32_16x16x32_bf16 v[124:127], v[160:163], v[184:187], v[124:127]
	v_mfma_f32_16x16x32_bf16 v[108:111], v[160:163], v[192:195], v[108:111]
	v_mfma_f32_16x16x32_bf16 v[92:95], v[160:163], v[200:203], v[92:95]
	v_mfma_f32_16x16x32_bf16 v[76:79], v[160:163], v[208:211], v[76:79]
	v_mfma_f32_16x16x32_bf16 v[120:123], v[164:167], v[180:183], v[120:123]
	v_mfma_f32_16x16x32_bf16 v[104:107], v[164:167], v[188:191], v[104:107]
	v_mfma_f32_16x16x32_bf16 v[88:91], v[164:167], v[196:199], v[88:91]
	v_mfma_f32_16x16x32_bf16 v[72:75], v[164:167], v[204:207], v[72:75]
	v_mfma_f32_16x16x32_bf16 v[112:115], v[172:175], v[180:183], v[112:115]
	v_mfma_f32_16x16x32_bf16 v[96:99], v[172:175], v[188:191], v[96:99]
	v_mfma_f32_16x16x32_bf16 v[80:83], v[172:175], v[196:199], v[80:83]
	v_mfma_f32_16x16x32_bf16 v[68:71], v[172:175], v[204:207], v[68:71]
	v_mfma_f32_16x16x32_bf16 v[120:123], v[168:171], v[184:187], v[120:123]
	v_mfma_f32_16x16x32_bf16 v[104:107], v[168:171], v[192:195], v[104:107]
	v_mfma_f32_16x16x32_bf16 v[88:91], v[168:171], v[200:203], v[88:91]
	v_mfma_f32_16x16x32_bf16 v[72:75], v[168:171], v[208:211], v[72:75]
	v_mfma_f32_16x16x32_bf16 v[112:115], v[176:179], v[184:187], v[112:115]
	v_mfma_f32_16x16x32_bf16 v[96:99], v[176:179], v[192:195], v[96:99]
	v_mfma_f32_16x16x32_bf16 v[80:83], v[176:179], v[200:203], v[80:83]
	v_mfma_f32_16x16x32_bf16 v[68:71], v[176:179], v[208:211], v[68:71]
	s_barrier
; #define PG8_STAGE(bufoff, gbase, voff) do { _Pragma("unroll") for (int _i = 0; _i < 2; ++_i) \
;         __builtin_amdgcn_global_load_lds((const unsigned*)((const char*)(gbase) + (voff)[_i]), (LAS unsigned*)(lds + (bufoff) + ldsw + _i * 8192), 16, 0, 0); } while (0)
; #define PG8_LDA(dst, b, h) do { _Pragma("unroll") for (int m = 0; m < 4; ++m) _Pragma("unroll") for (int k = 0; k < 2; ++k) dst[m][k] = *(const LAS bf16x8*)(pA + PG8_SA(b, h) + m * 2048 + k * 1024); } while (0)
; #define PG8_MMA(ai, bj, At, Bt) do { __builtin_amdgcn_s_setprio(1); _Pragma("unroll") for (int m = 0; m < 4; ++m) _Pragma("unroll") for (int n = 0; n < 2; ++n) _Pragma("unroll") for (int k = 0; k < 2; ++k) \
;         acc[ai][bj][m][n] = __builtin_amdgcn_mfma_f32_16x16x32_bf16(Bt[n][k], At[m][k], acc[ai][bj][m][n], 0, 0, 0); __builtin_amdgcn_s_setprio(0); } while (0)
; #define PG8_WAIT_V(n) asm volatile("s_waitcnt vmcnt(" #n ")" ::: "memory")
; #define PG8_WAIT_L(n) asm volatile("s_waitcnt lgkmcnt(" #n ")" ::: "memory")
; #define PG8_BAR __builtin_amdgcn_s_barrier()
; #define PG8_SCHED __builtin_amdgcn_sched_barrier(0)
; template <class Desc, class Epi, bool ALIGN_EPI>
; __device__ __forceinline__ void gemm_phase(LAS unsigned char* lds, const Desc& D, const Epi& E, int G, int c) {
;     ...
;             PG8_LDA(At, 1, 1); PG8_STAGE(PG8_SB(1, 0), b3, voffB); PG8_STAGE(PG8_SB(1, 1), b3 + hstepB, voffB); PG8_STAGE(PG8_SA(1, 0), a3, voffA);
;             PG8_WAIT_V(8); PG8_WAIT_L(0); PG8_BAR; PG8_MMA(1, 0, At, B0); PG8_MMA(1, 1, At, B1); PG8_BAR; PG8_SCHED;
;         }
;         if constexpr (ALIGN_EPI) { if (wr == 0) PG8_BAR; }
	s_mov_b32 m0, s31
	v_lshl_add_u64 v[212:213], v[212:213], 0, s[76:77]
	s_add_u32 s16, s16, 0x20080
	ds_read_b128 v[180:183], v148 offset:49152
	ds_read_b128 v[184:187], v148 offset:50176
	ds_read_b128 v[188:191], v148 offset:51200
	ds_read_b128 v[192:195], v148 offset:52224
	ds_read_b128 v[196:199], v148 offset:53248
	ds_read_b128 v[200:203], v148 offset:54272
	ds_read_b128 v[204:207], v148 offset:55296
	ds_read_b128 v[208:211], v148 offset:56320
	global_load_lds_dwordx4 v[212:213], off
	v_lshl_add_u64 v[212:213], v[214:215], 0, s[76:77]
	s_mov_b32 m0, s33
	s_addc_u32 s17, s17, 0
	global_load_lds_dwordx4 v[212:213], off
	v_lshl_add_u64 v[212:213], s[16:17], 0, v[136:137]
	s_mov_b32 m0, s38
	s_nop 0
	global_load_lds_dwordx4 v[212:213], off
	v_lshl_add_u64 v[212:213], s[16:17], 0, v[132:133]
	s_mov_b32 m0, s39
	s_nop 0
	global_load_lds_dwordx4 v[212:213], off
	v_lshl_add_u64 v[212:213], v[216:217], 0, s[76:77]
	s_mov_b32 m0, s34
	s_nop 0
	global_load_lds_dwordx4 v[212:213], off
	v_lshl_add_u64 v[212:213], v[218:219], 0, s[76:77]
	s_mov_b32 m0, s35
	s_nop 0
	global_load_lds_dwordx4 v[212:213], off
	s_waitcnt vmcnt(8)
	s_waitcnt lgkmcnt(0)
	s_barrier
	v_mfma_f32_16x16x32_bf16 v[64:67], v[144:147], v[180:183], v[64:67]
	v_mfma_f32_16x16x32_bf16 v[52:55], v[144:147], v[188:191], v[52:55]
	v_mfma_f32_16x16x32_bf16 v[36:39], v[144:147], v[196:199], v[36:39]
	v_mfma_f32_16x16x32_bf16 v[20:23], v[144:147], v[204:207], v[20:23]
	v_mfma_f32_16x16x32_bf16 v[60:63], v[156:159], v[180:183], v[60:63]
	v_mfma_f32_16x16x32_bf16 v[44:47], v[156:159], v[188:191], v[44:47]
	v_mfma_f32_16x16x32_bf16 v[28:31], v[156:159], v[196:199], v[28:31]
	v_mfma_f32_16x16x32_bf16 v[12:15], v[156:159], v[204:207], v[12:15]
	v_mfma_f32_16x16x32_bf16 v[64:67], v[152:155], v[184:187], v[64:67]
	v_mfma_f32_16x16x32_bf16 v[52:55], v[152:155], v[192:195], v[52:55]
	v_mfma_f32_16x16x32_bf16 v[36:39], v[152:155], v[200:203], v[36:39]
	v_mfma_f32_16x16x32_bf16 v[20:23], v[152:155], v[208:211], v[20:23]
	v_mfma_f32_16x16x32_bf16 v[60:63], v[160:163], v[184:187], v[60:63]
	v_mfma_f32_16x16x32_bf16 v[44:47], v[160:163], v[192:195], v[44:47]
	v_mfma_f32_16x16x32_bf16 v[28:31], v[160:163], v[200:203], v[28:31]
	v_mfma_f32_16x16x32_bf16 v[12:15], v[160:163], v[208:211], v[12:15]
	v_mfma_f32_16x16x32_bf16 v[56:59], v[164:167], v[180:183], v[56:59]
	v_mfma_f32_16x16x32_bf16 v[40:43], v[164:167], v[188:191], v[40:43]
	v_mfma_f32_16x16x32_bf16 v[24:27], v[164:167], v[196:199], v[24:27]
	v_mfma_f32_16x16x32_bf16 v[8:11], v[164:167], v[204:207], v[8:11]
	v_mfma_f32_16x16x32_bf16 v[48:51], v[172:175], v[180:183], v[48:51]
	v_mfma_f32_16x16x32_bf16 v[32:35], v[172:175], v[188:191], v[32:35]
	v_mfma_f32_16x16x32_bf16 v[16:19], v[172:175], v[196:199], v[16:19]
	v_mfma_f32_16x16x32_bf16 v[4:7], v[172:175], v[204:207], v[4:7]
	v_mfma_f32_16x16x32_bf16 v[56:59], v[168:171], v[184:187], v[56:59]
	v_mfma_f32_16x16x32_bf16 v[40:43], v[168:171], v[192:195], v[40:43]
	v_mfma_f32_16x16x32_bf16 v[24:27], v[168:171], v[200:203], v[24:27]
	v_mfma_f32_16x16x32_bf16 v[8:11], v[168:171], v[208:211], v[8:11]
	v_mfma_f32_16x16x32_bf16 v[48:51], v[176:179], v[184:187], v[48:51]
	v_mfma_f32_16x16x32_bf16 v[32:35], v[176:179], v[192:195], v[32:35]
	v_mfma_f32_16x16x32_bf16 v[16:19], v[176:179], v[200:203], v[16:19]
	v_mfma_f32_16x16x32_bf16 v[4:7], v[176:179], v[208:211], v[4:7]
	s_barrier
	s_add_i32 s46, s46, 2
	s_add_u32 s12, s12, 0x100
	s_addc_u32 s13, s13, 0
	s_add_u32 s7, s7, 0x100
	s_addc_u32 s45, s45, 0
	s_cmp_gt_u32 s46, 5
	s_cbranch_scc0 .LBB0_603
	v_readlane_b32 s46, v255, 36
	s_and_b64 vcc, exec, s[4:5]
	v_readlane_b32 s47, v255, 37
	s_cbranch_vccz .LBB0_606
	s_barrier

; #define PG8_STAGE(bufoff, gbase, voff) do { _Pragma("unroll") for (int _i = 0; _i < 2; ++_i) \
;         __builtin_amdgcn_global_load_lds((const unsigned*)((const char*)(gbase) + (voff)[_i]), (LAS unsigned*)(lds + (bufoff) + ldsw + _i * 8192), 16, 0, 0); } while (0)
; #define PG8_LDA(dst, b, h) do { _Pragma("unroll") for (int m = 0; m < 4; ++m) _Pragma("unroll") for (int k = 0; k < 2; ++k) dst[m][k] = *(const LAS bf16x8*)(pA + PG8_SA(b, h) + m * 2048 + k * 1024); } while (0)
; #define PG8_LDB(dst, b, h) do { _Pragma("unroll") for (int n = 0; n < 2; ++n) _Pragma("unroll") for (int k = 0; k < 2; ++k) dst[n][k] = *(const LAS bf16x8*)(pB + (PG8_SB(b, h) - 4 * HTB) + n * 2048 + k * 1024); } while (0)
; #define PG8_MMA(ai, bj, At, Bt) do { __builtin_amdgcn_s_setprio(1); _Pragma("unroll") for (int m = 0; m < 4; ++m) _Pragma("unroll") for (int n = 0; n < 2; ++n) _Pragma("unroll") for (int k = 0; k < 2; ++k) \
;         acc[ai][bj][m][n] = __builtin_amdgcn_mfma_f32_16x16x32_bf16(Bt[n][k], At[m][k], acc[ai][bj][m][n], 0, 0, 0); __builtin_amdgcn_s_setprio(0); } while (0)
; #define PG8_WAIT_V(n) asm volatile("s_waitcnt vmcnt(" #n ")" ::: "memory")
; #define PG8_WAIT_L(n) asm volatile("s_waitcnt lgkmcnt(" #n ")" ::: "memory")
; #define PG8_BAR __builtin_amdgcn_s_barrier()
; #define PG8_SCHED __builtin_amdgcn_sched_barrier(0)
; template <class Desc, class Epi, bool ALIGN_EPI>
; __device__ __forceinline__ void gemm_phase(LAS unsigned char* lds, const Desc& D, const Epi& E, int G, int c) {
;     ...
;             PG8_LDB(B0, 0, 0); PG8_LDB(B1, 0, 1); PG8_SCHED; PG8_LDA(At, 0, 0); PG8_STAGE(PG8_SA(1, 1), a1 + hstepA, voffA);
;             PG8_WAIT_V(8); PG8_WAIT_L(0); PG8_BAR; PG8_MMA(0, 0, At, B0); PG8_MMA(0, 1, At, B1); PG8_BAR; PG8_SCHED;
;             PG8_LDA(At, 0, 1); PG8_STAGE(PG8_SB(0, 0), b2, voffB); PG8_STAGE(PG8_SB(0, 1), b2 + hstepB, voffB); PG8_STAGE(PG8_SA(0, 0), a2, voffA);
;             PG8_WAIT_V(8); PG8_WAIT_L(0); PG8_BAR; PG8_MMA(1, 0, At, B0); PG8_MMA(1, 1, At, B1); PG8_BAR; PG8_SCHED;
.LBB0_1164:
	s_waitcnt lgkmcnt(0)
	ds_read_b128 v[132:135], v229
	ds_read_b128 v[136:139], v229 offset:1024
	ds_read_b128 v[140:143], v229 offset:2048
	ds_read_b128 v[144:147], v229 offset:3072
	ds_read_b128 v[148:151], v229 offset:16384
	ds_read_b128 v[152:155], v229 offset:17408
	ds_read_b128 v[156:159], v229 offset:18432
	ds_read_b128 v[160:163], v229 offset:19456
	s_add_i32 s20, s14, 2
	s_add_u32 s16, s12, 0xfff00080
	s_addc_u32 s17, s13, -1
	s_cmp_eq_u32 s1, s14
	s_cselect_b32 s19, s39, s17
	s_cselect_b32 s18, s38, s16
	s_cselect_b32 s17, s41, s11
	s_cselect_b32 s16, s40, s3
	v_lshl_add_u64 v[208:209], s[12:13], 0, v[204:205]
	s_add_i32 m0, s35, 0xc000
	ds_read_b128 v[164:167], v228
	ds_read_b128 v[168:171], v228 offset:1024
	ds_read_b128 v[172:175], v228 offset:2048
	ds_read_b128 v[176:179], v228 offset:3072
	ds_read_b128 v[180:183], v228 offset:4096
	ds_read_b128 v[184:187], v228 offset:5120
	ds_read_b128 v[188:191], v228 offset:6144
	ds_read_b128 v[192:195], v228 offset:7168
	global_load_lds_dwordx4 v[208:209], off
	v_lshl_add_u64 v[208:209], s[12:13], 0, v[206:207]
	s_add_i32 m0, s35, 0xe000
	s_nop 0
	global_load_lds_dwordx4 v[208:209], off
	s_waitcnt vmcnt(8)
	s_waitcnt lgkmcnt(0)
	s_barrier
	v_mfma_f32_16x16x32_bf16 v[128:131], v[132:135], v[164:167], v[128:131]
	v_mfma_f32_16x16x32_bf16 v[120:123], v[132:135], v[172:175], v[120:123]
	v_mfma_f32_16x16x32_bf16 v[112:115], v[132:135], v[180:183], v[112:115]
	v_mfma_f32_16x16x32_bf16 v[104:107], v[132:135], v[188:191], v[104:107]
	v_mfma_f32_16x16x32_bf16 v[124:127], v[140:143], v[164:167], v[124:127]
	v_mfma_f32_16x16x32_bf16 v[116:119], v[140:143], v[172:175], v[116:119]
	v_mfma_f32_16x16x32_bf16 v[108:111], v[140:143], v[180:183], v[108:111]
	v_mfma_f32_16x16x32_bf16 v[100:103], v[140:143], v[188:191], v[100:103]
	v_mfma_f32_16x16x32_bf16 v[128:131], v[136:139], v[168:171], v[128:131]
	v_mfma_f32_16x16x32_bf16 v[120:123], v[136:139], v[176:179], v[120:123]
	v_mfma_f32_16x16x32_bf16 v[112:115], v[136:139], v[184:187], v[112:115]
	v_mfma_f32_16x16x32_bf16 v[104:107], v[136:139], v[192:195], v[104:107]
	v_mfma_f32_16x16x32_bf16 v[124:127], v[144:147], v[168:171], v[124:127]
	v_mfma_f32_16x16x32_bf16 v[116:119], v[144:147], v[176:179], v[116:119]
	v_mfma_f32_16x16x32_bf16 v[108:111], v[144:147], v[184:187], v[108:111]
	v_mfma_f32_16x16x32_bf16 v[100:103], v[144:147], v[192:195], v[100:103]
	v_mfma_f32_16x16x32_bf16 v[96:99], v[148:151], v[164:167], v[96:99]
	v_mfma_f32_16x16x32_bf16 v[88:91], v[148:151], v[172:175], v[88:91]
	v_mfma_f32_16x16x32_bf16 v[64:67], v[148:151], v[180:183], v[64:67]
	v_mfma_f32_16x16x32_bf16 v[32:35], v[148:151], v[188:191], v[32:35]
	v_mfma_f32_16x16x32_bf16 v[92:95], v[156:159], v[164:167], v[92:95]
	v_mfma_f32_16x16x32_bf16 v[80:83], v[156:159], v[172:175], v[80:83]
	v_mfma_f32_16x16x32_bf16 v[52:55], v[156:159], v[180:183], v[52:55]
	v_mfma_f32_16x16x32_bf16 v[20:23], v[156:159], v[188:191], v[20:23]
	v_mfma_f32_16x16x32_bf16 v[96:99], v[152:155], v[168:171], v[96:99]
	v_mfma_f32_16x16x32_bf16 v[88:91], v[152:155], v[176:179], v[88:91]
	v_mfma_f32_16x16x32_bf16 v[64:67], v[152:155], v[184:187], v[64:67]
	v_mfma_f32_16x16x32_bf16 v[32:35], v[152:155], v[192:195], v[32:35]
	v_mfma_f32_16x16x32_bf16 v[92:95], v[160:163], v[168:171], v[92:95]
	v_mfma_f32_16x16x32_bf16 v[80:83], v[160:163], v[176:179], v[80:83]
	v_mfma_f32_16x16x32_bf16 v[52:55], v[160:163], v[184:187], v[52:55]
	v_mfma_f32_16x16x32_bf16 v[20:23], v[160:163], v[192:195], v[20:23]
	s_barrier
	s_mov_b32 m0, s44
	v_lshl_add_u64 v[208:209], s[16:17], 0, v[198:199]
	s_add_u32 s62, s16, 0x100000
	ds_read_b128 v[164:167], v228 offset:16384
	ds_read_b128 v[168:171], v228 offset:17408
	ds_read_b128 v[172:175], v228 offset:18432
	ds_read_b128 v[176:179], v228 offset:19456
	ds_read_b128 v[180:183], v228 offset:20480
	ds_read_b128 v[184:187], v228 offset:21504
	ds_read_b128 v[188:191], v228 offset:22528
	ds_read_b128 v[192:195], v228 offset:23552
	global_load_lds_dwordx4 v[208:209], off
	v_lshl_add_u64 v[210:211], s[16:17], 0, v[202:203]
	s_mov_b32 m0, s45
	s_addc_u32 s63, s17, 0
	global_load_lds_dwordx4 v[210:211], off
	v_lshl_add_u64 v[212:213], s[62:63], 0, v[198:199]
	s_mov_b32 m0, s46
	v_lshl_add_u64 v[214:215], s[18:19], 0, v[200:201]
	global_load_lds_dwordx4 v[212:213], off
	v_lshl_add_u64 v[212:213], s[62:63], 0, v[202:203]
	s_mov_b32 m0, s47
	s_nop 0
	global_load_lds_dwordx4 v[212:213], off
	v_lshl_add_u64 v[212:213], s[18:19], 0, v[196:197]
	s_mov_b32 m0, s35
	s_nop 0
	global_load_lds_dwordx4 v[212:213], off
	s_mov_b32 m0, s48
	s_nop 0
	global_load_lds_dwordx4 v[214:215], off
	s_waitcnt vmcnt(8)
	s_waitcnt lgkmcnt(0)
	s_barrier
; #define PG8_STAGE(bufoff, gbase, voff) do { _Pragma("unroll") for (int _i = 0; _i < 2; ++_i) \
;         __builtin_amdgcn_global_load_lds((const unsigned*)((const char*)(gbase) + (voff)[_i]), (LAS unsigned*)(lds + (bufoff) + ldsw + _i * 8192), 16, 0, 0); } while (0)
; #define PG8_LDA(dst, b, h) do { _Pragma("unroll") for (int m = 0; m < 4; ++m) _Pragma("unroll") for (int k = 0; k < 2; ++k) dst[m][k] = *(const LAS bf16x8*)(pA + PG8_SA(b, h) + m * 2048 + k * 1024); } while (0)
; #define PG8_LDB(dst, b, h) do { _Pragma("unroll") for (int n = 0; n < 2; ++n) _Pragma("unroll") for (int k = 0; k < 2; ++k) dst[n][k] = *(const LAS bf16x8*)(pB + (PG8_SB(b, h) - 4 * HTB) + n * 2048 + k * 1024); } while (0)
; #define PG8_MMA(ai, bj, At, Bt) do { __builtin_amdgcn_s_setprio(1); _Pragma("unroll") for (int m = 0; m < 4; ++m) _Pragma("unroll") for (int n = 0; n < 2; ++n) _Pragma("unroll") for (int k = 0; k < 2; ++k) \
;         acc[ai][bj][m][n] = __builtin_amdgcn_mfma_f32_16x16x32_bf16(Bt[n][k], At[m][k], acc[ai][bj][m][n], 0, 0, 0); __builtin_amdgcn_s_setprio(0); } while (0)
; #define PG8_WAIT_V(n) asm volatile("s_waitcnt vmcnt(" #n ")" ::: "memory")
; #define PG8_WAIT_L(n) asm volatile("s_waitcnt lgkmcnt(" #n ")" ::: "memory")
; #define PG8_BAR __builtin_amdgcn_s_barrier()
; #define PG8_SCHED __builtin_amdgcn_sched_barrier(0)
; template <class Desc, class Epi, bool ALIGN_EPI>
; __device__ __forceinline__ void gemm_phase(LAS unsigned char* lds, const Desc& D, const Epi& E, int G, int c) {
;     ...
;             PG8_WAIT_V(8); PG8_WAIT_L(0); PG8_BAR; PG8_MMA(1, 0, At, B0); PG8_MMA(1, 1, At, B1); PG8_BAR; PG8_SCHED;
;             PG8_LDB(B0, 1, 0); PG8_LDB(B1, 1, 1); PG8_SCHED; PG8_LDA(At, 1, 0); PG8_STAGE(PG8_SA(0, 1), a2 + hstepA, voffA);
;             PG8_WAIT_V(8); PG8_WAIT_L(0); PG8_BAR; PG8_MMA(0, 0, At, B0); PG8_MMA(0, 1, At, B1); PG8_BAR; PG8_SCHED;
	v_mfma_f32_16x16x32_bf16 v[84:87], v[132:135], v[164:167], v[84:87]
	v_mfma_f32_16x16x32_bf16 v[72:75], v[132:135], v[172:175], v[72:75]
	v_mfma_f32_16x16x32_bf16 v[60:63], v[132:135], v[180:183], v[60:63]
	v_mfma_f32_16x16x32_bf16 v[48:51], v[132:135], v[188:191], v[48:51]
	v_mfma_f32_16x16x32_bf16 v[76:79], v[140:143], v[164:167], v[76:79]
	v_mfma_f32_16x16x32_bf16 v[68:71], v[140:143], v[172:175], v[68:71]
	v_mfma_f32_16x16x32_bf16 v[56:59], v[140:143], v[180:183], v[56:59]
	v_mfma_f32_16x16x32_bf16 v[44:47], v[140:143], v[188:191], v[44:47]
	v_mfma_f32_16x16x32_bf16 v[84:87], v[136:139], v[168:171], v[84:87]
	v_mfma_f32_16x16x32_bf16 v[72:75], v[136:139], v[176:179], v[72:75]
	v_mfma_f32_16x16x32_bf16 v[60:63], v[136:139], v[184:187], v[60:63]
	v_mfma_f32_16x16x32_bf16 v[48:51], v[136:139], v[192:195], v[48:51]
	v_mfma_f32_16x16x32_bf16 v[76:79], v[144:147], v[168:171], v[76:79]
	v_mfma_f32_16x16x32_bf16 v[68:71], v[144:147], v[176:179], v[68:71]
	v_mfma_f32_16x16x32_bf16 v[56:59], v[144:147], v[184:187], v[56:59]
	v_mfma_f32_16x16x32_bf16 v[44:47], v[144:147], v[192:195], v[44:47]
	v_mfma_f32_16x16x32_bf16 v[40:43], v[148:151], v[164:167], v[40:43]
	v_mfma_f32_16x16x32_bf16 v[28:31], v[148:151], v[172:175], v[28:31]
	v_mfma_f32_16x16x32_bf16 v[16:19], v[148:151], v[180:183], v[16:19]
	v_mfma_f32_16x16x32_bf16 v[8:11], v[148:151], v[188:191], v[8:11]
	v_mfma_f32_16x16x32_bf16 v[36:39], v[156:159], v[164:167], v[36:39]
	v_mfma_f32_16x16x32_bf16 v[24:27], v[156:159], v[172:175], v[24:27]
	v_mfma_f32_16x16x32_bf16 v[12:15], v[156:159], v[180:183], v[12:15]
	v_mfma_f32_16x16x32_bf16 v[4:7], v[156:159], v[188:191], v[4:7]
	v_mfma_f32_16x16x32_bf16 v[40:43], v[152:155], v[168:171], v[40:43]
	v_mfma_f32_16x16x32_bf16 v[28:31], v[152:155], v[176:179], v[28:31]
	v_mfma_f32_16x16x32_bf16 v[16:19], v[152:155], v[184:187], v[16:19]
	v_mfma_f32_16x16x32_bf16 v[8:11], v[152:155], v[192:195], v[8:11]
	v_mfma_f32_16x16x32_bf16 v[36:39], v[160:163], v[168:171], v[36:39]
	v_mfma_f32_16x16x32_bf16 v[24:27], v[160:163], v[176:179], v[24:27]
	v_mfma_f32_16x16x32_bf16 v[12:15], v[160:163], v[184:187], v[12:15]
	v_mfma_f32_16x16x32_bf16 v[4:7], v[160:163], v[192:195], v[4:7]
	s_barrier
	ds_read_b128 v[132:135], v229 offset:32768
	ds_read_b128 v[136:139], v229 offset:33792
	ds_read_b128 v[140:143], v229 offset:34816
	ds_read_b128 v[144:147], v229 offset:35840
	ds_read_b128 v[148:151], v229 offset:49152
	ds_read_b128 v[152:155], v229 offset:50176
	ds_read_b128 v[156:159], v229 offset:51200
	ds_read_b128 v[160:163], v229 offset:52224
	s_add_u32 s18, s18, 0x100000
	s_addc_u32 s19, s19, 0
	s_mov_b32 m0, s49
	v_lshl_add_u64 v[216:217], s[18:19], 0, v[196:197]
	ds_read_b128 v[164:167], v228 offset:32768
	ds_read_b128 v[168:171], v228 offset:33792
	ds_read_b128 v[172:175], v228 offset:34816
	ds_read_b128 v[176:179], v228 offset:35840
	ds_read_b128 v[180:183], v228 offset:36864
	ds_read_b128 v[184:187], v228 offset:37888
	ds_read_b128 v[188:191], v228 offset:38912
	ds_read_b128 v[192:195], v228 offset:39936
	global_load_lds_dwordx4 v[216:217], off
	v_lshl_add_u64 v[216:217], s[18:19], 0, v[200:201]
	s_mov_b32 m0, s50
	s_nop 0
	global_load_lds_dwordx4 v[216:217], off
	s_waitcnt vmcnt(8)
	s_waitcnt lgkmcnt(0)
	s_barrier
	v_mfma_f32_16x16x32_bf16 v[128:131], v[132:135], v[164:167], v[128:131]
	v_mfma_f32_16x16x32_bf16 v[120:123], v[132:135], v[172:175], v[120:123]
	v_mfma_f32_16x16x32_bf16 v[112:115], v[132:135], v[180:183], v[112:115]
	v_mfma_f32_16x16x32_bf16 v[104:107], v[132:135], v[188:191], v[104:107]
	v_mfma_f32_16x16x32_bf16 v[124:127], v[140:143], v[164:167], v[124:127]
	v_mfma_f32_16x16x32_bf16 v[116:119], v[140:143], v[172:175], v[116:119]
	v_mfma_f32_16x16x32_bf16 v[108:111], v[140:143], v[180:183], v[108:111]
	v_mfma_f32_16x16x32_bf16 v[100:103], v[140:143], v[188:191], v[100:103]
	v_mfma_f32_16x16x32_bf16 v[128:131], v[136:139], v[168:171], v[128:131]
	v_mfma_f32_16x16x32_bf16 v[120:123], v[136:139], v[176:179], v[120:123]
	v_mfma_f32_16x16x32_bf16 v[112:115], v[136:139], v[184:187], v[112:115]
	v_mfma_f32_16x16x32_bf16 v[104:107], v[136:139], v[192:195], v[104:107]
	v_mfma_f32_16x16x32_bf16 v[124:127], v[144:147], v[168:171], v[124:127]
	v_mfma_f32_16x16x32_bf16 v[116:119], v[144:147], v[176:179], v[116:119]
	v_mfma_f32_16x16x32_bf16 v[108:111], v[144:147], v[184:187], v[108:111]
	v_mfma_f32_16x16x32_bf16 v[100:103], v[144:147], v[192:195], v[100:103]
	v_mfma_f32_16x16x32_bf16 v[96:99], v[148:151], v[164:167], v[96:99]
	v_mfma_f32_16x16x32_bf16 v[88:91], v[148:151], v[172:175], v[88:91]
	v_mfma_f32_16x16x32_bf16 v[64:67], v[148:151], v[180:183], v[64:67]
	v_mfma_f32_16x16x32_bf16 v[32:35], v[148:151], v[188:191], v[32:35]
	v_mfma_f32_16x16x32_bf16 v[92:95], v[156:159], v[164:167], v[92:95]
	v_mfma_f32_16x16x32_bf16 v[80:83], v[156:159], v[172:175], v[80:83]
	v_mfma_f32_16x16x32_bf16 v[52:55], v[156:159], v[180:183], v[52:55]
	v_mfma_f32_16x16x32_bf16 v[20:23], v[156:159], v[188:191], v[20:23]
	v_mfma_f32_16x16x32_bf16 v[96:99], v[152:155], v[168:171], v[96:99]
	v_mfma_f32_16x16x32_bf16 v[88:91], v[152:155], v[176:179], v[88:91]
	v_mfma_f32_16x16x32_bf16 v[64:67], v[152:155], v[184:187], v[64:67]
	v_mfma_f32_16x16x32_bf16 v[32:35], v[152:155], v[192:195], v[32:35]
	v_mfma_f32_16x16x32_bf16 v[92:95], v[160:163], v[168:171], v[92:95]
	v_mfma_f32_16x16x32_bf16 v[80:83], v[160:163], v[176:179], v[80:83]
	v_mfma_f32_16x16x32_bf16 v[52:55], v[160:163], v[184:187], v[52:55]
	v_mfma_f32_16x16x32_bf16 v[20:23], v[160:163], v[192:195], v[20:23]
	s_barrier
; #define PG8_STAGE(bufoff, gbase, voff) do { _Pragma("unroll") for (int _i = 0; _i < 2; ++_i) \
;         __builtin_amdgcn_global_load_lds((const unsigned*)((const char*)(gbase) + (voff)[_i]), (LAS unsigned*)(lds + (bufoff) + ldsw + _i * 8192), 16, 0, 0); } while (0)
; #define PG8_LDA(dst, b, h) do { _Pragma("unroll") for (int m = 0; m < 4; ++m) _Pragma("unroll") for (int k = 0; k < 2; ++k) dst[m][k] = *(const LAS bf16x8*)(pA + PG8_SA(b, h) + m * 2048 + k * 1024); } while (0)
; #define PG8_MMA(ai, bj, At, Bt) do { __builtin_amdgcn_s_setprio(1); _Pragma("unroll") for (int m = 0; m < 4; ++m) _Pragma("unroll") for (int n = 0; n < 2; ++n) _Pragma("unroll") for (int k = 0; k < 2; ++k) \
;         acc[ai][bj][m][n] = __builtin_amdgcn_mfma_f32_16x16x32_bf16(Bt[n][k], At[m][k], acc[ai][bj][m][n], 0, 0, 0); __builtin_amdgcn_s_setprio(0); } while (0)
; #define PG8_WAIT_V(n) asm volatile("s_waitcnt vmcnt(" #n ")" ::: "memory")
; #define PG8_WAIT_L(n) asm volatile("s_waitcnt lgkmcnt(" #n ")" ::: "memory")
; #define PG8_BAR __builtin_amdgcn_s_barrier()
; #define PG8_SCHED __builtin_amdgcn_sched_barrier(0)
; template <class Desc, class Epi, bool ALIGN_EPI>
; __device__ __forceinline__ void gemm_phase(LAS unsigned char* lds, const Desc& D, const Epi& E, int G, int c) {
;     ...
;             PG8_LDA(At, 1, 1); PG8_STAGE(PG8_SB(1, 0), b3, voffB); PG8_STAGE(PG8_SB(1, 1), b3 + hstepB, voffB); PG8_STAGE(PG8_SA(1, 0), a3, voffA);
;             PG8_WAIT_V(8); PG8_WAIT_L(0); PG8_BAR; PG8_MMA(1, 0, At, B0); PG8_MMA(1, 1, At, B1); PG8_BAR; PG8_SCHED;
;         }
;         if constexpr (ALIGN_EPI) { if (wr == 0) PG8_BAR; }
	s_mov_b32 m0, s52
	v_lshl_add_u64 v[208:209], v[208:209], 0, s[76:77]
	s_add_u32 s16, s16, 0x100080
	ds_read_b128 v[164:167], v228 offset:49152
	ds_read_b128 v[168:171], v228 offset:50176
	ds_read_b128 v[172:175], v228 offset:51200
	ds_read_b128 v[176:179], v228 offset:52224
	ds_read_b128 v[180:183], v228 offset:53248
	ds_read_b128 v[184:187], v228 offset:54272
	ds_read_b128 v[188:191], v228 offset:55296
	ds_read_b128 v[192:195], v228 offset:56320
	global_load_lds_dwordx4 v[208:209], off
	v_lshl_add_u64 v[208:209], v[210:211], 0, s[76:77]
	s_mov_b32 m0, s53
	s_addc_u32 s17, s17, 0
	global_load_lds_dwordx4 v[208:209], off
	v_lshl_add_u64 v[208:209], s[16:17], 0, v[198:199]
	s_mov_b32 m0, s56
	s_nop 0
	global_load_lds_dwordx4 v[208:209], off
	v_lshl_add_u64 v[208:209], s[16:17], 0, v[202:203]
	s_mov_b32 m0, s57
	s_nop 0
	global_load_lds_dwordx4 v[208:209], off
	v_lshl_add_u64 v[208:209], v[212:213], 0, s[76:77]
	s_mov_b32 m0, s54
	s_nop 0
	global_load_lds_dwordx4 v[208:209], off
	v_lshl_add_u64 v[208:209], v[214:215], 0, s[76:77]
	s_mov_b32 m0, s55
	s_nop 0
	global_load_lds_dwordx4 v[208:209], off
	s_waitcnt vmcnt(8)
	s_waitcnt lgkmcnt(0)
	s_barrier
	v_mfma_f32_16x16x32_bf16 v[84:87], v[132:135], v[164:167], v[84:87]
	v_mfma_f32_16x16x32_bf16 v[72:75], v[132:135], v[172:175], v[72:75]
	v_mfma_f32_16x16x32_bf16 v[60:63], v[132:135], v[180:183], v[60:63]
	v_mfma_f32_16x16x32_bf16 v[48:51], v[132:135], v[188:191], v[48:51]
	v_mfma_f32_16x16x32_bf16 v[76:79], v[140:143], v[164:167], v[76:79]
	v_mfma_f32_16x16x32_bf16 v[68:71], v[140:143], v[172:175], v[68:71]
	v_mfma_f32_16x16x32_bf16 v[56:59], v[140:143], v[180:183], v[56:59]
	v_mfma_f32_16x16x32_bf16 v[44:47], v[140:143], v[188:191], v[44:47]
	v_mfma_f32_16x16x32_bf16 v[84:87], v[136:139], v[168:171], v[84:87]
	v_mfma_f32_16x16x32_bf16 v[72:75], v[136:139], v[176:179], v[72:75]
	v_mfma_f32_16x16x32_bf16 v[60:63], v[136:139], v[184:187], v[60:63]
	v_mfma_f32_16x16x32_bf16 v[48:51], v[136:139], v[192:195], v[48:51]
	v_mfma_f32_16x16x32_bf16 v[76:79], v[144:147], v[168:171], v[76:79]
	v_mfma_f32_16x16x32_bf16 v[68:71], v[144:147], v[176:179], v[68:71]
	v_mfma_f32_16x16x32_bf16 v[56:59], v[144:147], v[184:187], v[56:59]
	v_mfma_f32_16x16x32_bf16 v[44:47], v[144:147], v[192:195], v[44:47]
	v_mfma_f32_16x16x32_bf16 v[40:43], v[148:151], v[164:167], v[40:43]
	v_mfma_f32_16x16x32_bf16 v[28:31], v[148:151], v[172:175], v[28:31]
	v_mfma_f32_16x16x32_bf16 v[16:19], v[148:151], v[180:183], v[16:19]
	v_mfma_f32_16x16x32_bf16 v[8:11], v[148:151], v[188:191], v[8:11]
	v_mfma_f32_16x16x32_bf16 v[36:39], v[156:159], v[164:167], v[36:39]
	v_mfma_f32_16x16x32_bf16 v[24:27], v[156:159], v[172:175], v[24:27]
	v_mfma_f32_16x16x32_bf16 v[12:15], v[156:159], v[180:183], v[12:15]
	v_mfma_f32_16x16x32_bf16 v[4:7], v[156:159], v[188:191], v[4:7]
	v_mfma_f32_16x16x32_bf16 v[40:43], v[152:155], v[168:171], v[40:43]
	v_mfma_f32_16x16x32_bf16 v[28:31], v[152:155], v[176:179], v[28:31]
	v_mfma_f32_16x16x32_bf16 v[16:19], v[152:155], v[184:187], v[16:19]
	v_mfma_f32_16x16x32_bf16 v[8:11], v[152:155], v[192:195], v[8:11]
	v_mfma_f32_16x16x32_bf16 v[36:39], v[160:163], v[168:171], v[36:39]
	v_mfma_f32_16x16x32_bf16 v[24:27], v[160:163], v[176:179], v[24:27]
	v_mfma_f32_16x16x32_bf16 v[12:15], v[160:163], v[184:187], v[12:15]
	v_mfma_f32_16x16x32_bf16 v[4:7], v[160:163], v[192:195], v[4:7]
	s_barrier
	s_add_u32 s12, s12, 0x100
	s_addc_u32 s13, s13, 0
	s_add_u32 s3, s3, 0x100
	s_addc_u32 s11, s11, 0
	s_cmp_ge_u32 s20, s2
	s_mov_b32 s14, s20
	s_cbranch_scc0 .LBB0_1164
	s_and_b64 vcc, exec, s[8:9]
	s_cbranch_vccz .LBB0_1167
	s_barrier

;     __device__ __forceinline__ int nt(const Unit& u) const { return (u.pn >> 1) < 2 ? 22 : 20; }
; #define PG8_STAGE(bufoff, gbase, voff) do { _Pragma("unroll") for (int _i = 0; _i < 2; ++_i) \
;         __builtin_amdgcn_global_load_lds((const unsigned*)((const char*)(gbase) + (voff)[_i]), (LAS unsigned*)(lds + (bufoff) + ldsw + _i * 8192), 16, 0, 0); } while (0)
; #define PG8_LDA(dst, b, h) do { _Pragma("unroll") for (int m = 0; m < 4; ++m) _Pragma("unroll") for (int k = 0; k < 2; ++k) dst[m][k] = *(const LAS bf16x8*)(pA + PG8_SA(b, h) + m * 2048 + k * 1024); } while (0)
; #define PG8_LDB(dst, b, h) do { _Pragma("unroll") for (int n = 0; n < 2; ++n) _Pragma("unroll") for (int k = 0; k < 2; ++k) dst[n][k] = *(const LAS bf16x8*)(pB + (PG8_SB(b, h) - 4 * HTB) + n * 2048 + k * 1024); } while (0)
; #define PG8_MMA(ai, bj, At, Bt) do { __builtin_amdgcn_s_setprio(1); _Pragma("unroll") for (int m = 0; m < 4; ++m) _Pragma("unroll") for (int n = 0; n < 2; ++n) _Pragma("unroll") for (int k = 0; k < 2; ++k) \
;         acc[ai][bj][m][n] = __builtin_amdgcn_mfma_f32_16x16x32_bf16(Bt[n][k], At[m][k], acc[ai][bj][m][n], 0, 0, 0); __builtin_amdgcn_s_setprio(0); } while (0)
; #define PG8_WAIT_V(n) asm volatile("s_waitcnt vmcnt(" #n ")" ::: "memory")
; #define PG8_BAR __builtin_amdgcn_s_barrier()
; template <class Desc, class Epi, bool ALIGN_EPI>
; __device__ __forceinline__ void gemm_phase(LAS unsigned char* lds, const Desc& D, const Epi& E, int G, int c) {
;     ...
;         for (int t = 0; t < nt; t += 2) {
;             const bool last = (t == nt - 2);
;             if (last && has_next) PG8_AWAIT(nxt);
;             const char* a1 = cA + (size_t)(t + 1) * kstep;
;             const char* a2 = last ? nA : cA + (size_t)(t + 2) * kstep; const char* b2 = last ? nB : cB + (size_t)(t + 2) * kstep;
;             const char* a3 = a2 + kstep; const char* b3 = b2 + kstep;
;             PG8_LDB(B0, 0, 0); PG8_LDB(B1, 0, 1); PG8_SCHED; PG8_LDA(At, 0, 0); PG8_STAGE(PG8_SA(1, 1), a1 + hstepA, voffA);
;             PG8_WAIT_V(8); PG8_WAIT_L(0); PG8_BAR; PG8_MMA(0, 0, At, B0); PG8_MMA(0, 1, At, B1); PG8_BAR; PG8_SCHED;
;             PG8_LDA(At, 0, 1); PG8_STAGE(PG8_SB(0, 0), b2, voffB); PG8_STAGE(PG8_SB(0, 1), b2 + hstepB, voffB); PG8_STAGE(PG8_SA(0, 0), a2, voffA);
;             PG8_WAIT_V(8); PG8_WAIT_L(0); PG8_BAR; PG8_MMA(1, 0, At, B0); PG8_MMA(1, 1, At, B1); PG8_BAR; PG8_SCHED;
.LBB0_1324:
	ds_read_b128 v[144:147], v149
	ds_read_b128 v[152:155], v149 offset:1024
	ds_read_b128 v[156:159], v149 offset:2048
	ds_read_b128 v[160:163], v149 offset:3072
	ds_read_b128 v[164:167], v149 offset:16384
	ds_read_b128 v[168:171], v149 offset:17408
	ds_read_b128 v[172:175], v149 offset:18432
	ds_read_b128 v[176:179], v149 offset:19456
	s_add_i32 s50, s18, 2
	s_add_u32 s19, s16, 0xfff00080
	s_addc_u32 s20, s17, -1
	s_cmp_eq_u32 s9, s18
	s_cselect_b32 s18, s12, s48
	s_cselect_b32 s21, s11, s20
	s_cselect_b32 s20, s10, s19
	s_cselect_b32 s19, s13, s49
	v_lshl_add_u64 v[212:213], s[16:17], 0, v[140:141]
	s_add_i32 m0, s24, 0xc000
	ds_read_b128 v[180:183], v148
	ds_read_b128 v[184:187], v148 offset:1024
	ds_read_b128 v[188:191], v148 offset:2048
	ds_read_b128 v[192:195], v148 offset:3072
	ds_read_b128 v[196:199], v148 offset:4096
	ds_read_b128 v[200:203], v148 offset:5120
	ds_read_b128 v[204:207], v148 offset:6144
	ds_read_b128 v[208:211], v148 offset:7168
	global_load_lds_dwordx4 v[212:213], off
	v_lshl_add_u64 v[212:213], s[16:17], 0, v[142:143]
	s_add_i32 m0, s24, 0xe000
	s_nop 0
	global_load_lds_dwordx4 v[212:213], off
	s_waitcnt vmcnt(8)
	s_waitcnt lgkmcnt(0)
	s_barrier
	v_mfma_f32_16x16x32_bf16 v[128:131], v[144:147], v[180:183], v[128:131]
	v_mfma_f32_16x16x32_bf16 v[120:123], v[144:147], v[188:191], v[120:123]
	v_mfma_f32_16x16x32_bf16 v[104:107], v[144:147], v[196:199], v[104:107]
	v_mfma_f32_16x16x32_bf16 v[88:91], v[144:147], v[204:207], v[88:91]
	v_mfma_f32_16x16x32_bf16 v[124:127], v[156:159], v[180:183], v[124:127]
	v_mfma_f32_16x16x32_bf16 v[112:115], v[156:159], v[188:191], v[112:115]
	v_mfma_f32_16x16x32_bf16 v[96:99], v[156:159], v[196:199], v[96:99]
	v_mfma_f32_16x16x32_bf16 v[80:83], v[156:159], v[204:207], v[80:83]
	v_mfma_f32_16x16x32_bf16 v[128:131], v[152:155], v[184:187], v[128:131]
	v_mfma_f32_16x16x32_bf16 v[120:123], v[152:155], v[192:195], v[120:123]
	v_mfma_f32_16x16x32_bf16 v[104:107], v[152:155], v[200:203], v[104:107]
	v_mfma_f32_16x16x32_bf16 v[88:91], v[152:155], v[208:211], v[88:91]
	v_mfma_f32_16x16x32_bf16 v[124:127], v[160:163], v[184:187], v[124:127]
	v_mfma_f32_16x16x32_bf16 v[112:115], v[160:163], v[192:195], v[112:115]
	v_mfma_f32_16x16x32_bf16 v[96:99], v[160:163], v[200:203], v[96:99]
	v_mfma_f32_16x16x32_bf16 v[80:83], v[160:163], v[208:211], v[80:83]
	v_mfma_f32_16x16x32_bf16 v[116:119], v[164:167], v[180:183], v[116:119]
	v_mfma_f32_16x16x32_bf16 v[100:103], v[164:167], v[188:191], v[100:103]
	v_mfma_f32_16x16x32_bf16 v[84:87], v[164:167], v[196:199], v[84:87]
	v_mfma_f32_16x16x32_bf16 v[72:75], v[164:167], v[204:207], v[72:75]
	v_mfma_f32_16x16x32_bf16 v[108:111], v[172:175], v[180:183], v[108:111]
	v_mfma_f32_16x16x32_bf16 v[92:95], v[172:175], v[188:191], v[92:95]
	v_mfma_f32_16x16x32_bf16 v[76:79], v[172:175], v[196:199], v[76:79]
	v_mfma_f32_16x16x32_bf16 v[68:71], v[172:175], v[204:207], v[68:71]
	v_mfma_f32_16x16x32_bf16 v[116:119], v[168:171], v[184:187], v[116:119]
	v_mfma_f32_16x16x32_bf16 v[100:103], v[168:171], v[192:195], v[100:103]
	v_mfma_f32_16x16x32_bf16 v[84:87], v[168:171], v[200:203], v[84:87]
	v_mfma_f32_16x16x32_bf16 v[72:75], v[168:171], v[208:211], v[72:75]
	v_mfma_f32_16x16x32_bf16 v[108:111], v[176:179], v[184:187], v[108:111]
	v_mfma_f32_16x16x32_bf16 v[92:95], v[176:179], v[192:195], v[92:95]
	v_mfma_f32_16x16x32_bf16 v[76:79], v[176:179], v[200:203], v[76:79]
	v_mfma_f32_16x16x32_bf16 v[68:71], v[176:179], v[208:211], v[68:71]
	s_barrier
	s_mov_b32 m0, s25
	v_lshl_add_u64 v[212:213], s[18:19], 0, v[136:137]
	s_add_u32 s52, s18, 0x100000
	ds_read_b128 v[180:183], v148 offset:16384
	ds_read_b128 v[184:187], v148 offset:17408
	ds_read_b128 v[188:191], v148 offset:18432
	ds_read_b128 v[192:195], v148 offset:19456
	ds_read_b128 v[196:199], v148 offset:20480
	ds_read_b128 v[200:203], v148 offset:21504
	ds_read_b128 v[204:207], v148 offset:22528
	ds_read_b128 v[208:211], v148 offset:23552
	global_load_lds_dwordx4 v[212:213], off
	v_lshl_add_u64 v[214:215], s[18:19], 0, v[132:133]
	s_mov_b32 m0, s26
	s_addc_u32 s53, s19, 0
	global_load_lds_dwordx4 v[214:215], off
	v_lshl_add_u64 v[216:217], s[52:53], 0, v[136:137]
	s_mov_b32 m0, s27
	v_lshl_add_u64 v[218:219], s[20:21], 0, v[134:135]
	global_load_lds_dwordx4 v[216:217], off
	v_lshl_add_u64 v[216:217], s[52:53], 0, v[132:133]
	s_mov_b32 m0, s30
	s_nop 0
	global_load_lds_dwordx4 v[216:217], off
	v_lshl_add_u64 v[216:217], s[20:21], 0, v[138:139]
	s_mov_b32 m0, s24
	s_nop 0
	global_load_lds_dwordx4 v[216:217], off
	s_mov_b32 m0, s31
	s_nop 0
	global_load_lds_dwordx4 v[218:219], off
	s_waitcnt vmcnt(8)
	s_waitcnt lgkmcnt(0)
	s_barrier
; #define PG8_STAGE(bufoff, gbase, voff) do { _Pragma("unroll") for (int _i = 0; _i < 2; ++_i) \
;         __builtin_amdgcn_global_load_lds((const unsigned*)((const char*)(gbase) + (voff)[_i]), (LAS unsigned*)(lds + (bufoff) + ldsw + _i * 8192), 16, 0, 0); } while (0)
; #define PG8_LDA(dst, b, h) do { _Pragma("unroll") for (int m = 0; m < 4; ++m) _Pragma("unroll") for (int k = 0; k < 2; ++k) dst[m][k] = *(const LAS bf16x8*)(pA + PG8_SA(b, h) + m * 2048 + k * 1024); } while (0)
; #define PG8_LDB(dst, b, h) do { _Pragma("unroll") for (int n = 0; n < 2; ++n) _Pragma("unroll") for (int k = 0; k < 2; ++k) dst[n][k] = *(const LAS bf16x8*)(pB + (PG8_SB(b, h) - 4 * HTB) + n * 2048 + k * 1024); } while (0)
; #define PG8_MMA(ai, bj, At, Bt) do { __builtin_amdgcn_s_setprio(1); _Pragma("unroll") for (int m = 0; m < 4; ++m) _Pragma("unroll") for (int n = 0; n < 2; ++n) _Pragma("unroll") for (int k = 0; k < 2; ++k) \
;         acc[ai][bj][m][n] = __builtin_amdgcn_mfma_f32_16x16x32_bf16(Bt[n][k], At[m][k], acc[ai][bj][m][n], 0, 0, 0); __builtin_amdgcn_s_setprio(0); } while (0)
; #define PG8_WAIT_V(n) asm volatile("s_waitcnt vmcnt(" #n ")" ::: "memory")
; #define PG8_WAIT_L(n) asm volatile("s_waitcnt lgkmcnt(" #n ")" ::: "memory")
; #define PG8_BAR __builtin_amdgcn_s_barrier()
; #define PG8_SCHED __builtin_amdgcn_sched_barrier(0)
; template <class Desc, class Epi, bool ALIGN_EPI>
; __device__ __forceinline__ void gemm_phase(LAS unsigned char* lds, const Desc& D, const Epi& E, int G, int c) {
;     ...
;             PG8_WAIT_V(8); PG8_WAIT_L(0); PG8_BAR; PG8_MMA(1, 0, At, B0); PG8_MMA(1, 1, At, B1); PG8_BAR; PG8_SCHED;
;             PG8_LDB(B0, 1, 0); PG8_LDB(B1, 1, 1); PG8_SCHED; PG8_LDA(At, 1, 0); PG8_STAGE(PG8_SA(0, 1), a2 + hstepA, voffA);
;             PG8_WAIT_V(8); PG8_WAIT_L(0); PG8_BAR; PG8_MMA(0, 0, At, B0); PG8_MMA(0, 1, At, B1); PG8_BAR; PG8_SCHED;
	v_mfma_f32_16x16x32_bf16 v[64:67], v[144:147], v[180:183], v[64:67]
	v_mfma_f32_16x16x32_bf16 v[56:59], v[144:147], v[188:191], v[56:59]
	v_mfma_f32_16x16x32_bf16 v[40:43], v[144:147], v[196:199], v[40:43]
	v_mfma_f32_16x16x32_bf16 v[24:27], v[144:147], v[204:207], v[24:27]
	v_mfma_f32_16x16x32_bf16 v[60:63], v[156:159], v[180:183], v[60:63]
	v_mfma_f32_16x16x32_bf16 v[48:51], v[156:159], v[188:191], v[48:51]
	v_mfma_f32_16x16x32_bf16 v[32:35], v[156:159], v[196:199], v[32:35]
	v_mfma_f32_16x16x32_bf16 v[16:19], v[156:159], v[204:207], v[16:19]
	v_mfma_f32_16x16x32_bf16 v[64:67], v[152:155], v[184:187], v[64:67]
	v_mfma_f32_16x16x32_bf16 v[56:59], v[152:155], v[192:195], v[56:59]
	v_mfma_f32_16x16x32_bf16 v[40:43], v[152:155], v[200:203], v[40:43]
	v_mfma_f32_16x16x32_bf16 v[24:27], v[152:155], v[208:211], v[24:27]
	v_mfma_f32_16x16x32_bf16 v[60:63], v[160:163], v[184:187], v[60:63]
	v_mfma_f32_16x16x32_bf16 v[48:51], v[160:163], v[192:195], v[48:51]
	v_mfma_f32_16x16x32_bf16 v[32:35], v[160:163], v[200:203], v[32:35]
	v_mfma_f32_16x16x32_bf16 v[16:19], v[160:163], v[208:211], v[16:19]
	v_mfma_f32_16x16x32_bf16 v[52:55], v[164:167], v[180:183], v[52:55]
	v_mfma_f32_16x16x32_bf16 v[36:39], v[164:167], v[188:191], v[36:39]
	v_mfma_f32_16x16x32_bf16 v[20:23], v[164:167], v[196:199], v[20:23]
	v_mfma_f32_16x16x32_bf16 v[8:11], v[164:167], v[204:207], v[8:11]
	v_mfma_f32_16x16x32_bf16 v[44:47], v[172:175], v[180:183], v[44:47]
	v_mfma_f32_16x16x32_bf16 v[28:31], v[172:175], v[188:191], v[28:31]
	v_mfma_f32_16x16x32_bf16 v[12:15], v[172:175], v[196:199], v[12:15]
	v_mfma_f32_16x16x32_bf16 v[4:7], v[172:175], v[204:207], v[4:7]
	v_mfma_f32_16x16x32_bf16 v[52:55], v[168:171], v[184:187], v[52:55]
	v_mfma_f32_16x16x32_bf16 v[36:39], v[168:171], v[192:195], v[36:39]
	v_mfma_f32_16x16x32_bf16 v[20:23], v[168:171], v[200:203], v[20:23]
	v_mfma_f32_16x16x32_bf16 v[8:11], v[168:171], v[208:211], v[8:11]
	v_mfma_f32_16x16x32_bf16 v[44:47], v[176:179], v[184:187], v[44:47]
	v_mfma_f32_16x16x32_bf16 v[28:31], v[176:179], v[192:195], v[28:31]
	v_mfma_f32_16x16x32_bf16 v[12:15], v[176:179], v[200:203], v[12:15]
	v_mfma_f32_16x16x32_bf16 v[4:7], v[176:179], v[208:211], v[4:7]
	s_barrier
	ds_read_b128 v[144:147], v149 offset:32768
	ds_read_b128 v[152:155], v149 offset:33792
	ds_read_b128 v[156:159], v149 offset:34816
	ds_read_b128 v[160:163], v149 offset:35840
	ds_read_b128 v[164:167], v149 offset:49152
	ds_read_b128 v[168:171], v149 offset:50176
	ds_read_b128 v[172:175], v149 offset:51200
	ds_read_b128 v[176:179], v149 offset:52224
	s_add_u32 s20, s20, 0x100000
	s_addc_u32 s21, s21, 0
	s_mov_b32 m0, s33
	v_lshl_add_u64 v[220:221], s[20:21], 0, v[138:139]
	ds_read_b128 v[180:183], v148 offset:32768
	ds_read_b128 v[184:187], v148 offset:33792
	ds_read_b128 v[188:191], v148 offset:34816
	ds_read_b128 v[192:195], v148 offset:35840
	ds_read_b128 v[196:199], v148 offset:36864
	ds_read_b128 v[200:203], v148 offset:37888
	ds_read_b128 v[204:207], v148 offset:38912
	ds_read_b128 v[208:211], v148 offset:39936
	global_load_lds_dwordx4 v[220:221], off
	v_lshl_add_u64 v[220:221], s[20:21], 0, v[134:135]
	s_mov_b32 m0, s34
	s_nop 0
	global_load_lds_dwordx4 v[220:221], off
	s_waitcnt vmcnt(8)
	s_waitcnt lgkmcnt(0)
	s_barrier
	v_mfma_f32_16x16x32_bf16 v[128:131], v[144:147], v[180:183], v[128:131]
	v_mfma_f32_16x16x32_bf16 v[120:123], v[144:147], v[188:191], v[120:123]
	v_mfma_f32_16x16x32_bf16 v[104:107], v[144:147], v[196:199], v[104:107]
	v_mfma_f32_16x16x32_bf16 v[88:91], v[144:147], v[204:207], v[88:91]
	v_mfma_f32_16x16x32_bf16 v[124:127], v[156:159], v[180:183], v[124:127]
	v_mfma_f32_16x16x32_bf16 v[112:115], v[156:159], v[188:191], v[112:115]
	v_mfma_f32_16x16x32_bf16 v[96:99], v[156:159], v[196:199], v[96:99]
	v_mfma_f32_16x16x32_bf16 v[80:83], v[156:159], v[204:207], v[80:83]
	v_mfma_f32_16x16x32_bf16 v[128:131], v[152:155], v[184:187], v[128:131]
	v_mfma_f32_16x16x32_bf16 v[120:123], v[152:155], v[192:195], v[120:123]
	v_mfma_f32_16x16x32_bf16 v[104:107], v[152:155], v[200:203], v[104:107]
	v_mfma_f32_16x16x32_bf16 v[88:91], v[152:155], v[208:211], v[88:91]
	v_mfma_f32_16x16x32_bf16 v[124:127], v[160:163], v[184:187], v[124:127]
	v_mfma_f32_16x16x32_bf16 v[112:115], v[160:163], v[192:195], v[112:115]
	v_mfma_f32_16x16x32_bf16 v[96:99], v[160:163], v[200:203], v[96:99]
	v_mfma_f32_16x16x32_bf16 v[80:83], v[160:163], v[208:211], v[80:83]
	v_mfma_f32_16x16x32_bf16 v[116:119], v[164:167], v[180:183], v[116:119]
	v_mfma_f32_16x16x32_bf16 v[100:103], v[164:167], v[188:191], v[100:103]
	v_mfma_f32_16x16x32_bf16 v[84:87], v[164:167], v[196:199], v[84:87]
	v_mfma_f32_16x16x32_bf16 v[72:75], v[164:167], v[204:207], v[72:75]
	v_mfma_f32_16x16x32_bf16 v[108:111], v[172:175], v[180:183], v[108:111]
	v_mfma_f32_16x16x32_bf16 v[92:95], v[172:175], v[188:191], v[92:95]
	v_mfma_f32_16x16x32_bf16 v[76:79], v[172:175], v[196:199], v[76:79]
	v_mfma_f32_16x16x32_bf16 v[68:71], v[172:175], v[204:207], v[68:71]
	v_mfma_f32_16x16x32_bf16 v[116:119], v[168:171], v[184:187], v[116:119]
	v_mfma_f32_16x16x32_bf16 v[100:103], v[168:171], v[192:195], v[100:103]
	v_mfma_f32_16x16x32_bf16 v[84:87], v[168:171], v[200:203], v[84:87]
	v_mfma_f32_16x16x32_bf16 v[72:75], v[168:171], v[208:211], v[72:75]
	v_mfma_f32_16x16x32_bf16 v[108:111], v[176:179], v[184:187], v[108:111]
	v_mfma_f32_16x16x32_bf16 v[92:95], v[176:179], v[192:195], v[92:95]
	v_mfma_f32_16x16x32_bf16 v[76:79], v[176:179], v[200:203], v[76:79]
	v_mfma_f32_16x16x32_bf16 v[68:71], v[176:179], v[208:211], v[68:71]
	s_barrier
; #define PG8_STAGE(bufoff, gbase, voff) do { _Pragma("unroll") for (int _i = 0; _i < 2; ++_i) \
;         __builtin_amdgcn_global_load_lds((const unsigned*)((const char*)(gbase) + (voff)[_i]), (LAS unsigned*)(lds + (bufoff) + ldsw + _i * 8192), 16, 0, 0); } while (0)
; #define PG8_LDA(dst, b, h) do { _Pragma("unroll") for (int m = 0; m < 4; ++m) _Pragma("unroll") for (int k = 0; k < 2; ++k) dst[m][k] = *(const LAS bf16x8*)(pA + PG8_SA(b, h) + m * 2048 + k * 1024); } while (0)
; #define PG8_MMA(ai, bj, At, Bt) do { __builtin_amdgcn_s_setprio(1); _Pragma("unroll") for (int m = 0; m < 4; ++m) _Pragma("unroll") for (int n = 0; n < 2; ++n) _Pragma("unroll") for (int k = 0; k < 2; ++k) \
;         acc[ai][bj][m][n] = __builtin_amdgcn_mfma_f32_16x16x32_bf16(Bt[n][k], At[m][k], acc[ai][bj][m][n], 0, 0, 0); __builtin_amdgcn_s_setprio(0); } while (0)
; #define PG8_WAIT_V(n) asm volatile("s_waitcnt vmcnt(" #n ")" ::: "memory")
; #define PG8_WAIT_L(n) asm volatile("s_waitcnt lgkmcnt(" #n ")" ::: "memory")
; #define PG8_BAR __builtin_amdgcn_s_barrier()
; #define PG8_SCHED __builtin_amdgcn_sched_barrier(0)
; template <class Desc, class Epi, bool ALIGN_EPI>
; __device__ __forceinline__ void gemm_phase(LAS unsigned char* lds, const Desc& D, const Epi& E, int G, int c) {
;     ...
;             PG8_LDA(At, 1, 1); PG8_STAGE(PG8_SB(1, 0), b3, voffB); PG8_STAGE(PG8_SB(1, 1), b3 + hstepB, voffB); PG8_STAGE(PG8_SA(1, 0), a3, voffA);
;             PG8_WAIT_V(8); PG8_WAIT_L(0); PG8_BAR; PG8_MMA(1, 0, At, B0); PG8_MMA(1, 1, At, B1); PG8_BAR; PG8_SCHED;
;         }
	s_mov_b32 m0, s35
	v_lshl_add_u64 v[212:213], v[212:213], 0, s[76:77]
	s_add_u32 s18, s18, 0x100080
	ds_read_b128 v[180:183], v148 offset:49152
	ds_read_b128 v[184:187], v148 offset:50176
	ds_read_b128 v[188:191], v148 offset:51200
	ds_read_b128 v[192:195], v148 offset:52224
	ds_read_b128 v[196:199], v148 offset:53248
	ds_read_b128 v[200:203], v148 offset:54272
	ds_read_b128 v[204:207], v148 offset:55296
	ds_read_b128 v[208:211], v148 offset:56320
	global_load_lds_dwordx4 v[212:213], off
	v_lshl_add_u64 v[212:213], v[214:215], 0, s[76:77]
	s_mov_b32 m0, s38
	s_addc_u32 s19, s19, 0
	global_load_lds_dwordx4 v[212:213], off
	v_lshl_add_u64 v[212:213], s[18:19], 0, v[136:137]
	s_mov_b32 m0, s41
	s_nop 0
	global_load_lds_dwordx4 v[212:213], off
	v_lshl_add_u64 v[212:213], s[18:19], 0, v[132:133]
	s_mov_b32 m0, s42
	s_nop 0
	global_load_lds_dwordx4 v[212:213], off
	v_lshl_add_u64 v[212:213], v[216:217], 0, s[76:77]
	s_mov_b32 m0, s39
	s_nop 0
	global_load_lds_dwordx4 v[212:213], off
	v_lshl_add_u64 v[212:213], v[218:219], 0, s[76:77]
	s_mov_b32 m0, s40
	s_nop 0
	global_load_lds_dwordx4 v[212:213], off
	s_waitcnt vmcnt(8)
	s_waitcnt lgkmcnt(0)
	s_barrier
	v_mfma_f32_16x16x32_bf16 v[64:67], v[144:147], v[180:183], v[64:67]
	v_mfma_f32_16x16x32_bf16 v[56:59], v[144:147], v[188:191], v[56:59]
	v_mfma_f32_16x16x32_bf16 v[40:43], v[144:147], v[196:199], v[40:43]
	v_mfma_f32_16x16x32_bf16 v[24:27], v[144:147], v[204:207], v[24:27]
	v_mfma_f32_16x16x32_bf16 v[60:63], v[156:159], v[180:183], v[60:63]
	v_mfma_f32_16x16x32_bf16 v[48:51], v[156:159], v[188:191], v[48:51]
	v_mfma_f32_16x16x32_bf16 v[32:35], v[156:159], v[196:199], v[32:35]
	v_mfma_f32_16x16x32_bf16 v[16:19], v[156:159], v[204:207], v[16:19]
	v_mfma_f32_16x16x32_bf16 v[64:67], v[152:155], v[184:187], v[64:67]
	v_mfma_f32_16x16x32_bf16 v[56:59], v[152:155], v[192:195], v[56:59]
	v_mfma_f32_16x16x32_bf16 v[40:43], v[152:155], v[200:203], v[40:43]
	v_mfma_f32_16x16x32_bf16 v[24:27], v[152:155], v[208:211], v[24:27]
	v_mfma_f32_16x16x32_bf16 v[60:63], v[160:163], v[184:187], v[60:63]
	v_mfma_f32_16x16x32_bf16 v[48:51], v[160:163], v[192:195], v[48:51]
	v_mfma_f32_16x16x32_bf16 v[32:35], v[160:163], v[200:203], v[32:35]
	v_mfma_f32_16x16x32_bf16 v[16:19], v[160:163], v[208:211], v[16:19]
	v_mfma_f32_16x16x32_bf16 v[52:55], v[164:167], v[180:183], v[52:55]
	v_mfma_f32_16x16x32_bf16 v[36:39], v[164:167], v[188:191], v[36:39]
	v_mfma_f32_16x16x32_bf16 v[20:23], v[164:167], v[196:199], v[20:23]
	v_mfma_f32_16x16x32_bf16 v[8:11], v[164:167], v[204:207], v[8:11]
	v_mfma_f32_16x16x32_bf16 v[44:47], v[172:175], v[180:183], v[44:47]
	v_mfma_f32_16x16x32_bf16 v[28:31], v[172:175], v[188:191], v[28:31]
	v_mfma_f32_16x16x32_bf16 v[12:15], v[172:175], v[196:199], v[12:15]
	v_mfma_f32_16x16x32_bf16 v[4:7], v[172:175], v[204:207], v[4:7]
	v_mfma_f32_16x16x32_bf16 v[52:55], v[168:171], v[184:187], v[52:55]
	v_mfma_f32_16x16x32_bf16 v[36:39], v[168:171], v[192:195], v[36:39]
	v_mfma_f32_16x16x32_bf16 v[20:23], v[168:171], v[200:203], v[20:23]
	v_mfma_f32_16x16x32_bf16 v[8:11], v[168:171], v[208:211], v[8:11]
	v_mfma_f32_16x16x32_bf16 v[44:47], v[176:179], v[184:187], v[44:47]
	v_mfma_f32_16x16x32_bf16 v[28:31], v[176:179], v[192:195], v[28:31]
	v_mfma_f32_16x16x32_bf16 v[12:15], v[176:179], v[200:203], v[12:15]
	v_mfma_f32_16x16x32_bf16 v[4:7], v[176:179], v[208:211], v[4:7]
	s_barrier
	s_add_u32 s16, s16, 0x100
	s_addc_u32 s17, s17, 0
	s_add_u32 s48, s48, 0x100
	s_addc_u32 s49, s49, 0
	s_cmp_ge_u32 s50, s46
	s_mov_b32 s18, s50
	s_cbranch_scc0 .LBB0_1324
	s_and_b64 vcc, exec, s[6:7]
	s_cbranch_vccz .LBB0_1327
	s_barrier

;     __device__ __forceinline__ int nt(const Unit& u) const { return (u.pn >> 1) < 2 ? 22 : 20; }
; #define PG8_STAGE(bufoff, gbase, voff) do { _Pragma("unroll") for (int _i = 0; _i < 2; ++_i) \
;         __builtin_amdgcn_global_load_lds((const unsigned*)((const char*)(gbase) + (voff)[_i]), (LAS unsigned*)(lds + (bufoff) + ldsw + _i * 8192), 16, 0, 0); } while (0)
; #define PG8_LDA(dst, b, h) do { _Pragma("unroll") for (int m = 0; m < 4; ++m) _Pragma("unroll") for (int k = 0; k < 2; ++k) dst[m][k] = *(const LAS bf16x8*)(pA + PG8_SA(b, h) + m * 2048 + k * 1024); } while (0)
; #define PG8_LDB(dst, b, h) do { _Pragma("unroll") for (int n = 0; n < 2; ++n) _Pragma("unroll") for (int k = 0; k < 2; ++k) dst[n][k] = *(const LAS bf16x8*)(pB + (PG8_SB(b, h) - 4 * HTB) + n * 2048 + k * 1024); } while (0)
; #define PG8_MMA(ai, bj, At, Bt) do { __builtin_amdgcn_s_setprio(1); _Pragma("unroll") for (int m = 0; m < 4; ++m) _Pragma("unroll") for (int n = 0; n < 2; ++n) _Pragma("unroll") for (int k = 0; k < 2; ++k) \
;         acc[ai][bj][m][n] = __builtin_amdgcn_mfma_f32_16x16x32_bf16(Bt[n][k], At[m][k], acc[ai][bj][m][n], 0, 0, 0); __builtin_amdgcn_s_setprio(0); } while (0)
; #define PG8_WAIT_V(n) asm volatile("s_waitcnt vmcnt(" #n ")" ::: "memory")
; #define PG8_BAR __builtin_amdgcn_s_barrier()
; template <class Desc, class Epi, bool ALIGN_EPI>
; __device__ __forceinline__ void gemm_phase(LAS unsigned char* lds, const Desc& D, const Epi& E, int G, int c) {
;     ...
;         for (int t = 0; t < nt; t += 2) {
;             const bool last = (t == nt - 2);
;             if (last && has_next) PG8_AWAIT(nxt);
;             const char* a1 = cA + (size_t)(t + 1) * kstep;
;             const char* a2 = last ? nA : cA + (size_t)(t + 2) * kstep; const char* b2 = last ? nB : cB + (size_t)(t + 2) * kstep;
;             const char* a3 = a2 + kstep; const char* b3 = b2 + kstep;
;             PG8_LDB(B0, 0, 0); PG8_LDB(B1, 0, 1); PG8_SCHED; PG8_LDA(At, 0, 0); PG8_STAGE(PG8_SA(1, 1), a1 + hstepA, voffA);
;             PG8_WAIT_V(8); PG8_WAIT_L(0); PG8_BAR; PG8_MMA(0, 0, At, B0); PG8_MMA(0, 1, At, B1); PG8_BAR; PG8_SCHED;
;             PG8_LDA(At, 0, 1); PG8_STAGE(PG8_SB(0, 0), b2, voffB); PG8_STAGE(PG8_SB(0, 1), b2 + hstepB, voffB); PG8_STAGE(PG8_SA(0, 0), a2, voffA);
;             PG8_WAIT_V(8); PG8_WAIT_L(0); PG8_BAR; PG8_MMA(1, 0, At, B0); PG8_MMA(1, 1, At, B1); PG8_BAR; PG8_SCHED;
.LBB0_1479:
	ds_read_b128 v[116:119], v225
	ds_read_b128 v[128:131], v225 offset:1024
	ds_read_b128 v[132:135], v225 offset:2048
	ds_read_b128 v[136:139], v225 offset:3072
	ds_read_b128 v[140:143], v225 offset:16384
	ds_read_b128 v[144:147], v225 offset:17408
	ds_read_b128 v[148:151], v225 offset:18432
	ds_read_b128 v[152:155], v225 offset:19456
	s_add_u32 s12, s0, 0xfffe0080
	s_addc_u32 s13, s1, -1
	s_cmp_eq_u32 s52, 4
	s_cselect_b32 s17, s37, s13
	s_cselect_b32 s16, s36, s12
	s_cselect_b32 s13, s21, s33
	s_cselect_b32 s12, s24, s27
	v_lshl_add_u64 v[208:209], s[0:1], 0, v[200:201]
	s_add_i32 m0, s31, 0xc000
	ds_read_b128 v[164:167], v224
	ds_read_b128 v[168:171], v224 offset:1024
	ds_read_b128 v[172:175], v224 offset:2048
	ds_read_b128 v[176:179], v224 offset:3072
	ds_read_b128 v[180:183], v224 offset:4096
	ds_read_b128 v[184:187], v224 offset:5120
	ds_read_b128 v[188:191], v224 offset:6144
	ds_read_b128 v[204:207], v224 offset:7168
	global_load_lds_dwordx4 v[208:209], off
	v_lshl_add_u64 v[208:209], s[0:1], 0, v[202:203]
	s_add_i32 m0, s31, 0xe000
	s_nop 0
	global_load_lds_dwordx4 v[208:209], off
	s_waitcnt vmcnt(8)
	s_waitcnt lgkmcnt(0)
	s_barrier
	v_mfma_f32_16x16x32_bf16 v[160:163], v[116:119], v[164:167], v[160:163]
	v_mfma_f32_16x16x32_bf16 v[112:115], v[116:119], v[172:175], v[112:115]
	v_mfma_f32_16x16x32_bf16 v[96:99], v[116:119], v[180:183], v[96:99]
	v_mfma_f32_16x16x32_bf16 v[80:83], v[116:119], v[188:191], v[80:83]
	v_mfma_f32_16x16x32_bf16 v[156:159], v[132:135], v[164:167], v[156:159]
	v_mfma_f32_16x16x32_bf16 v[108:111], v[132:135], v[172:175], v[108:111]
	v_mfma_f32_16x16x32_bf16 v[92:95], v[132:135], v[180:183], v[92:95]
	v_mfma_f32_16x16x32_bf16 v[76:79], v[132:135], v[188:191], v[76:79]
	v_mfma_f32_16x16x32_bf16 v[160:163], v[128:131], v[168:171], v[160:163]
	v_mfma_f32_16x16x32_bf16 v[112:115], v[128:131], v[176:179], v[112:115]
	v_mfma_f32_16x16x32_bf16 v[96:99], v[128:131], v[184:187], v[96:99]
	v_mfma_f32_16x16x32_bf16 v[80:83], v[128:131], v[204:207], v[80:83]
	v_mfma_f32_16x16x32_bf16 v[156:159], v[136:139], v[168:171], v[156:159]
	v_mfma_f32_16x16x32_bf16 v[108:111], v[136:139], v[176:179], v[108:111]
	v_mfma_f32_16x16x32_bf16 v[92:95], v[136:139], v[184:187], v[92:95]
	v_mfma_f32_16x16x32_bf16 v[76:79], v[136:139], v[204:207], v[76:79]
	v_mfma_f32_16x16x32_bf16 v[124:127], v[140:143], v[164:167], v[124:127]
	v_mfma_f32_16x16x32_bf16 v[104:107], v[140:143], v[172:175], v[104:107]
	v_mfma_f32_16x16x32_bf16 v[88:91], v[140:143], v[180:183], v[88:91]
	v_mfma_f32_16x16x32_bf16 v[72:75], v[140:143], v[188:191], v[72:75]
	v_mfma_f32_16x16x32_bf16 v[120:123], v[148:151], v[164:167], v[120:123]
	v_mfma_f32_16x16x32_bf16 v[100:103], v[148:151], v[172:175], v[100:103]
	v_mfma_f32_16x16x32_bf16 v[84:87], v[148:151], v[180:183], v[84:87]
	v_mfma_f32_16x16x32_bf16 v[68:71], v[148:151], v[188:191], v[68:71]
	v_mfma_f32_16x16x32_bf16 v[124:127], v[144:147], v[168:171], v[124:127]
	v_mfma_f32_16x16x32_bf16 v[104:107], v[144:147], v[176:179], v[104:107]
	v_mfma_f32_16x16x32_bf16 v[88:91], v[144:147], v[184:187], v[88:91]
	v_mfma_f32_16x16x32_bf16 v[72:75], v[144:147], v[204:207], v[72:75]
	v_mfma_f32_16x16x32_bf16 v[120:123], v[152:155], v[168:171], v[120:123]
	v_mfma_f32_16x16x32_bf16 v[100:103], v[152:155], v[176:179], v[100:103]
	v_mfma_f32_16x16x32_bf16 v[84:87], v[152:155], v[184:187], v[84:87]
	v_mfma_f32_16x16x32_bf16 v[68:71], v[152:155], v[204:207], v[68:71]
	s_barrier
	s_mov_b32 m0, s34
	v_lshl_add_u64 v[208:209], s[12:13], 0, v[196:197]
	s_add_u32 s54, s12, 0x20000
	ds_read_b128 v[164:167], v224 offset:16384
	ds_read_b128 v[168:171], v224 offset:17408
	ds_read_b128 v[172:175], v224 offset:18432
	ds_read_b128 v[176:179], v224 offset:19456
	ds_read_b128 v[180:183], v224 offset:20480
	ds_read_b128 v[184:187], v224 offset:21504
	ds_read_b128 v[188:191], v224 offset:22528
	ds_read_b128 v[204:207], v224 offset:23552
	global_load_lds_dwordx4 v[208:209], off
	v_lshl_add_u64 v[210:211], s[12:13], 0, v[192:193]
	s_mov_b32 m0, s35
	s_addc_u32 s55, s13, 0
	global_load_lds_dwordx4 v[210:211], off
	v_lshl_add_u64 v[212:213], s[54:55], 0, v[196:197]
	s_mov_b32 m0, s40
	v_lshl_add_u64 v[214:215], s[16:17], 0, v[194:195]
	global_load_lds_dwordx4 v[212:213], off
	v_lshl_add_u64 v[212:213], s[54:55], 0, v[192:193]
	s_mov_b32 m0, s41
	s_nop 0
	global_load_lds_dwordx4 v[212:213], off
	v_lshl_add_u64 v[212:213], s[16:17], 0, v[198:199]
	s_mov_b32 m0, s31
	s_nop 0
	global_load_lds_dwordx4 v[212:213], off
	s_mov_b32 m0, s42
	s_nop 0
	global_load_lds_dwordx4 v[214:215], off
	s_waitcnt vmcnt(8)
	s_waitcnt lgkmcnt(0)
	s_barrier
; #define PG8_STAGE(bufoff, gbase, voff) do { _Pragma("unroll") for (int _i = 0; _i < 2; ++_i) \
;         __builtin_amdgcn_global_load_lds((const unsigned*)((const char*)(gbase) + (voff)[_i]), (LAS unsigned*)(lds + (bufoff) + ldsw + _i * 8192), 16, 0, 0); } while (0)
; #define PG8_LDA(dst, b, h) do { _Pragma("unroll") for (int m = 0; m < 4; ++m) _Pragma("unroll") for (int k = 0; k < 2; ++k) dst[m][k] = *(const LAS bf16x8*)(pA + PG8_SA(b, h) + m * 2048 + k * 1024); } while (0)
; #define PG8_LDB(dst, b, h) do { _Pragma("unroll") for (int n = 0; n < 2; ++n) _Pragma("unroll") for (int k = 0; k < 2; ++k) dst[n][k] = *(const LAS bf16x8*)(pB + (PG8_SB(b, h) - 4 * HTB) + n * 2048 + k * 1024); } while (0)
; #define PG8_MMA(ai, bj, At, Bt) do { __builtin_amdgcn_s_setprio(1); _Pragma("unroll") for (int m = 0; m < 4; ++m) _Pragma("unroll") for (int n = 0; n < 2; ++n) _Pragma("unroll") for (int k = 0; k < 2; ++k) \
;         acc[ai][bj][m][n] = __builtin_amdgcn_mfma_f32_16x16x32_bf16(Bt[n][k], At[m][k], acc[ai][bj][m][n], 0, 0, 0); __builtin_amdgcn_s_setprio(0); } while (0)
; #define PG8_WAIT_V(n) asm volatile("s_waitcnt vmcnt(" #n ")" ::: "memory")
; #define PG8_WAIT_L(n) asm volatile("s_waitcnt lgkmcnt(" #n ")" ::: "memory")
; #define PG8_BAR __builtin_amdgcn_s_barrier()
; #define PG8_SCHED __builtin_amdgcn_sched_barrier(0)
; template <class Desc, class Epi, bool ALIGN_EPI>
; __device__ __forceinline__ void gemm_phase(LAS unsigned char* lds, const Desc& D, const Epi& E, int G, int c) {
;     ...
;             PG8_WAIT_V(8); PG8_WAIT_L(0); PG8_BAR; PG8_MMA(1, 0, At, B0); PG8_MMA(1, 1, At, B1); PG8_BAR; PG8_SCHED;
;             PG8_LDB(B0, 1, 0); PG8_LDB(B1, 1, 1); PG8_SCHED; PG8_LDA(At, 1, 0); PG8_STAGE(PG8_SA(0, 1), a2 + hstepA, voffA);
;             PG8_WAIT_V(8); PG8_WAIT_L(0); PG8_BAR; PG8_MMA(0, 0, At, B0); PG8_MMA(0, 1, At, B1); PG8_BAR; PG8_SCHED;
	v_mfma_f32_16x16x32_bf16 v[64:67], v[116:119], v[164:167], v[64:67]
	v_mfma_f32_16x16x32_bf16 v[48:51], v[116:119], v[172:175], v[48:51]
	v_mfma_f32_16x16x32_bf16 v[32:35], v[116:119], v[180:183], v[32:35]
	v_mfma_f32_16x16x32_bf16 v[16:19], v[116:119], v[188:191], v[16:19]
	v_mfma_f32_16x16x32_bf16 v[60:63], v[132:135], v[164:167], v[60:63]
	v_mfma_f32_16x16x32_bf16 v[44:47], v[132:135], v[172:175], v[44:47]
	v_mfma_f32_16x16x32_bf16 v[28:31], v[132:135], v[180:183], v[28:31]
	v_mfma_f32_16x16x32_bf16 v[12:15], v[132:135], v[188:191], v[12:15]
	v_mfma_f32_16x16x32_bf16 v[64:67], v[128:131], v[168:171], v[64:67]
	v_mfma_f32_16x16x32_bf16 v[48:51], v[128:131], v[176:179], v[48:51]
	v_mfma_f32_16x16x32_bf16 v[32:35], v[128:131], v[184:187], v[32:35]
	v_mfma_f32_16x16x32_bf16 v[16:19], v[128:131], v[204:207], v[16:19]
	v_mfma_f32_16x16x32_bf16 v[60:63], v[136:139], v[168:171], v[60:63]
	v_mfma_f32_16x16x32_bf16 v[44:47], v[136:139], v[176:179], v[44:47]
	v_mfma_f32_16x16x32_bf16 v[28:31], v[136:139], v[184:187], v[28:31]
	v_mfma_f32_16x16x32_bf16 v[12:15], v[136:139], v[204:207], v[12:15]
	v_mfma_f32_16x16x32_bf16 v[56:59], v[140:143], v[164:167], v[56:59]
	v_mfma_f32_16x16x32_bf16 v[40:43], v[140:143], v[172:175], v[40:43]
	v_mfma_f32_16x16x32_bf16 v[24:27], v[140:143], v[180:183], v[24:27]
	v_mfma_f32_16x16x32_bf16 v[8:11], v[140:143], v[188:191], v[8:11]
	v_mfma_f32_16x16x32_bf16 v[52:55], v[148:151], v[164:167], v[52:55]
	v_mfma_f32_16x16x32_bf16 v[36:39], v[148:151], v[172:175], v[36:39]
	v_mfma_f32_16x16x32_bf16 v[20:23], v[148:151], v[180:183], v[20:23]
	v_mfma_f32_16x16x32_bf16 v[4:7], v[148:151], v[188:191], v[4:7]
	v_mfma_f32_16x16x32_bf16 v[56:59], v[144:147], v[168:171], v[56:59]
	v_mfma_f32_16x16x32_bf16 v[40:43], v[144:147], v[176:179], v[40:43]
	v_mfma_f32_16x16x32_bf16 v[24:27], v[144:147], v[184:187], v[24:27]
	v_mfma_f32_16x16x32_bf16 v[8:11], v[144:147], v[204:207], v[8:11]
	v_mfma_f32_16x16x32_bf16 v[52:55], v[152:155], v[168:171], v[52:55]
	v_mfma_f32_16x16x32_bf16 v[36:39], v[152:155], v[176:179], v[36:39]
	v_mfma_f32_16x16x32_bf16 v[20:23], v[152:155], v[184:187], v[20:23]
	v_mfma_f32_16x16x32_bf16 v[4:7], v[152:155], v[204:207], v[4:7]
	s_barrier
	ds_read_b128 v[116:119], v225 offset:32768
	ds_read_b128 v[128:131], v225 offset:33792
	ds_read_b128 v[132:135], v225 offset:34816
	ds_read_b128 v[136:139], v225 offset:35840
	ds_read_b128 v[140:143], v225 offset:49152
	ds_read_b128 v[144:147], v225 offset:50176
	ds_read_b128 v[148:151], v225 offset:51200
	ds_read_b128 v[152:155], v225 offset:52224
	s_add_u32 s16, s16, 0x20000
	s_addc_u32 s17, s17, 0
	s_mov_b32 m0, s43
	v_lshl_add_u64 v[216:217], s[16:17], 0, v[198:199]
	ds_read_b128 v[164:167], v224 offset:32768
	ds_read_b128 v[168:171], v224 offset:33792
	ds_read_b128 v[172:175], v224 offset:34816
	ds_read_b128 v[176:179], v224 offset:35840
	ds_read_b128 v[180:183], v224 offset:36864
	ds_read_b128 v[184:187], v224 offset:37888
	ds_read_b128 v[188:191], v224 offset:38912
	ds_read_b128 v[204:207], v224 offset:39936
	global_load_lds_dwordx4 v[216:217], off
	v_lshl_add_u64 v[216:217], s[16:17], 0, v[194:195]
	s_mov_b32 m0, s44
	s_nop 0
	global_load_lds_dwordx4 v[216:217], off
	s_waitcnt vmcnt(8)
	s_waitcnt lgkmcnt(0)
	s_barrier
	v_mfma_f32_16x16x32_bf16 v[160:163], v[116:119], v[164:167], v[160:163]
	v_mfma_f32_16x16x32_bf16 v[112:115], v[116:119], v[172:175], v[112:115]
	v_mfma_f32_16x16x32_bf16 v[96:99], v[116:119], v[180:183], v[96:99]
	v_mfma_f32_16x16x32_bf16 v[80:83], v[116:119], v[188:191], v[80:83]
	v_mfma_f32_16x16x32_bf16 v[156:159], v[132:135], v[164:167], v[156:159]
	v_mfma_f32_16x16x32_bf16 v[108:111], v[132:135], v[172:175], v[108:111]
	v_mfma_f32_16x16x32_bf16 v[92:95], v[132:135], v[180:183], v[92:95]
	v_mfma_f32_16x16x32_bf16 v[76:79], v[132:135], v[188:191], v[76:79]
	v_mfma_f32_16x16x32_bf16 v[160:163], v[128:131], v[168:171], v[160:163]
	v_mfma_f32_16x16x32_bf16 v[112:115], v[128:131], v[176:179], v[112:115]
	v_mfma_f32_16x16x32_bf16 v[96:99], v[128:131], v[184:187], v[96:99]
	v_mfma_f32_16x16x32_bf16 v[80:83], v[128:131], v[204:207], v[80:83]
	v_mfma_f32_16x16x32_bf16 v[156:159], v[136:139], v[168:171], v[156:159]
	v_mfma_f32_16x16x32_bf16 v[108:111], v[136:139], v[176:179], v[108:111]
	v_mfma_f32_16x16x32_bf16 v[92:95], v[136:139], v[184:187], v[92:95]
	v_mfma_f32_16x16x32_bf16 v[76:79], v[136:139], v[204:207], v[76:79]
	v_mfma_f32_16x16x32_bf16 v[124:127], v[140:143], v[164:167], v[124:127]
	v_mfma_f32_16x16x32_bf16 v[104:107], v[140:143], v[172:175], v[104:107]
	v_mfma_f32_16x16x32_bf16 v[88:91], v[140:143], v[180:183], v[88:91]
	v_mfma_f32_16x16x32_bf16 v[72:75], v[140:143], v[188:191], v[72:75]
	v_mfma_f32_16x16x32_bf16 v[120:123], v[148:151], v[164:167], v[120:123]
	v_mfma_f32_16x16x32_bf16 v[100:103], v[148:151], v[172:175], v[100:103]
	v_mfma_f32_16x16x32_bf16 v[84:87], v[148:151], v[180:183], v[84:87]
	v_mfma_f32_16x16x32_bf16 v[68:71], v[148:151], v[188:191], v[68:71]
	v_mfma_f32_16x16x32_bf16 v[124:127], v[144:147], v[168:171], v[124:127]
	v_mfma_f32_16x16x32_bf16 v[104:107], v[144:147], v[176:179], v[104:107]
	v_mfma_f32_16x16x32_bf16 v[88:91], v[144:147], v[184:187], v[88:91]
	v_mfma_f32_16x16x32_bf16 v[72:75], v[144:147], v[204:207], v[72:75]
	v_mfma_f32_16x16x32_bf16 v[120:123], v[152:155], v[168:171], v[120:123]
	v_mfma_f32_16x16x32_bf16 v[100:103], v[152:155], v[176:179], v[100:103]
	v_mfma_f32_16x16x32_bf16 v[84:87], v[152:155], v[184:187], v[84:87]
	v_mfma_f32_16x16x32_bf16 v[68:71], v[152:155], v[204:207], v[68:71]
	s_barrier
; #define PG8_STAGE(bufoff, gbase, voff) do { _Pragma("unroll") for (int _i = 0; _i < 2; ++_i) \
;         __builtin_amdgcn_global_load_lds((const unsigned*)((const char*)(gbase) + (voff)[_i]), (LAS unsigned*)(lds + (bufoff) + ldsw + _i * 8192), 16, 0, 0); } while (0)
; #define PG8_LDA(dst, b, h) do { _Pragma("unroll") for (int m = 0; m < 4; ++m) _Pragma("unroll") for (int k = 0; k < 2; ++k) dst[m][k] = *(const LAS bf16x8*)(pA + PG8_SA(b, h) + m * 2048 + k * 1024); } while (0)
; #define PG8_MMA(ai, bj, At, Bt) do { __builtin_amdgcn_s_setprio(1); _Pragma("unroll") for (int m = 0; m < 4; ++m) _Pragma("unroll") for (int n = 0; n < 2; ++n) _Pragma("unroll") for (int k = 0; k < 2; ++k) \
;         acc[ai][bj][m][n] = __builtin_amdgcn_mfma_f32_16x16x32_bf16(Bt[n][k], At[m][k], acc[ai][bj][m][n], 0, 0, 0); __builtin_amdgcn_s_setprio(0); } while (0)
; #define PG8_WAIT_V(n) asm volatile("s_waitcnt vmcnt(" #n ")" ::: "memory")
; #define PG8_WAIT_L(n) asm volatile("s_waitcnt lgkmcnt(" #n ")" ::: "memory")
; #define PG8_BAR __builtin_amdgcn_s_barrier()
; #define PG8_SCHED __builtin_amdgcn_sched_barrier(0)
; template <class Desc, class Epi, bool ALIGN_EPI>
; __device__ __forceinline__ void gemm_phase(LAS unsigned char* lds, const Desc& D, const Epi& E, int G, int c) {
;     ...
;             PG8_LDA(At, 1, 1); PG8_STAGE(PG8_SB(1, 0), b3, voffB); PG8_STAGE(PG8_SB(1, 1), b3 + hstepB, voffB); PG8_STAGE(PG8_SA(1, 0), a3, voffA);
;             PG8_WAIT_V(8); PG8_WAIT_L(0); PG8_BAR; PG8_MMA(1, 0, At, B0); PG8_MMA(1, 1, At, B1); PG8_BAR; PG8_SCHED;
;         }
	s_mov_b32 m0, s45
	v_lshl_add_u64 v[208:209], v[208:209], 0, s[76:77]
	s_add_u32 s12, s12, 0x20080
	ds_read_b128 v[164:167], v224 offset:49152
	ds_read_b128 v[168:171], v224 offset:50176
	ds_read_b128 v[172:175], v224 offset:51200
	ds_read_b128 v[176:179], v224 offset:52224
	ds_read_b128 v[180:183], v224 offset:53248
	ds_read_b128 v[184:187], v224 offset:54272
	ds_read_b128 v[188:191], v224 offset:55296
	ds_read_b128 v[204:207], v224 offset:56320
	global_load_lds_dwordx4 v[208:209], off
	v_lshl_add_u64 v[208:209], v[210:211], 0, s[76:77]
	s_mov_b32 m0, s46
	s_addc_u32 s13, s13, 0
	global_load_lds_dwordx4 v[208:209], off
	v_lshl_add_u64 v[208:209], s[12:13], 0, v[196:197]
	s_mov_b32 m0, s49
	s_nop 0
	global_load_lds_dwordx4 v[208:209], off
	v_lshl_add_u64 v[208:209], s[12:13], 0, v[192:193]
	s_mov_b32 m0, s50
	s_nop 0
	global_load_lds_dwordx4 v[208:209], off
	v_lshl_add_u64 v[208:209], v[212:213], 0, s[76:77]
	s_mov_b32 m0, s47
	s_nop 0
	global_load_lds_dwordx4 v[208:209], off
	v_lshl_add_u64 v[208:209], v[214:215], 0, s[76:77]
	s_mov_b32 m0, s48
	s_nop 0
	global_load_lds_dwordx4 v[208:209], off
	s_waitcnt vmcnt(8)
	s_waitcnt lgkmcnt(0)
	s_barrier
	v_mfma_f32_16x16x32_bf16 v[64:67], v[116:119], v[164:167], v[64:67]
	v_mfma_f32_16x16x32_bf16 v[48:51], v[116:119], v[172:175], v[48:51]
	v_mfma_f32_16x16x32_bf16 v[32:35], v[116:119], v[180:183], v[32:35]
	v_mfma_f32_16x16x32_bf16 v[16:19], v[116:119], v[188:191], v[16:19]
	v_mfma_f32_16x16x32_bf16 v[60:63], v[132:135], v[164:167], v[60:63]
	v_mfma_f32_16x16x32_bf16 v[44:47], v[132:135], v[172:175], v[44:47]
	v_mfma_f32_16x16x32_bf16 v[28:31], v[132:135], v[180:183], v[28:31]
	v_mfma_f32_16x16x32_bf16 v[12:15], v[132:135], v[188:191], v[12:15]
	v_mfma_f32_16x16x32_bf16 v[64:67], v[128:131], v[168:171], v[64:67]
	v_mfma_f32_16x16x32_bf16 v[48:51], v[128:131], v[176:179], v[48:51]
	v_mfma_f32_16x16x32_bf16 v[32:35], v[128:131], v[184:187], v[32:35]
	v_mfma_f32_16x16x32_bf16 v[16:19], v[128:131], v[204:207], v[16:19]
	v_mfma_f32_16x16x32_bf16 v[60:63], v[136:139], v[168:171], v[60:63]
	v_mfma_f32_16x16x32_bf16 v[44:47], v[136:139], v[176:179], v[44:47]
	v_mfma_f32_16x16x32_bf16 v[28:31], v[136:139], v[184:187], v[28:31]
	v_mfma_f32_16x16x32_bf16 v[12:15], v[136:139], v[204:207], v[12:15]
	v_mfma_f32_16x16x32_bf16 v[56:59], v[140:143], v[164:167], v[56:59]
	v_mfma_f32_16x16x32_bf16 v[40:43], v[140:143], v[172:175], v[40:43]
	v_mfma_f32_16x16x32_bf16 v[24:27], v[140:143], v[180:183], v[24:27]
	v_mfma_f32_16x16x32_bf16 v[8:11], v[140:143], v[188:191], v[8:11]
	v_mfma_f32_16x16x32_bf16 v[52:55], v[148:151], v[164:167], v[52:55]
	v_mfma_f32_16x16x32_bf16 v[36:39], v[148:151], v[172:175], v[36:39]
	v_mfma_f32_16x16x32_bf16 v[20:23], v[148:151], v[180:183], v[20:23]
	v_mfma_f32_16x16x32_bf16 v[4:7], v[148:151], v[188:191], v[4:7]
	v_mfma_f32_16x16x32_bf16 v[56:59], v[144:147], v[168:171], v[56:59]
	v_mfma_f32_16x16x32_bf16 v[40:43], v[144:147], v[176:179], v[40:43]
	v_mfma_f32_16x16x32_bf16 v[24:27], v[144:147], v[184:187], v[24:27]
	v_mfma_f32_16x16x32_bf16 v[8:11], v[144:147], v[204:207], v[8:11]
	v_mfma_f32_16x16x32_bf16 v[52:55], v[152:155], v[168:171], v[52:55]
	v_mfma_f32_16x16x32_bf16 v[36:39], v[152:155], v[176:179], v[36:39]
	v_mfma_f32_16x16x32_bf16 v[20:23], v[152:155], v[184:187], v[20:23]
	v_mfma_f32_16x16x32_bf16 v[4:7], v[152:155], v[204:207], v[4:7]
	s_barrier
	s_add_i32 s52, s52, 2
	s_add_u32 s0, s0, 0x100
	s_addc_u32 s1, s1, 0
	s_add_u32 s27, s27, 0x100
	s_addc_u32 s33, s33, 0
	s_cmp_gt_u32 s52, 5
	s_cbranch_scc0 .LBB0_1479
	s_and_b64 vcc, exec, s[8:9]
	s_cbranch_vccz .LBB0_1482
	s_barrier

;     __device__ __forceinline__ int nt(const Unit& u) const { return (u.pn >> 1) < 2 ? 22 : 20; }
; #define PG8_STAGE(bufoff, gbase, voff) do { _Pragma("unroll") for (int _i = 0; _i < 2; ++_i) \
;         __builtin_amdgcn_global_load_lds((const unsigned*)((const char*)(gbase) + (voff)[_i]), (LAS unsigned*)(lds + (bufoff) + ldsw + _i * 8192), 16, 0, 0); } while (0)
; #define PG8_LDA(dst, b, h) do { _Pragma("unroll") for (int m = 0; m < 4; ++m) _Pragma("unroll") for (int k = 0; k < 2; ++k) dst[m][k] = *(const LAS bf16x8*)(pA + PG8_SA(b, h) + m * 2048 + k * 1024); } while (0)
; #define PG8_LDB(dst, b, h) do { _Pragma("unroll") for (int n = 0; n < 2; ++n) _Pragma("unroll") for (int k = 0; k < 2; ++k) dst[n][k] = *(const LAS bf16x8*)(pB + (PG8_SB(b, h) - 4 * HTB) + n * 2048 + k * 1024); } while (0)
; #define PG8_MMA(ai, bj, At, Bt) do { __builtin_amdgcn_s_setprio(1); _Pragma("unroll") for (int m = 0; m < 4; ++m) _Pragma("unroll") for (int n = 0; n < 2; ++n) _Pragma("unroll") for (int k = 0; k < 2; ++k) \
;         acc[ai][bj][m][n] = __builtin_amdgcn_mfma_f32_16x16x32_bf16(Bt[n][k], At[m][k], acc[ai][bj][m][n], 0, 0, 0); __builtin_amdgcn_s_setprio(0); } while (0)
; #define PG8_WAIT_V(n) asm volatile("s_waitcnt vmcnt(" #n ")" ::: "memory")
; #define PG8_BAR __builtin_amdgcn_s_barrier()
; template <class Desc, class Epi, bool ALIGN_EPI>
; __device__ __forceinline__ void gemm_phase(LAS unsigned char* lds, const Desc& D, const Epi& E, int G, int c) {
;     ...
;         for (int t = 0; t < nt; t += 2) {
;             const bool last = (t == nt - 2);
;             if (last && has_next) PG8_AWAIT(nxt);
;             const char* a1 = cA + (size_t)(t + 1) * kstep;
;             const char* a2 = last ? nA : cA + (size_t)(t + 2) * kstep; const char* b2 = last ? nB : cB + (size_t)(t + 2) * kstep;
;             const char* a3 = a2 + kstep; const char* b3 = b2 + kstep;
;             PG8_LDB(B0, 0, 0); PG8_LDB(B1, 0, 1); PG8_SCHED; PG8_LDA(At, 0, 0); PG8_STAGE(PG8_SA(1, 1), a1 + hstepA, voffA);
;             PG8_WAIT_V(8); PG8_WAIT_L(0); PG8_BAR; PG8_MMA(0, 0, At, B0); PG8_MMA(0, 1, At, B1); PG8_BAR; PG8_SCHED;
;             PG8_LDA(At, 0, 1); PG8_STAGE(PG8_SB(0, 0), b2, voffB); PG8_STAGE(PG8_SB(0, 1), b2 + hstepB, voffB); PG8_STAGE(PG8_SA(0, 0), a2, voffA);
;             PG8_WAIT_V(8); PG8_WAIT_L(0); PG8_BAR; PG8_MMA(1, 0, At, B0); PG8_MMA(1, 1, At, B1); PG8_BAR; PG8_SCHED;
.LBB0_1517:
	ds_read_b128 v[116:119], v225
	ds_read_b128 v[128:131], v225 offset:1024
	ds_read_b128 v[132:135], v225 offset:2048
	ds_read_b128 v[136:139], v225 offset:3072
	ds_read_b128 v[140:143], v225 offset:16384
	ds_read_b128 v[144:147], v225 offset:17408
	ds_read_b128 v[148:151], v225 offset:18432
	ds_read_b128 v[152:155], v225 offset:19456
	s_add_u32 s12, s0, 0xfffe0080
	s_addc_u32 s13, s1, -1
	s_cmp_eq_u32 s54, 4
	s_cselect_b32 s17, s37, s13
	s_cselect_b32 s16, s36, s12
	s_cselect_b32 s13, s21, s33
	s_cselect_b32 s12, s24, s27
	v_lshl_add_u64 v[208:209], s[0:1], 0, v[200:201]
	s_add_i32 m0, s31, 0xc000
	ds_read_b128 v[164:167], v224
	ds_read_b128 v[168:171], v224 offset:1024
	ds_read_b128 v[172:175], v224 offset:2048
	ds_read_b128 v[176:179], v224 offset:3072
	ds_read_b128 v[180:183], v224 offset:4096
	ds_read_b128 v[184:187], v224 offset:5120
	ds_read_b128 v[188:191], v224 offset:6144
	ds_read_b128 v[204:207], v224 offset:7168
	global_load_lds_dwordx4 v[208:209], off
	v_lshl_add_u64 v[208:209], s[0:1], 0, v[202:203]
	s_add_i32 m0, s31, 0xe000
	s_nop 0
	global_load_lds_dwordx4 v[208:209], off
	s_waitcnt vmcnt(8)
	s_waitcnt lgkmcnt(0)
	s_barrier
	v_mfma_f32_16x16x32_bf16 v[160:163], v[116:119], v[164:167], v[160:163]
	v_mfma_f32_16x16x32_bf16 v[112:115], v[116:119], v[172:175], v[112:115]
	v_mfma_f32_16x16x32_bf16 v[96:99], v[116:119], v[180:183], v[96:99]
	v_mfma_f32_16x16x32_bf16 v[80:83], v[116:119], v[188:191], v[80:83]
	v_mfma_f32_16x16x32_bf16 v[156:159], v[132:135], v[164:167], v[156:159]
	v_mfma_f32_16x16x32_bf16 v[108:111], v[132:135], v[172:175], v[108:111]
	v_mfma_f32_16x16x32_bf16 v[92:95], v[132:135], v[180:183], v[92:95]
	v_mfma_f32_16x16x32_bf16 v[76:79], v[132:135], v[188:191], v[76:79]
	v_mfma_f32_16x16x32_bf16 v[160:163], v[128:131], v[168:171], v[160:163]
	v_mfma_f32_16x16x32_bf16 v[112:115], v[128:131], v[176:179], v[112:115]
	v_mfma_f32_16x16x32_bf16 v[96:99], v[128:131], v[184:187], v[96:99]
	v_mfma_f32_16x16x32_bf16 v[80:83], v[128:131], v[204:207], v[80:83]
	v_mfma_f32_16x16x32_bf16 v[156:159], v[136:139], v[168:171], v[156:159]
	v_mfma_f32_16x16x32_bf16 v[108:111], v[136:139], v[176:179], v[108:111]
	v_mfma_f32_16x16x32_bf16 v[92:95], v[136:139], v[184:187], v[92:95]
	v_mfma_f32_16x16x32_bf16 v[76:79], v[136:139], v[204:207], v[76:79]
	v_mfma_f32_16x16x32_bf16 v[124:127], v[140:143], v[164:167], v[124:127]
	v_mfma_f32_16x16x32_bf16 v[104:107], v[140:143], v[172:175], v[104:107]
	v_mfma_f32_16x16x32_bf16 v[88:91], v[140:143], v[180:183], v[88:91]
	v_mfma_f32_16x16x32_bf16 v[72:75], v[140:143], v[188:191], v[72:75]
	v_mfma_f32_16x16x32_bf16 v[120:123], v[148:151], v[164:167], v[120:123]
	v_mfma_f32_16x16x32_bf16 v[100:103], v[148:151], v[172:175], v[100:103]
	v_mfma_f32_16x16x32_bf16 v[84:87], v[148:151], v[180:183], v[84:87]
	v_mfma_f32_16x16x32_bf16 v[68:71], v[148:151], v[188:191], v[68:71]
	v_mfma_f32_16x16x32_bf16 v[124:127], v[144:147], v[168:171], v[124:127]
	v_mfma_f32_16x16x32_bf16 v[104:107], v[144:147], v[176:179], v[104:107]
	v_mfma_f32_16x16x32_bf16 v[88:91], v[144:147], v[184:187], v[88:91]
	v_mfma_f32_16x16x32_bf16 v[72:75], v[144:147], v[204:207], v[72:75]
	v_mfma_f32_16x16x32_bf16 v[120:123], v[152:155], v[168:171], v[120:123]
	v_mfma_f32_16x16x32_bf16 v[100:103], v[152:155], v[176:179], v[100:103]
	v_mfma_f32_16x16x32_bf16 v[84:87], v[152:155], v[184:187], v[84:87]
	v_mfma_f32_16x16x32_bf16 v[68:71], v[152:155], v[204:207], v[68:71]
	s_barrier
	s_mov_b32 m0, s34
	v_lshl_add_u64 v[208:209], s[12:13], 0, v[196:197]
	s_add_u32 s56, s12, 0x20000
	ds_read_b128 v[164:167], v224 offset:16384
	ds_read_b128 v[168:171], v224 offset:17408
	ds_read_b128 v[172:175], v224 offset:18432
	ds_read_b128 v[176:179], v224 offset:19456
	ds_read_b128 v[180:183], v224 offset:20480
	ds_read_b128 v[184:187], v224 offset:21504
	ds_read_b128 v[188:191], v224 offset:22528
	ds_read_b128 v[204:207], v224 offset:23552
	global_load_lds_dwordx4 v[208:209], off
	v_lshl_add_u64 v[210:211], s[12:13], 0, v[192:193]
	s_mov_b32 m0, s35
	s_addc_u32 s57, s13, 0
	global_load_lds_dwordx4 v[210:211], off
	v_lshl_add_u64 v[212:213], s[56:57], 0, v[196:197]
	s_mov_b32 m0, s42
	v_lshl_add_u64 v[214:215], s[16:17], 0, v[194:195]
	global_load_lds_dwordx4 v[212:213], off
	v_lshl_add_u64 v[212:213], s[56:57], 0, v[192:193]
	s_mov_b32 m0, s43
	s_nop 0
	global_load_lds_dwordx4 v[212:213], off
	v_lshl_add_u64 v[212:213], s[16:17], 0, v[198:199]
	s_mov_b32 m0, s31
	s_nop 0
	global_load_lds_dwordx4 v[212:213], off
	s_mov_b32 m0, s44
	s_nop 0
	global_load_lds_dwordx4 v[214:215], off
	s_waitcnt vmcnt(8)
	s_waitcnt lgkmcnt(0)
	s_barrier
; #define PG8_STAGE(bufoff, gbase, voff) do { _Pragma("unroll") for (int _i = 0; _i < 2; ++_i) \
;         __builtin_amdgcn_global_load_lds((const unsigned*)((const char*)(gbase) + (voff)[_i]), (LAS unsigned*)(lds + (bufoff) + ldsw + _i * 8192), 16, 0, 0); } while (0)
; #define PG8_LDA(dst, b, h) do { _Pragma("unroll") for (int m = 0; m < 4; ++m) _Pragma("unroll") for (int k = 0; k < 2; ++k) dst[m][k] = *(const LAS bf16x8*)(pA + PG8_SA(b, h) + m * 2048 + k * 1024); } while (0)
; #define PG8_LDB(dst, b, h) do { _Pragma("unroll") for (int n = 0; n < 2; ++n) _Pragma("unroll") for (int k = 0; k < 2; ++k) dst[n][k] = *(const LAS bf16x8*)(pB + (PG8_SB(b, h) - 4 * HTB) + n * 2048 + k * 1024); } while (0)
; #define PG8_MMA(ai, bj, At, Bt) do { __builtin_amdgcn_s_setprio(1); _Pragma("unroll") for (int m = 0; m < 4; ++m) _Pragma("unroll") for (int n = 0; n < 2; ++n) _Pragma("unroll") for (int k = 0; k < 2; ++k) \
;         acc[ai][bj][m][n] = __builtin_amdgcn_mfma_f32_16x16x32_bf16(Bt[n][k], At[m][k], acc[ai][bj][m][n], 0, 0, 0); __builtin_amdgcn_s_setprio(0); } while (0)
; #define PG8_WAIT_V(n) asm volatile("s_waitcnt vmcnt(" #n ")" ::: "memory")
; #define PG8_WAIT_L(n) asm volatile("s_waitcnt lgkmcnt(" #n ")" ::: "memory")
; #define PG8_BAR __builtin_amdgcn_s_barrier()
; #define PG8_SCHED __builtin_amdgcn_sched_barrier(0)
; template <class Desc, class Epi, bool ALIGN_EPI>
; __device__ __forceinline__ void gemm_phase(LAS unsigned char* lds, const Desc& D, const Epi& E, int G, int c) {
;     ...
;             PG8_WAIT_V(8); PG8_WAIT_L(0); PG8_BAR; PG8_MMA(1, 0, At, B0); PG8_MMA(1, 1, At, B1); PG8_BAR; PG8_SCHED;
;             PG8_LDB(B0, 1, 0); PG8_LDB(B1, 1, 1); PG8_SCHED; PG8_LDA(At, 1, 0); PG8_STAGE(PG8_SA(0, 1), a2 + hstepA, voffA);
;             PG8_WAIT_V(8); PG8_WAIT_L(0); PG8_BAR; PG8_MMA(0, 0, At, B0); PG8_MMA(0, 1, At, B1); PG8_BAR; PG8_SCHED;
	v_mfma_f32_16x16x32_bf16 v[64:67], v[116:119], v[164:167], v[64:67]
	v_mfma_f32_16x16x32_bf16 v[48:51], v[116:119], v[172:175], v[48:51]
	v_mfma_f32_16x16x32_bf16 v[32:35], v[116:119], v[180:183], v[32:35]
	v_mfma_f32_16x16x32_bf16 v[16:19], v[116:119], v[188:191], v[16:19]
	v_mfma_f32_16x16x32_bf16 v[60:63], v[132:135], v[164:167], v[60:63]
	v_mfma_f32_16x16x32_bf16 v[44:47], v[132:135], v[172:175], v[44:47]
	v_mfma_f32_16x16x32_bf16 v[28:31], v[132:135], v[180:183], v[28:31]
	v_mfma_f32_16x16x32_bf16 v[12:15], v[132:135], v[188:191], v[12:15]
	v_mfma_f32_16x16x32_bf16 v[64:67], v[128:131], v[168:171], v[64:67]
	v_mfma_f32_16x16x32_bf16 v[48:51], v[128:131], v[176:179], v[48:51]
	v_mfma_f32_16x16x32_bf16 v[32:35], v[128:131], v[184:187], v[32:35]
	v_mfma_f32_16x16x32_bf16 v[16:19], v[128:131], v[204:207], v[16:19]
	v_mfma_f32_16x16x32_bf16 v[60:63], v[136:139], v[168:171], v[60:63]
	v_mfma_f32_16x16x32_bf16 v[44:47], v[136:139], v[176:179], v[44:47]
	v_mfma_f32_16x16x32_bf16 v[28:31], v[136:139], v[184:187], v[28:31]
	v_mfma_f32_16x16x32_bf16 v[12:15], v[136:139], v[204:207], v[12:15]
	v_mfma_f32_16x16x32_bf16 v[56:59], v[140:143], v[164:167], v[56:59]
	v_mfma_f32_16x16x32_bf16 v[40:43], v[140:143], v[172:175], v[40:43]
	v_mfma_f32_16x16x32_bf16 v[24:27], v[140:143], v[180:183], v[24:27]
	v_mfma_f32_16x16x32_bf16 v[8:11], v[140:143], v[188:191], v[8:11]
	v_mfma_f32_16x16x32_bf16 v[52:55], v[148:151], v[164:167], v[52:55]
	v_mfma_f32_16x16x32_bf16 v[36:39], v[148:151], v[172:175], v[36:39]
	v_mfma_f32_16x16x32_bf16 v[20:23], v[148:151], v[180:183], v[20:23]
	v_mfma_f32_16x16x32_bf16 v[4:7], v[148:151], v[188:191], v[4:7]
	v_mfma_f32_16x16x32_bf16 v[56:59], v[144:147], v[168:171], v[56:59]
	v_mfma_f32_16x16x32_bf16 v[40:43], v[144:147], v[176:179], v[40:43]
	v_mfma_f32_16x16x32_bf16 v[24:27], v[144:147], v[184:187], v[24:27]
	v_mfma_f32_16x16x32_bf16 v[8:11], v[144:147], v[204:207], v[8:11]
	v_mfma_f32_16x16x32_bf16 v[52:55], v[152:155], v[168:171], v[52:55]
	v_mfma_f32_16x16x32_bf16 v[36:39], v[152:155], v[176:179], v[36:39]
	v_mfma_f32_16x16x32_bf16 v[20:23], v[152:155], v[184:187], v[20:23]
	v_mfma_f32_16x16x32_bf16 v[4:7], v[152:155], v[204:207], v[4:7]
	s_barrier
	ds_read_b128 v[116:119], v225 offset:32768
	ds_read_b128 v[128:131], v225 offset:33792
	ds_read_b128 v[132:135], v225 offset:34816
	ds_read_b128 v[136:139], v225 offset:35840
	ds_read_b128 v[140:143], v225 offset:49152
	ds_read_b128 v[144:147], v225 offset:50176
	ds_read_b128 v[148:151], v225 offset:51200
	ds_read_b128 v[152:155], v225 offset:52224
	s_add_u32 s16, s16, 0x20000
	s_addc_u32 s17, s17, 0
	s_mov_b32 m0, s45
	v_lshl_add_u64 v[216:217], s[16:17], 0, v[198:199]
	ds_read_b128 v[164:167], v224 offset:32768
	ds_read_b128 v[168:171], v224 offset:33792
	ds_read_b128 v[172:175], v224 offset:34816
	ds_read_b128 v[176:179], v224 offset:35840
	ds_read_b128 v[180:183], v224 offset:36864
	ds_read_b128 v[184:187], v224 offset:37888
	ds_read_b128 v[188:191], v224 offset:38912
	ds_read_b128 v[204:207], v224 offset:39936
	global_load_lds_dwordx4 v[216:217], off
	v_lshl_add_u64 v[216:217], s[16:17], 0, v[194:195]
	s_mov_b32 m0, s46
	s_nop 0
	global_load_lds_dwordx4 v[216:217], off
	s_waitcnt vmcnt(8)
	s_waitcnt lgkmcnt(0)
	s_barrier
	v_mfma_f32_16x16x32_bf16 v[160:163], v[116:119], v[164:167], v[160:163]
	v_mfma_f32_16x16x32_bf16 v[112:115], v[116:119], v[172:175], v[112:115]
	v_mfma_f32_16x16x32_bf16 v[96:99], v[116:119], v[180:183], v[96:99]
	v_mfma_f32_16x16x32_bf16 v[80:83], v[116:119], v[188:191], v[80:83]
	v_mfma_f32_16x16x32_bf16 v[156:159], v[132:135], v[164:167], v[156:159]
	v_mfma_f32_16x16x32_bf16 v[108:111], v[132:135], v[172:175], v[108:111]
	v_mfma_f32_16x16x32_bf16 v[92:95], v[132:135], v[180:183], v[92:95]
	v_mfma_f32_16x16x32_bf16 v[76:79], v[132:135], v[188:191], v[76:79]
	v_mfma_f32_16x16x32_bf16 v[160:163], v[128:131], v[168:171], v[160:163]
	v_mfma_f32_16x16x32_bf16 v[112:115], v[128:131], v[176:179], v[112:115]
	v_mfma_f32_16x16x32_bf16 v[96:99], v[128:131], v[184:187], v[96:99]
	v_mfma_f32_16x16x32_bf16 v[80:83], v[128:131], v[204:207], v[80:83]
	v_mfma_f32_16x16x32_bf16 v[156:159], v[136:139], v[168:171], v[156:159]
	v_mfma_f32_16x16x32_bf16 v[108:111], v[136:139], v[176:179], v[108:111]
	v_mfma_f32_16x16x32_bf16 v[92:95], v[136:139], v[184:187], v[92:95]
	v_mfma_f32_16x16x32_bf16 v[76:79], v[136:139], v[204:207], v[76:79]
	v_mfma_f32_16x16x32_bf16 v[124:127], v[140:143], v[164:167], v[124:127]
	v_mfma_f32_16x16x32_bf16 v[104:107], v[140:143], v[172:175], v[104:107]
	v_mfma_f32_16x16x32_bf16 v[88:91], v[140:143], v[180:183], v[88:91]
	v_mfma_f32_16x16x32_bf16 v[72:75], v[140:143], v[188:191], v[72:75]
	v_mfma_f32_16x16x32_bf16 v[120:123], v[148:151], v[164:167], v[120:123]
	v_mfma_f32_16x16x32_bf16 v[100:103], v[148:151], v[172:175], v[100:103]
	v_mfma_f32_16x16x32_bf16 v[84:87], v[148:151], v[180:183], v[84:87]
	v_mfma_f32_16x16x32_bf16 v[68:71], v[148:151], v[188:191], v[68:71]
	v_mfma_f32_16x16x32_bf16 v[124:127], v[144:147], v[168:171], v[124:127]
	v_mfma_f32_16x16x32_bf16 v[104:107], v[144:147], v[176:179], v[104:107]
	v_mfma_f32_16x16x32_bf16 v[88:91], v[144:147], v[184:187], v[88:91]
	v_mfma_f32_16x16x32_bf16 v[72:75], v[144:147], v[204:207], v[72:75]
	v_mfma_f32_16x16x32_bf16 v[120:123], v[152:155], v[168:171], v[120:123]
	v_mfma_f32_16x16x32_bf16 v[100:103], v[152:155], v[176:179], v[100:103]
	v_mfma_f32_16x16x32_bf16 v[84:87], v[152:155], v[184:187], v[84:87]
	v_mfma_f32_16x16x32_bf16 v[68:71], v[152:155], v[204:207], v[68:71]
	s_barrier
; #define PG8_STAGE(bufoff, gbase, voff) do { _Pragma("unroll") for (int _i = 0; _i < 2; ++_i) \
;         __builtin_amdgcn_global_load_lds((const unsigned*)((const char*)(gbase) + (voff)[_i]), (LAS unsigned*)(lds + (bufoff) + ldsw + _i * 8192), 16, 0, 0); } while (0)
; #define PG8_LDA(dst, b, h) do { _Pragma("unroll") for (int m = 0; m < 4; ++m) _Pragma("unroll") for (int k = 0; k < 2; ++k) dst[m][k] = *(const LAS bf16x8*)(pA + PG8_SA(b, h) + m * 2048 + k * 1024); } while (0)
; #define PG8_MMA(ai, bj, At, Bt) do { __builtin_amdgcn_s_setprio(1); _Pragma("unroll") for (int m = 0; m < 4; ++m) _Pragma("unroll") for (int n = 0; n < 2; ++n) _Pragma("unroll") for (int k = 0; k < 2; ++k) \
;         acc[ai][bj][m][n] = __builtin_amdgcn_mfma_f32_16x16x32_bf16(Bt[n][k], At[m][k], acc[ai][bj][m][n], 0, 0, 0); __builtin_amdgcn_s_setprio(0); } while (0)
; #define PG8_WAIT_V(n) asm volatile("s_waitcnt vmcnt(" #n ")" ::: "memory")
; #define PG8_WAIT_L(n) asm volatile("s_waitcnt lgkmcnt(" #n ")" ::: "memory")
; #define PG8_BAR __builtin_amdgcn_s_barrier()
; #define PG8_SCHED __builtin_amdgcn_sched_barrier(0)
; template <class Desc, class Epi, bool ALIGN_EPI>
; __device__ __forceinline__ void gemm_phase(LAS unsigned char* lds, const Desc& D, const Epi& E, int G, int c) {
;     ...
;             PG8_LDA(At, 1, 1); PG8_STAGE(PG8_SB(1, 0), b3, voffB); PG8_STAGE(PG8_SB(1, 1), b3 + hstepB, voffB); PG8_STAGE(PG8_SA(1, 0), a3, voffA);
;             PG8_WAIT_V(8); PG8_WAIT_L(0); PG8_BAR; PG8_MMA(1, 0, At, B0); PG8_MMA(1, 1, At, B1); PG8_BAR; PG8_SCHED;
;         }
	s_mov_b32 m0, s47
	v_lshl_add_u64 v[208:209], v[208:209], 0, s[76:77]
	s_add_u32 s12, s12, 0x20080
	ds_read_b128 v[164:167], v224 offset:49152
	ds_read_b128 v[168:171], v224 offset:50176
	ds_read_b128 v[172:175], v224 offset:51200
	ds_read_b128 v[176:179], v224 offset:52224
	ds_read_b128 v[180:183], v224 offset:53248
	ds_read_b128 v[184:187], v224 offset:54272
	ds_read_b128 v[188:191], v224 offset:55296
	ds_read_b128 v[204:207], v224 offset:56320
	global_load_lds_dwordx4 v[208:209], off
	v_lshl_add_u64 v[208:209], v[210:211], 0, s[76:77]
	s_mov_b32 m0, s48
	s_addc_u32 s13, s13, 0
	global_load_lds_dwordx4 v[208:209], off
	v_lshl_add_u64 v[208:209], s[12:13], 0, v[196:197]
	s_mov_b32 m0, s51
	s_nop 0
	global_load_lds_dwordx4 v[208:209], off
	v_lshl_add_u64 v[208:209], s[12:13], 0, v[192:193]
	s_mov_b32 m0, s52
	s_nop 0
	global_load_lds_dwordx4 v[208:209], off
	v_lshl_add_u64 v[208:209], v[212:213], 0, s[76:77]
	s_mov_b32 m0, s49
	s_nop 0
	global_load_lds_dwordx4 v[208:209], off
	v_lshl_add_u64 v[208:209], v[214:215], 0, s[76:77]
	s_mov_b32 m0, s50
	s_nop 0
	global_load_lds_dwordx4 v[208:209], off
	s_waitcnt vmcnt(8)
	s_waitcnt lgkmcnt(0)
	s_barrier
	v_mfma_f32_16x16x32_bf16 v[64:67], v[116:119], v[164:167], v[64:67]
	v_mfma_f32_16x16x32_bf16 v[48:51], v[116:119], v[172:175], v[48:51]
	v_mfma_f32_16x16x32_bf16 v[32:35], v[116:119], v[180:183], v[32:35]
	v_mfma_f32_16x16x32_bf16 v[16:19], v[116:119], v[188:191], v[16:19]
	v_mfma_f32_16x16x32_bf16 v[60:63], v[132:135], v[164:167], v[60:63]
	v_mfma_f32_16x16x32_bf16 v[44:47], v[132:135], v[172:175], v[44:47]
	v_mfma_f32_16x16x32_bf16 v[28:31], v[132:135], v[180:183], v[28:31]
	v_mfma_f32_16x16x32_bf16 v[12:15], v[132:135], v[188:191], v[12:15]
	v_mfma_f32_16x16x32_bf16 v[64:67], v[128:131], v[168:171], v[64:67]
	v_mfma_f32_16x16x32_bf16 v[48:51], v[128:131], v[176:179], v[48:51]
	v_mfma_f32_16x16x32_bf16 v[32:35], v[128:131], v[184:187], v[32:35]
	v_mfma_f32_16x16x32_bf16 v[16:19], v[128:131], v[204:207], v[16:19]
	v_mfma_f32_16x16x32_bf16 v[60:63], v[136:139], v[168:171], v[60:63]
	v_mfma_f32_16x16x32_bf16 v[44:47], v[136:139], v[176:179], v[44:47]
	v_mfma_f32_16x16x32_bf16 v[28:31], v[136:139], v[184:187], v[28:31]
	v_mfma_f32_16x16x32_bf16 v[12:15], v[136:139], v[204:207], v[12:15]
	v_mfma_f32_16x16x32_bf16 v[56:59], v[140:143], v[164:167], v[56:59]
	v_mfma_f32_16x16x32_bf16 v[40:43], v[140:143], v[172:175], v[40:43]
	v_mfma_f32_16x16x32_bf16 v[24:27], v[140:143], v[180:183], v[24:27]
	v_mfma_f32_16x16x32_bf16 v[8:11], v[140:143], v[188:191], v[8:11]
	v_mfma_f32_16x16x32_bf16 v[52:55], v[148:151], v[164:167], v[52:55]
	v_mfma_f32_16x16x32_bf16 v[36:39], v[148:151], v[172:175], v[36:39]
	v_mfma_f32_16x16x32_bf16 v[20:23], v[148:151], v[180:183], v[20:23]
	v_mfma_f32_16x16x32_bf16 v[4:7], v[148:151], v[188:191], v[4:7]
	v_mfma_f32_16x16x32_bf16 v[56:59], v[144:147], v[168:171], v[56:59]
	v_mfma_f32_16x16x32_bf16 v[40:43], v[144:147], v[176:179], v[40:43]
	v_mfma_f32_16x16x32_bf16 v[24:27], v[144:147], v[184:187], v[24:27]
	v_mfma_f32_16x16x32_bf16 v[8:11], v[144:147], v[204:207], v[8:11]
	v_mfma_f32_16x16x32_bf16 v[52:55], v[152:155], v[168:171], v[52:55]
	v_mfma_f32_16x16x32_bf16 v[36:39], v[152:155], v[176:179], v[36:39]
	v_mfma_f32_16x16x32_bf16 v[20:23], v[152:155], v[184:187], v[20:23]
	v_mfma_f32_16x16x32_bf16 v[4:7], v[152:155], v[204:207], v[4:7]
	s_barrier
	s_add_i32 s54, s54, 2
	s_add_u32 s0, s0, 0x100
	s_addc_u32 s1, s1, 0
	s_add_u32 s27, s27, 0x100
	s_addc_u32 s33, s33, 0
	s_cmp_gt_u32 s54, 5
	s_cbranch_scc0 .LBB0_1517
	s_and_b64 vcc, exec, s[10:11]
	s_cbranch_vccz .LBB0_1520
	s_barrier

;     __device__ __forceinline__ int nt(const Unit& u) const { return (u.pn >> 1) < 2 ? 22 : 20; }
; #define PG8_STAGE(bufoff, gbase, voff) do { _Pragma("unroll") for (int _i = 0; _i < 2; ++_i) \
;         __builtin_amdgcn_global_load_lds((const unsigned*)((const char*)(gbase) + (voff)[_i]), (LAS unsigned*)(lds + (bufoff) + ldsw + _i * 8192), 16, 0, 0); } while (0)
; #define PG8_LDA(dst, b, h) do { _Pragma("unroll") for (int m = 0; m < 4; ++m) _Pragma("unroll") for (int k = 0; k < 2; ++k) dst[m][k] = *(const LAS bf16x8*)(pA + PG8_SA(b, h) + m * 2048 + k * 1024); } while (0)
; #define PG8_LDB(dst, b, h) do { _Pragma("unroll") for (int n = 0; n < 2; ++n) _Pragma("unroll") for (int k = 0; k < 2; ++k) dst[n][k] = *(const LAS bf16x8*)(pB + (PG8_SB(b, h) - 4 * HTB) + n * 2048 + k * 1024); } while (0)
; #define PG8_MMA(ai, bj, At, Bt) do { __builtin_amdgcn_s_setprio(1); _Pragma("unroll") for (int m = 0; m < 4; ++m) _Pragma("unroll") for (int n = 0; n < 2; ++n) _Pragma("unroll") for (int k = 0; k < 2; ++k) \
;         acc[ai][bj][m][n] = __builtin_amdgcn_mfma_f32_16x16x32_bf16(Bt[n][k], At[m][k], acc[ai][bj][m][n], 0, 0, 0); __builtin_amdgcn_s_setprio(0); } while (0)
; #define PG8_WAIT_V(n) asm volatile("s_waitcnt vmcnt(" #n ")" ::: "memory")
; #define PG8_BAR __builtin_amdgcn_s_barrier()
; template <class Desc, class Epi, bool ALIGN_EPI>
; __device__ __forceinline__ void gemm_phase(LAS unsigned char* lds, const Desc& D, const Epi& E, int G, int c) {
;     ...
;         for (int t = 0; t < nt; t += 2) {
;             const bool last = (t == nt - 2);
;             if (last && has_next) PG8_AWAIT(nxt);
;             const char* a1 = cA + (size_t)(t + 1) * kstep;
;             const char* a2 = last ? nA : cA + (size_t)(t + 2) * kstep; const char* b2 = last ? nB : cB + (size_t)(t + 2) * kstep;
;             const char* a3 = a2 + kstep; const char* b3 = b2 + kstep;
;             PG8_LDB(B0, 0, 0); PG8_LDB(B1, 0, 1); PG8_SCHED; PG8_LDA(At, 0, 0); PG8_STAGE(PG8_SA(1, 1), a1 + hstepA, voffA);
;             PG8_WAIT_V(8); PG8_WAIT_L(0); PG8_BAR; PG8_MMA(0, 0, At, B0); PG8_MMA(0, 1, At, B1); PG8_BAR; PG8_SCHED;
;             PG8_LDA(At, 0, 1); PG8_STAGE(PG8_SB(0, 0), b2, voffB); PG8_STAGE(PG8_SB(0, 1), b2 + hstepB, voffB); PG8_STAGE(PG8_SA(0, 0), a2, voffA);
;             PG8_WAIT_V(8); PG8_WAIT_L(0); PG8_BAR; PG8_MMA(1, 0, At, B0); PG8_MMA(1, 1, At, B1); PG8_BAR; PG8_SCHED;
.LBB0_1580:
	s_or_b32 s14, s30, 1
	s_add_i32 s30, s30, 2
	s_mov_b32 s31, s15
	s_lshl_b64 s[72:73], s[14:15], 7
	s_lshl_b64 s[74:75], s[30:31], 7
	s_add_u32 s14, s18, s74
	ds_read_b128 v[140:143], v163
	ds_read_b128 v[144:147], v163 offset:1024
	ds_read_b128 v[148:151], v163 offset:2048
	ds_read_b128 v[152:155], v163 offset:3072
	ds_read_b128 v[156:159], v163 offset:16384
	ds_read_b128 v[166:169], v163 offset:17408
	ds_read_b128 v[170:173], v163 offset:18432
	ds_read_b128 v[174:177], v163 offset:19456
	s_addc_u32 s31, s19, s75
	s_and_b64 s[46:47], s[34:35], exec
	s_cselect_b32 s47, s43, s31
	s_cselect_b32 s46, s42, s14
	s_add_u32 s14, s20, s74
	s_addc_u32 s31, s21, s75
	s_and_b64 s[34:35], s[34:35], exec
	s_cselect_b32 s35, s3, s31
	s_cselect_b32 s34, s13, s14
	s_add_u32 s14, s18, s72
	s_addc_u32 s31, s19, s73
	s_add_u32 s72, s14, 0x100000
	s_addc_u32 s73, s31, 0
	s_add_i32 m0, s52, 0xc000
	ds_read_b128 v[178:181], v162
	ds_read_b128 v[182:185], v162 offset:1024
	ds_read_b128 v[186:189], v162 offset:2048
	ds_read_b128 v[190:193], v162 offset:3072
	ds_read_b128 v[194:197], v162 offset:4096
	ds_read_b128 v[198:201], v162 offset:5120
	ds_read_b128 v[202:205], v162 offset:6144
	ds_read_b128 v[206:209], v162 offset:7168
	global_load_lds_dwordx4 v132, s[72:73]
	s_add_i32 m0, s52, 0xe000
	s_nop 0
	global_load_lds_dwordx4 v136, s[72:73]
	s_waitcnt vmcnt(8)
	s_waitcnt lgkmcnt(0)
	s_barrier
	v_mfma_f32_16x16x32_bf16 v[128:131], v[140:143], v[178:181], v[128:131]
	v_mfma_f32_16x16x32_bf16 v[120:123], v[140:143], v[186:189], v[120:123]
	v_mfma_f32_16x16x32_bf16 v[112:115], v[140:143], v[194:197], v[112:115]
	v_mfma_f32_16x16x32_bf16 v[104:107], v[140:143], v[202:205], v[104:107]
	v_mfma_f32_16x16x32_bf16 v[124:127], v[148:151], v[178:181], v[124:127]
	v_mfma_f32_16x16x32_bf16 v[116:119], v[148:151], v[186:189], v[116:119]
	v_mfma_f32_16x16x32_bf16 v[108:111], v[148:151], v[194:197], v[108:111]
	v_mfma_f32_16x16x32_bf16 v[100:103], v[148:151], v[202:205], v[100:103]
	v_mfma_f32_16x16x32_bf16 v[128:131], v[144:147], v[182:185], v[128:131]
	v_mfma_f32_16x16x32_bf16 v[120:123], v[144:147], v[190:193], v[120:123]
	v_mfma_f32_16x16x32_bf16 v[112:115], v[144:147], v[198:201], v[112:115]
	v_mfma_f32_16x16x32_bf16 v[104:107], v[144:147], v[206:209], v[104:107]
	v_mfma_f32_16x16x32_bf16 v[124:127], v[152:155], v[182:185], v[124:127]
	v_mfma_f32_16x16x32_bf16 v[116:119], v[152:155], v[190:193], v[116:119]
	v_mfma_f32_16x16x32_bf16 v[108:111], v[152:155], v[198:201], v[108:111]
	v_mfma_f32_16x16x32_bf16 v[100:103], v[152:155], v[206:209], v[100:103]
	v_mfma_f32_16x16x32_bf16 v[96:99], v[156:159], v[178:181], v[96:99]
	v_mfma_f32_16x16x32_bf16 v[88:91], v[156:159], v[186:189], v[88:91]
	v_mfma_f32_16x16x32_bf16 v[80:83], v[156:159], v[194:197], v[80:83]
	v_mfma_f32_16x16x32_bf16 v[72:75], v[156:159], v[202:205], v[72:75]
	v_mfma_f32_16x16x32_bf16 v[92:95], v[170:173], v[178:181], v[92:95]
	v_mfma_f32_16x16x32_bf16 v[84:87], v[170:173], v[186:189], v[84:87]
	v_mfma_f32_16x16x32_bf16 v[76:79], v[170:173], v[194:197], v[76:79]
	v_mfma_f32_16x16x32_bf16 v[68:71], v[170:173], v[202:205], v[68:71]
	v_mfma_f32_16x16x32_bf16 v[96:99], v[166:169], v[182:185], v[96:99]
	v_mfma_f32_16x16x32_bf16 v[88:91], v[166:169], v[190:193], v[88:91]
	v_mfma_f32_16x16x32_bf16 v[80:83], v[166:169], v[198:201], v[80:83]
	v_mfma_f32_16x16x32_bf16 v[72:75], v[166:169], v[206:209], v[72:75]
	v_mfma_f32_16x16x32_bf16 v[92:95], v[174:177], v[182:185], v[92:95]
	v_mfma_f32_16x16x32_bf16 v[84:87], v[174:177], v[190:193], v[84:87]
	v_mfma_f32_16x16x32_bf16 v[76:79], v[174:177], v[198:201], v[76:79]
	v_mfma_f32_16x16x32_bf16 v[68:71], v[174:177], v[206:209], v[68:71]
	s_barrier
	s_mov_b32 m0, s53
	s_add_u32 s72, s34, 0x100000
	s_addc_u32 s73, s35, 0
	ds_read_b128 v[178:181], v162 offset:16384
	ds_read_b128 v[182:185], v162 offset:17408
	ds_read_b128 v[186:189], v162 offset:18432
	ds_read_b128 v[190:193], v162 offset:19456
	ds_read_b128 v[194:197], v162 offset:20480
	ds_read_b128 v[198:201], v162 offset:21504
	ds_read_b128 v[202:205], v162 offset:22528
	ds_read_b128 v[206:209], v162 offset:23552
	global_load_lds_dwordx4 v134, s[34:35]
	s_mov_b32 m0, s54
	s_nop 0
	global_load_lds_dwordx4 v138, s[34:35]
	s_mov_b32 m0, s55
	s_nop 0
	global_load_lds_dwordx4 v134, s[72:73]
	s_mov_b32 m0, s56
	s_nop 0
	global_load_lds_dwordx4 v138, s[72:73]
	s_mov_b32 m0, s52
	s_nop 0
	global_load_lds_dwordx4 v132, s[46:47]
	s_mov_b32 m0, s57
	s_nop 0
	global_load_lds_dwordx4 v136, s[46:47]
	s_waitcnt vmcnt(8)
	s_waitcnt lgkmcnt(0)
	s_barrier
; #define PG8_STAGE(bufoff, gbase, voff) do { _Pragma("unroll") for (int _i = 0; _i < 2; ++_i) \
;         __builtin_amdgcn_global_load_lds((const unsigned*)((const char*)(gbase) + (voff)[_i]), (LAS unsigned*)(lds + (bufoff) + ldsw + _i * 8192), 16, 0, 0); } while (0)
; #define PG8_LDA(dst, b, h) do { _Pragma("unroll") for (int m = 0; m < 4; ++m) _Pragma("unroll") for (int k = 0; k < 2; ++k) dst[m][k] = *(const LAS bf16x8*)(pA + PG8_SA(b, h) + m * 2048 + k * 1024); } while (0)
; #define PG8_LDB(dst, b, h) do { _Pragma("unroll") for (int n = 0; n < 2; ++n) _Pragma("unroll") for (int k = 0; k < 2; ++k) dst[n][k] = *(const LAS bf16x8*)(pB + (PG8_SB(b, h) - 4 * HTB) + n * 2048 + k * 1024); } while (0)
; #define PG8_MMA(ai, bj, At, Bt) do { __builtin_amdgcn_s_setprio(1); _Pragma("unroll") for (int m = 0; m < 4; ++m) _Pragma("unroll") for (int n = 0; n < 2; ++n) _Pragma("unroll") for (int k = 0; k < 2; ++k) \
;         acc[ai][bj][m][n] = __builtin_amdgcn_mfma_f32_16x16x32_bf16(Bt[n][k], At[m][k], acc[ai][bj][m][n], 0, 0, 0); __builtin_amdgcn_s_setprio(0); } while (0)
; #define PG8_WAIT_V(n) asm volatile("s_waitcnt vmcnt(" #n ")" ::: "memory")
; #define PG8_WAIT_L(n) asm volatile("s_waitcnt lgkmcnt(" #n ")" ::: "memory")
; #define PG8_BAR __builtin_amdgcn_s_barrier()
; #define PG8_SCHED __builtin_amdgcn_sched_barrier(0)
; template <class Desc, class Epi, bool ALIGN_EPI>
; __device__ __forceinline__ void gemm_phase(LAS unsigned char* lds, const Desc& D, const Epi& E, int G, int c) {
;     ...
;             PG8_WAIT_V(8); PG8_WAIT_L(0); PG8_BAR; PG8_MMA(1, 0, At, B0); PG8_MMA(1, 1, At, B1); PG8_BAR; PG8_SCHED;
;             PG8_LDB(B0, 1, 0); PG8_LDB(B1, 1, 1); PG8_SCHED; PG8_LDA(At, 1, 0); PG8_STAGE(PG8_SA(0, 1), a2 + hstepA, voffA);
;             PG8_WAIT_V(8); PG8_WAIT_L(0); PG8_BAR; PG8_MMA(0, 0, At, B0); PG8_MMA(0, 1, At, B1); PG8_BAR; PG8_SCHED;
	v_mfma_f32_16x16x32_bf16 v[64:67], v[140:143], v[178:181], v[64:67]
	v_mfma_f32_16x16x32_bf16 v[32:35], v[140:143], v[186:189], v[32:35]
	v_mfma_f32_16x16x32_bf16 v[16:19], v[140:143], v[194:197], v[16:19]
	v_mfma_f32_16x16x32_bf16 v[8:11], v[140:143], v[202:205], v[8:11]
	v_mfma_f32_16x16x32_bf16 v[52:55], v[148:151], v[178:181], v[52:55]
	v_mfma_f32_16x16x32_bf16 v[20:23], v[148:151], v[186:189], v[20:23]
	v_mfma_f32_16x16x32_bf16 v[12:15], v[148:151], v[194:197], v[12:15]
	v_mfma_f32_16x16x32_bf16 v[4:7], v[148:151], v[202:205], v[4:7]
	v_mfma_f32_16x16x32_bf16 v[64:67], v[144:147], v[182:185], v[64:67]
	v_mfma_f32_16x16x32_bf16 v[32:35], v[144:147], v[190:193], v[32:35]
	v_mfma_f32_16x16x32_bf16 v[16:19], v[144:147], v[198:201], v[16:19]
	v_mfma_f32_16x16x32_bf16 v[8:11], v[144:147], v[206:209], v[8:11]
	v_mfma_f32_16x16x32_bf16 v[52:55], v[152:155], v[182:185], v[52:55]
	v_mfma_f32_16x16x32_bf16 v[20:23], v[152:155], v[190:193], v[20:23]
	v_mfma_f32_16x16x32_bf16 v[12:15], v[152:155], v[198:201], v[12:15]
	v_mfma_f32_16x16x32_bf16 v[4:7], v[152:155], v[206:209], v[4:7]
	v_mfma_f32_16x16x32_bf16 v[60:63], v[156:159], v[178:181], v[60:63]
	v_mfma_f32_16x16x32_bf16 v[48:51], v[156:159], v[186:189], v[48:51]
	v_mfma_f32_16x16x32_bf16 v[40:43], v[156:159], v[194:197], v[40:43]
	v_mfma_f32_16x16x32_bf16 v[28:31], v[156:159], v[202:205], v[28:31]
	v_mfma_f32_16x16x32_bf16 v[56:59], v[170:173], v[178:181], v[56:59]
	v_mfma_f32_16x16x32_bf16 v[44:47], v[170:173], v[186:189], v[44:47]
	v_mfma_f32_16x16x32_bf16 v[36:39], v[170:173], v[194:197], v[36:39]
	v_mfma_f32_16x16x32_bf16 v[24:27], v[170:173], v[202:205], v[24:27]
	v_mfma_f32_16x16x32_bf16 v[60:63], v[166:169], v[182:185], v[60:63]
	v_mfma_f32_16x16x32_bf16 v[48:51], v[166:169], v[190:193], v[48:51]
	v_mfma_f32_16x16x32_bf16 v[40:43], v[166:169], v[198:201], v[40:43]
	v_mfma_f32_16x16x32_bf16 v[28:31], v[166:169], v[206:209], v[28:31]
	v_mfma_f32_16x16x32_bf16 v[56:59], v[174:177], v[182:185], v[56:59]
	v_mfma_f32_16x16x32_bf16 v[44:47], v[174:177], v[190:193], v[44:47]
	v_mfma_f32_16x16x32_bf16 v[36:39], v[174:177], v[198:201], v[36:39]
	v_mfma_f32_16x16x32_bf16 v[24:27], v[174:177], v[206:209], v[24:27]
	s_barrier
	ds_read_b128 v[140:143], v163 offset:32768
	ds_read_b128 v[144:147], v163 offset:33792
	ds_read_b128 v[148:151], v163 offset:34816
	ds_read_b128 v[152:155], v163 offset:35840
	ds_read_b128 v[156:159], v163 offset:49152
	ds_read_b128 v[166:169], v163 offset:50176
	ds_read_b128 v[170:173], v163 offset:51200
	ds_read_b128 v[174:177], v163 offset:52224
	s_add_u32 s46, s46, 0x100000
	s_addc_u32 s47, s47, 0
	s_mov_b32 m0, s58
	ds_read_b128 v[178:181], v162 offset:32768
	ds_read_b128 v[182:185], v162 offset:33792
	ds_read_b128 v[186:189], v162 offset:34816
	ds_read_b128 v[190:193], v162 offset:35840
	ds_read_b128 v[194:197], v162 offset:36864
	ds_read_b128 v[198:201], v162 offset:37888
	ds_read_b128 v[202:205], v162 offset:38912
	ds_read_b128 v[206:209], v162 offset:39936
	global_load_lds_dwordx4 v132, s[46:47]
	s_mov_b32 m0, s59
	s_nop 0
	global_load_lds_dwordx4 v136, s[46:47]
	s_waitcnt vmcnt(8)
	s_waitcnt lgkmcnt(0)
	s_barrier
	v_mfma_f32_16x16x32_bf16 v[128:131], v[140:143], v[178:181], v[128:131]
	v_mfma_f32_16x16x32_bf16 v[120:123], v[140:143], v[186:189], v[120:123]
	v_mfma_f32_16x16x32_bf16 v[112:115], v[140:143], v[194:197], v[112:115]
	v_mfma_f32_16x16x32_bf16 v[104:107], v[140:143], v[202:205], v[104:107]
	v_mfma_f32_16x16x32_bf16 v[124:127], v[148:151], v[178:181], v[124:127]
	v_mfma_f32_16x16x32_bf16 v[116:119], v[148:151], v[186:189], v[116:119]
	v_mfma_f32_16x16x32_bf16 v[108:111], v[148:151], v[194:197], v[108:111]
	v_mfma_f32_16x16x32_bf16 v[100:103], v[148:151], v[202:205], v[100:103]
	v_mfma_f32_16x16x32_bf16 v[128:131], v[144:147], v[182:185], v[128:131]
	v_mfma_f32_16x16x32_bf16 v[120:123], v[144:147], v[190:193], v[120:123]
	v_mfma_f32_16x16x32_bf16 v[112:115], v[144:147], v[198:201], v[112:115]
	v_mfma_f32_16x16x32_bf16 v[104:107], v[144:147], v[206:209], v[104:107]
	v_mfma_f32_16x16x32_bf16 v[124:127], v[152:155], v[182:185], v[124:127]
	v_mfma_f32_16x16x32_bf16 v[116:119], v[152:155], v[190:193], v[116:119]
	v_mfma_f32_16x16x32_bf16 v[108:111], v[152:155], v[198:201], v[108:111]
	v_mfma_f32_16x16x32_bf16 v[100:103], v[152:155], v[206:209], v[100:103]
	v_mfma_f32_16x16x32_bf16 v[96:99], v[156:159], v[178:181], v[96:99]
	v_mfma_f32_16x16x32_bf16 v[88:91], v[156:159], v[186:189], v[88:91]
	v_mfma_f32_16x16x32_bf16 v[80:83], v[156:159], v[194:197], v[80:83]
	v_mfma_f32_16x16x32_bf16 v[72:75], v[156:159], v[202:205], v[72:75]
	v_mfma_f32_16x16x32_bf16 v[92:95], v[170:173], v[178:181], v[92:95]
	v_mfma_f32_16x16x32_bf16 v[84:87], v[170:173], v[186:189], v[84:87]
	v_mfma_f32_16x16x32_bf16 v[76:79], v[170:173], v[194:197], v[76:79]
	v_mfma_f32_16x16x32_bf16 v[68:71], v[170:173], v[202:205], v[68:71]
	v_mfma_f32_16x16x32_bf16 v[96:99], v[166:169], v[182:185], v[96:99]
	v_mfma_f32_16x16x32_bf16 v[88:91], v[166:169], v[190:193], v[88:91]
	v_mfma_f32_16x16x32_bf16 v[80:83], v[166:169], v[198:201], v[80:83]
	v_mfma_f32_16x16x32_bf16 v[72:75], v[166:169], v[206:209], v[72:75]
	v_mfma_f32_16x16x32_bf16 v[92:95], v[174:177], v[182:185], v[92:95]
	v_mfma_f32_16x16x32_bf16 v[84:87], v[174:177], v[190:193], v[84:87]
	v_mfma_f32_16x16x32_bf16 v[76:79], v[174:177], v[198:201], v[76:79]
	v_mfma_f32_16x16x32_bf16 v[68:71], v[174:177], v[206:209], v[68:71]
	s_barrier
; #define PG8_STAGE(bufoff, gbase, voff) do { _Pragma("unroll") for (int _i = 0; _i < 2; ++_i) \
;         __builtin_amdgcn_global_load_lds((const unsigned*)((const char*)(gbase) + (voff)[_i]), (LAS unsigned*)(lds + (bufoff) + ldsw + _i * 8192), 16, 0, 0); } while (0)
; #define PG8_LDA(dst, b, h) do { _Pragma("unroll") for (int m = 0; m < 4; ++m) _Pragma("unroll") for (int k = 0; k < 2; ++k) dst[m][k] = *(const LAS bf16x8*)(pA + PG8_SA(b, h) + m * 2048 + k * 1024); } while (0)
; #define PG8_MMA(ai, bj, At, Bt) do { __builtin_amdgcn_s_setprio(1); _Pragma("unroll") for (int m = 0; m < 4; ++m) _Pragma("unroll") for (int n = 0; n < 2; ++n) _Pragma("unroll") for (int k = 0; k < 2; ++k) \
;         acc[ai][bj][m][n] = __builtin_amdgcn_mfma_f32_16x16x32_bf16(Bt[n][k], At[m][k], acc[ai][bj][m][n], 0, 0, 0); __builtin_amdgcn_s_setprio(0); } while (0)
; #define PG8_WAIT_V(n) asm volatile("s_waitcnt vmcnt(" #n ")" ::: "memory")
; #define PG8_WAIT_L(n) asm volatile("s_waitcnt lgkmcnt(" #n ")" ::: "memory")
; #define PG8_BAR __builtin_amdgcn_s_barrier()
; #define PG8_SCHED __builtin_amdgcn_sched_barrier(0)
; template <class Desc, class Epi, bool ALIGN_EPI>
; __device__ __forceinline__ void gemm_phase(LAS unsigned char* lds, const Desc& D, const Epi& E, int G, int c) {
;     ...
;             PG8_LDA(At, 1, 1); PG8_STAGE(PG8_SB(1, 0), b3, voffB); PG8_STAGE(PG8_SB(1, 1), b3 + hstepB, voffB); PG8_STAGE(PG8_SA(1, 0), a3, voffA);
;             PG8_WAIT_V(8); PG8_WAIT_L(0); PG8_BAR; PG8_MMA(1, 0, At, B0); PG8_MMA(1, 1, At, B1); PG8_BAR; PG8_SCHED;
;         }
	s_mov_b32 m0, s61
	s_add_u32 s74, s34, 0x80
	s_addc_u32 s75, s35, 0
	s_add_u32 s34, s34, 0x100080
	s_addc_u32 s35, s35, 0
	ds_read_b128 v[178:181], v162 offset:49152
	ds_read_b128 v[182:185], v162 offset:50176
	ds_read_b128 v[186:189], v162 offset:51200
	ds_read_b128 v[190:193], v162 offset:52224
	ds_read_b128 v[194:197], v162 offset:53248
	ds_read_b128 v[198:201], v162 offset:54272
	ds_read_b128 v[202:205], v162 offset:55296
	ds_read_b128 v[206:209], v162 offset:56320
	global_load_lds_dwordx4 v134, s[74:75]
	s_mov_b32 m0, s62
	s_nop 0
	global_load_lds_dwordx4 v138, s[74:75]
	s_mov_b32 m0, s65
	s_nop 0
	global_load_lds_dwordx4 v134, s[34:35]
	s_mov_b32 m0, s67
	s_nop 0
	global_load_lds_dwordx4 v138, s[34:35]
	s_sub_u32 s74, s46, 0xfff80
	s_subb_u32 s75, s47, 0
	s_mov_b32 m0, s63
	s_nop 0
	global_load_lds_dwordx4 v132, s[74:75]
	s_mov_b32 m0, s64
	s_nop 0
	global_load_lds_dwordx4 v136, s[74:75]
	s_waitcnt vmcnt(8)
	s_waitcnt lgkmcnt(0)
	s_barrier
	v_mfma_f32_16x16x32_bf16 v[64:67], v[140:143], v[178:181], v[64:67]
	v_mfma_f32_16x16x32_bf16 v[32:35], v[140:143], v[186:189], v[32:35]
	v_mfma_f32_16x16x32_bf16 v[16:19], v[140:143], v[194:197], v[16:19]
	v_mfma_f32_16x16x32_bf16 v[8:11], v[140:143], v[202:205], v[8:11]
	v_mfma_f32_16x16x32_bf16 v[52:55], v[148:151], v[178:181], v[52:55]
	v_mfma_f32_16x16x32_bf16 v[20:23], v[148:151], v[186:189], v[20:23]
	v_mfma_f32_16x16x32_bf16 v[12:15], v[148:151], v[194:197], v[12:15]
	v_mfma_f32_16x16x32_bf16 v[4:7], v[148:151], v[202:205], v[4:7]
	v_mfma_f32_16x16x32_bf16 v[64:67], v[144:147], v[182:185], v[64:67]
	v_mfma_f32_16x16x32_bf16 v[32:35], v[144:147], v[190:193], v[32:35]
	v_mfma_f32_16x16x32_bf16 v[16:19], v[144:147], v[198:201], v[16:19]
	v_mfma_f32_16x16x32_bf16 v[8:11], v[144:147], v[206:209], v[8:11]
	v_mfma_f32_16x16x32_bf16 v[52:55], v[152:155], v[182:185], v[52:55]
	v_mfma_f32_16x16x32_bf16 v[20:23], v[152:155], v[190:193], v[20:23]
	v_mfma_f32_16x16x32_bf16 v[12:15], v[152:155], v[198:201], v[12:15]
	v_mfma_f32_16x16x32_bf16 v[4:7], v[152:155], v[206:209], v[4:7]
	v_mfma_f32_16x16x32_bf16 v[60:63], v[156:159], v[178:181], v[60:63]
	v_mfma_f32_16x16x32_bf16 v[48:51], v[156:159], v[186:189], v[48:51]
	v_mfma_f32_16x16x32_bf16 v[40:43], v[156:159], v[194:197], v[40:43]
	v_mfma_f32_16x16x32_bf16 v[28:31], v[156:159], v[202:205], v[28:31]
	v_mfma_f32_16x16x32_bf16 v[56:59], v[170:173], v[178:181], v[56:59]
	v_mfma_f32_16x16x32_bf16 v[44:47], v[170:173], v[186:189], v[44:47]
	v_mfma_f32_16x16x32_bf16 v[36:39], v[170:173], v[194:197], v[36:39]
	v_mfma_f32_16x16x32_bf16 v[24:27], v[170:173], v[202:205], v[24:27]
	v_mfma_f32_16x16x32_bf16 v[60:63], v[166:169], v[182:185], v[60:63]
	v_mfma_f32_16x16x32_bf16 v[48:51], v[166:169], v[190:193], v[48:51]
	v_mfma_f32_16x16x32_bf16 v[40:43], v[166:169], v[198:201], v[40:43]
	v_mfma_f32_16x16x32_bf16 v[28:31], v[166:169], v[206:209], v[28:31]
	v_mfma_f32_16x16x32_bf16 v[56:59], v[174:177], v[182:185], v[56:59]
	v_mfma_f32_16x16x32_bf16 v[44:47], v[174:177], v[190:193], v[44:47]
	v_mfma_f32_16x16x32_bf16 v[36:39], v[174:177], v[198:201], v[36:39]
	v_mfma_f32_16x16x32_bf16 v[24:27], v[174:177], v[206:209], v[24:27]
	s_barrier
	s_cmp_ge_u32 s30, s2
	s_cbranch_scc1 .LBB0_1591

;     __device__ __forceinline__ int nt(const Unit& u) const { return (u.pn >> 1) < 2 ? 22 : 20; }
; #define PG8_STAGE(bufoff, gbase, voff) do { _Pragma("unroll") for (int _i = 0; _i < 2; ++_i) \
;         __builtin_amdgcn_global_load_lds((const unsigned*)((const char*)(gbase) + (voff)[_i]), (LAS unsigned*)(lds + (bufoff) + ldsw + _i * 8192), 16, 0, 0); } while (0)
; #define PG8_LDA(dst, b, h) do { _Pragma("unroll") for (int m = 0; m < 4; ++m) _Pragma("unroll") for (int k = 0; k < 2; ++k) dst[m][k] = *(const LAS bf16x8*)(pA + PG8_SA(b, h) + m * 2048 + k * 1024); } while (0)
; #define PG8_LDB(dst, b, h) do { _Pragma("unroll") for (int n = 0; n < 2; ++n) _Pragma("unroll") for (int k = 0; k < 2; ++k) dst[n][k] = *(const LAS bf16x8*)(pB + (PG8_SB(b, h) - 4 * HTB) + n * 2048 + k * 1024); } while (0)
; #define PG8_MMA(ai, bj, At, Bt) do { __builtin_amdgcn_s_setprio(1); _Pragma("unroll") for (int m = 0; m < 4; ++m) _Pragma("unroll") for (int n = 0; n < 2; ++n) _Pragma("unroll") for (int k = 0; k < 2; ++k) \
;         acc[ai][bj][m][n] = __builtin_amdgcn_mfma_f32_16x16x32_bf16(Bt[n][k], At[m][k], acc[ai][bj][m][n], 0, 0, 0); __builtin_amdgcn_s_setprio(0); } while (0)
; #define PG8_WAIT_V(n) asm volatile("s_waitcnt vmcnt(" #n ")" ::: "memory")
; #define PG8_BAR __builtin_amdgcn_s_barrier()
; template <class Desc, class Epi, bool ALIGN_EPI>
; __device__ __forceinline__ void gemm_phase(LAS unsigned char* lds, const Desc& D, const Epi& E, int G, int c) {
;     ...
;         for (int t = 0; t < nt; t += 2) {
;             const bool last = (t == nt - 2);
;             if (last && has_next) PG8_AWAIT(nxt);
;             const char* a1 = cA + (size_t)(t + 1) * kstep;
;             const char* a2 = last ? nA : cA + (size_t)(t + 2) * kstep; const char* b2 = last ? nB : cB + (size_t)(t + 2) * kstep;
;             const char* a3 = a2 + kstep; const char* b3 = b2 + kstep;
;             PG8_LDB(B0, 0, 0); PG8_LDB(B1, 0, 1); PG8_SCHED; PG8_LDA(At, 0, 0); PG8_STAGE(PG8_SA(1, 1), a1 + hstepA, voffA);
;             PG8_WAIT_V(8); PG8_WAIT_L(0); PG8_BAR; PG8_MMA(0, 0, At, B0); PG8_MMA(0, 1, At, B1); PG8_BAR; PG8_SCHED;
;             PG8_LDA(At, 0, 1); PG8_STAGE(PG8_SB(0, 0), b2, voffB); PG8_STAGE(PG8_SB(0, 1), b2 + hstepB, voffB); PG8_STAGE(PG8_SA(0, 0), a2, voffA);
;             PG8_WAIT_V(8); PG8_WAIT_L(0); PG8_BAR; PG8_MMA(1, 0, At, B0); PG8_MMA(1, 1, At, B1); PG8_BAR; PG8_SCHED;
.LBB0_1765:
	s_or_b32 s14, s39, 1
	s_lshl_b64 s[40:41], s[14:15], 7
	s_add_i32 s14, s39, 2
	s_lshl_b64 s[42:43], s[14:15], 7
	s_add_u32 s39, s12, s42
	s_waitcnt lgkmcnt(0)
	ds_read_b128 v[132:135], v248
	ds_read_b128 v[136:139], v248 offset:1024
	ds_read_b128 v[140:143], v248 offset:2048
	ds_read_b128 v[144:147], v248 offset:3072
	ds_read_b128 v[148:151], v248 offset:16384
	ds_read_b128 v[152:155], v248 offset:17408
	ds_read_b128 v[156:159], v248 offset:18432
	ds_read_b128 v[160:163], v248 offset:19456
	s_addc_u32 s78, s13, s43
	s_and_b64 s[30:31], s[20:21], exec
	s_cselect_b32 s31, s49, s78
	s_cselect_b32 s30, s48, s39
	s_add_u32 s39, s16, s42
	s_addc_u32 s42, s17, s43
	s_and_b64 s[20:21], s[20:21], exec
	s_cselect_b32 s21, s51, s42
	s_cselect_b32 s20, s50, s39
	s_add_u32 s39, s12, s40
	s_addc_u32 s41, s13, s41
	s_add_u32 s40, s39, 0x2b0000
	s_addc_u32 s41, s41, 0
	v_lshl_add_u64 v[196:197], s[40:41], 0, v[200:201]
	s_add_i32 m0, s56, 0xc000
	ds_read_b128 v[164:167], v247
	ds_read_b128 v[168:171], v247 offset:1024
	ds_read_b128 v[172:175], v247 offset:2048
	ds_read_b128 v[176:179], v247 offset:3072
	ds_read_b128 v[180:183], v247 offset:4096
	ds_read_b128 v[184:187], v247 offset:5120
	ds_read_b128 v[188:191], v247 offset:6144
	ds_read_b128 v[192:195], v247 offset:7168
	global_load_lds_dwordx4 v[196:197], off
	v_lshl_add_u64 v[196:197], s[40:41], 0, v[204:205]
	s_add_i32 m0, s56, 0xe000
	s_nop 0
	global_load_lds_dwordx4 v[196:197], off
	s_waitcnt vmcnt(8)
	s_waitcnt lgkmcnt(0)
	s_barrier
	v_mfma_f32_16x16x32_bf16 v[128:131], v[132:135], v[164:167], v[128:131]
	v_mfma_f32_16x16x32_bf16 v[120:123], v[132:135], v[172:175], v[120:123]
	v_mfma_f32_16x16x32_bf16 v[112:115], v[132:135], v[180:183], v[112:115]
	v_mfma_f32_16x16x32_bf16 v[104:107], v[132:135], v[188:191], v[104:107]
	v_mfma_f32_16x16x32_bf16 v[124:127], v[140:143], v[164:167], v[124:127]
	v_mfma_f32_16x16x32_bf16 v[116:119], v[140:143], v[172:175], v[116:119]
	v_mfma_f32_16x16x32_bf16 v[108:111], v[140:143], v[180:183], v[108:111]
	v_mfma_f32_16x16x32_bf16 v[100:103], v[140:143], v[188:191], v[100:103]
	v_mfma_f32_16x16x32_bf16 v[128:131], v[136:139], v[168:171], v[128:131]
	v_mfma_f32_16x16x32_bf16 v[120:123], v[136:139], v[176:179], v[120:123]
	v_mfma_f32_16x16x32_bf16 v[112:115], v[136:139], v[184:187], v[112:115]
	v_mfma_f32_16x16x32_bf16 v[104:107], v[136:139], v[192:195], v[104:107]
	v_mfma_f32_16x16x32_bf16 v[124:127], v[144:147], v[168:171], v[124:127]
	v_mfma_f32_16x16x32_bf16 v[116:119], v[144:147], v[176:179], v[116:119]
	v_mfma_f32_16x16x32_bf16 v[108:111], v[144:147], v[184:187], v[108:111]
	v_mfma_f32_16x16x32_bf16 v[100:103], v[144:147], v[192:195], v[100:103]
	v_mfma_f32_16x16x32_bf16 v[96:99], v[148:151], v[164:167], v[96:99]
	v_mfma_f32_16x16x32_bf16 v[88:91], v[148:151], v[172:175], v[88:91]
	v_mfma_f32_16x16x32_bf16 v[64:67], v[148:151], v[180:183], v[64:67]
	v_mfma_f32_16x16x32_bf16 v[32:35], v[148:151], v[188:191], v[32:35]
	v_mfma_f32_16x16x32_bf16 v[92:95], v[156:159], v[164:167], v[92:95]
	v_mfma_f32_16x16x32_bf16 v[80:83], v[156:159], v[172:175], v[80:83]
	v_mfma_f32_16x16x32_bf16 v[52:55], v[156:159], v[180:183], v[52:55]
	v_mfma_f32_16x16x32_bf16 v[20:23], v[156:159], v[188:191], v[20:23]
	v_mfma_f32_16x16x32_bf16 v[96:99], v[152:155], v[168:171], v[96:99]
	v_mfma_f32_16x16x32_bf16 v[88:91], v[152:155], v[176:179], v[88:91]
	v_mfma_f32_16x16x32_bf16 v[64:67], v[152:155], v[184:187], v[64:67]
	v_mfma_f32_16x16x32_bf16 v[32:35], v[152:155], v[192:195], v[32:35]
	v_mfma_f32_16x16x32_bf16 v[92:95], v[160:163], v[168:171], v[92:95]
	v_mfma_f32_16x16x32_bf16 v[80:83], v[160:163], v[176:179], v[80:83]
	v_mfma_f32_16x16x32_bf16 v[52:55], v[160:163], v[184:187], v[52:55]
	v_mfma_f32_16x16x32_bf16 v[20:23], v[160:163], v[192:195], v[20:23]
	s_barrier
	s_mov_b32 m0, s57
	v_lshl_add_u64 v[196:197], s[20:21], 0, v[202:203]
	s_add_u32 s40, s20, 0x2b0000
	ds_read_b128 v[164:167], v247 offset:16384
	ds_read_b128 v[168:171], v247 offset:17408
	ds_read_b128 v[172:175], v247 offset:18432
	ds_read_b128 v[176:179], v247 offset:19456
	ds_read_b128 v[180:183], v247 offset:20480
	ds_read_b128 v[184:187], v247 offset:21504
	ds_read_b128 v[188:191], v247 offset:22528
	ds_read_b128 v[192:195], v247 offset:23552
	global_load_lds_dwordx4 v[196:197], off
	v_lshl_add_u64 v[198:199], s[20:21], 0, v[206:207]
	s_mov_b32 m0, s58
	s_addc_u32 s41, s21, 0
	global_load_lds_dwordx4 v[198:199], off
	v_lshl_add_u64 v[208:209], s[40:41], 0, v[202:203]
	s_mov_b32 m0, s59
	v_lshl_add_u64 v[210:211], s[30:31], 0, v[204:205]
	global_load_lds_dwordx4 v[208:209], off
	v_lshl_add_u64 v[208:209], s[40:41], 0, v[206:207]
	s_mov_b32 m0, s60
	s_nop 0
	global_load_lds_dwordx4 v[208:209], off
	v_lshl_add_u64 v[208:209], s[30:31], 0, v[200:201]
	s_mov_b32 m0, s56
	s_nop 0
	global_load_lds_dwordx4 v[208:209], off
	s_mov_b32 m0, s61
	s_nop 0
	global_load_lds_dwordx4 v[210:211], off
	s_waitcnt vmcnt(8)
	s_waitcnt lgkmcnt(0)
	s_barrier
; #define PG8_STAGE(bufoff, gbase, voff) do { _Pragma("unroll") for (int _i = 0; _i < 2; ++_i) \
;         __builtin_amdgcn_global_load_lds((const unsigned*)((const char*)(gbase) + (voff)[_i]), (LAS unsigned*)(lds + (bufoff) + ldsw + _i * 8192), 16, 0, 0); } while (0)
; #define PG8_LDA(dst, b, h) do { _Pragma("unroll") for (int m = 0; m < 4; ++m) _Pragma("unroll") for (int k = 0; k < 2; ++k) dst[m][k] = *(const LAS bf16x8*)(pA + PG8_SA(b, h) + m * 2048 + k * 1024); } while (0)
; #define PG8_LDB(dst, b, h) do { _Pragma("unroll") for (int n = 0; n < 2; ++n) _Pragma("unroll") for (int k = 0; k < 2; ++k) dst[n][k] = *(const LAS bf16x8*)(pB + (PG8_SB(b, h) - 4 * HTB) + n * 2048 + k * 1024); } while (0)
; #define PG8_MMA(ai, bj, At, Bt) do { __builtin_amdgcn_s_setprio(1); _Pragma("unroll") for (int m = 0; m < 4; ++m) _Pragma("unroll") for (int n = 0; n < 2; ++n) _Pragma("unroll") for (int k = 0; k < 2; ++k) \
;         acc[ai][bj][m][n] = __builtin_amdgcn_mfma_f32_16x16x32_bf16(Bt[n][k], At[m][k], acc[ai][bj][m][n], 0, 0, 0); __builtin_amdgcn_s_setprio(0); } while (0)
; #define PG8_WAIT_V(n) asm volatile("s_waitcnt vmcnt(" #n ")" ::: "memory")
; #define PG8_WAIT_L(n) asm volatile("s_waitcnt lgkmcnt(" #n ")" ::: "memory")
; #define PG8_BAR __builtin_amdgcn_s_barrier()
; #define PG8_SCHED __builtin_amdgcn_sched_barrier(0)
; template <class Desc, class Epi, bool ALIGN_EPI>
; __device__ __forceinline__ void gemm_phase(LAS unsigned char* lds, const Desc& D, const Epi& E, int G, int c) {
;     ...
;             PG8_WAIT_V(8); PG8_WAIT_L(0); PG8_BAR; PG8_MMA(1, 0, At, B0); PG8_MMA(1, 1, At, B1); PG8_BAR; PG8_SCHED;
;             PG8_LDB(B0, 1, 0); PG8_LDB(B1, 1, 1); PG8_SCHED; PG8_LDA(At, 1, 0); PG8_STAGE(PG8_SA(0, 1), a2 + hstepA, voffA);
;             PG8_WAIT_V(8); PG8_WAIT_L(0); PG8_BAR; PG8_MMA(0, 0, At, B0); PG8_MMA(0, 1, At, B1); PG8_BAR; PG8_SCHED;
	v_mfma_f32_16x16x32_bf16 v[84:87], v[132:135], v[164:167], v[84:87]
	v_mfma_f32_16x16x32_bf16 v[72:75], v[132:135], v[172:175], v[72:75]
	v_mfma_f32_16x16x32_bf16 v[60:63], v[132:135], v[180:183], v[60:63]
	v_mfma_f32_16x16x32_bf16 v[48:51], v[132:135], v[188:191], v[48:51]
	v_mfma_f32_16x16x32_bf16 v[76:79], v[140:143], v[164:167], v[76:79]
	v_mfma_f32_16x16x32_bf16 v[68:71], v[140:143], v[172:175], v[68:71]
	v_mfma_f32_16x16x32_bf16 v[56:59], v[140:143], v[180:183], v[56:59]
	v_mfma_f32_16x16x32_bf16 v[44:47], v[140:143], v[188:191], v[44:47]
	v_mfma_f32_16x16x32_bf16 v[84:87], v[136:139], v[168:171], v[84:87]
	v_mfma_f32_16x16x32_bf16 v[72:75], v[136:139], v[176:179], v[72:75]
	v_mfma_f32_16x16x32_bf16 v[60:63], v[136:139], v[184:187], v[60:63]
	v_mfma_f32_16x16x32_bf16 v[48:51], v[136:139], v[192:195], v[48:51]
	v_mfma_f32_16x16x32_bf16 v[76:79], v[144:147], v[168:171], v[76:79]
	v_mfma_f32_16x16x32_bf16 v[68:71], v[144:147], v[176:179], v[68:71]
	v_mfma_f32_16x16x32_bf16 v[56:59], v[144:147], v[184:187], v[56:59]
	v_mfma_f32_16x16x32_bf16 v[44:47], v[144:147], v[192:195], v[44:47]
	v_mfma_f32_16x16x32_bf16 v[40:43], v[148:151], v[164:167], v[40:43]
	v_mfma_f32_16x16x32_bf16 v[28:31], v[148:151], v[172:175], v[28:31]
	v_mfma_f32_16x16x32_bf16 v[16:19], v[148:151], v[180:183], v[16:19]
	v_mfma_f32_16x16x32_bf16 v[8:11], v[148:151], v[188:191], v[8:11]
	v_mfma_f32_16x16x32_bf16 v[36:39], v[156:159], v[164:167], v[36:39]
	v_mfma_f32_16x16x32_bf16 v[24:27], v[156:159], v[172:175], v[24:27]
	v_mfma_f32_16x16x32_bf16 v[12:15], v[156:159], v[180:183], v[12:15]
	v_mfma_f32_16x16x32_bf16 v[4:7], v[156:159], v[188:191], v[4:7]
	v_mfma_f32_16x16x32_bf16 v[40:43], v[152:155], v[168:171], v[40:43]
	v_mfma_f32_16x16x32_bf16 v[28:31], v[152:155], v[176:179], v[28:31]
	v_mfma_f32_16x16x32_bf16 v[16:19], v[152:155], v[184:187], v[16:19]
	v_mfma_f32_16x16x32_bf16 v[8:11], v[152:155], v[192:195], v[8:11]
	v_mfma_f32_16x16x32_bf16 v[36:39], v[160:163], v[168:171], v[36:39]
	v_mfma_f32_16x16x32_bf16 v[24:27], v[160:163], v[176:179], v[24:27]
	v_mfma_f32_16x16x32_bf16 v[12:15], v[160:163], v[184:187], v[12:15]
	v_mfma_f32_16x16x32_bf16 v[4:7], v[160:163], v[192:195], v[4:7]
	s_barrier
	ds_read_b128 v[132:135], v248 offset:32768
	ds_read_b128 v[136:139], v248 offset:33792
	ds_read_b128 v[140:143], v248 offset:34816
	ds_read_b128 v[144:147], v248 offset:35840
	ds_read_b128 v[148:151], v248 offset:49152
	ds_read_b128 v[152:155], v248 offset:50176
	ds_read_b128 v[156:159], v248 offset:51200
	ds_read_b128 v[160:163], v248 offset:52224
	s_add_u32 s30, s30, 0x2b0000
	s_addc_u32 s31, s31, 0
	s_mov_b32 m0, s62
	v_lshl_add_u64 v[212:213], s[30:31], 0, v[200:201]
	ds_read_b128 v[164:167], v247 offset:32768
	ds_read_b128 v[168:171], v247 offset:33792
	ds_read_b128 v[172:175], v247 offset:34816
	ds_read_b128 v[176:179], v247 offset:35840
	ds_read_b128 v[180:183], v247 offset:36864
	ds_read_b128 v[184:187], v247 offset:37888
	ds_read_b128 v[188:191], v247 offset:38912
	ds_read_b128 v[192:195], v247 offset:39936
	global_load_lds_dwordx4 v[212:213], off
	v_lshl_add_u64 v[212:213], s[30:31], 0, v[204:205]
	s_mov_b32 m0, s63
	s_nop 0
	global_load_lds_dwordx4 v[212:213], off
	s_waitcnt vmcnt(8)
	s_waitcnt lgkmcnt(0)
	s_barrier
	v_mfma_f32_16x16x32_bf16 v[128:131], v[132:135], v[164:167], v[128:131]
	v_mfma_f32_16x16x32_bf16 v[120:123], v[132:135], v[172:175], v[120:123]
	v_mfma_f32_16x16x32_bf16 v[112:115], v[132:135], v[180:183], v[112:115]
	v_mfma_f32_16x16x32_bf16 v[104:107], v[132:135], v[188:191], v[104:107]
	v_mfma_f32_16x16x32_bf16 v[124:127], v[140:143], v[164:167], v[124:127]
	v_mfma_f32_16x16x32_bf16 v[116:119], v[140:143], v[172:175], v[116:119]
	v_mfma_f32_16x16x32_bf16 v[108:111], v[140:143], v[180:183], v[108:111]
	v_mfma_f32_16x16x32_bf16 v[100:103], v[140:143], v[188:191], v[100:103]
	v_mfma_f32_16x16x32_bf16 v[128:131], v[136:139], v[168:171], v[128:131]
	v_mfma_f32_16x16x32_bf16 v[120:123], v[136:139], v[176:179], v[120:123]
	v_mfma_f32_16x16x32_bf16 v[112:115], v[136:139], v[184:187], v[112:115]
	v_mfma_f32_16x16x32_bf16 v[104:107], v[136:139], v[192:195], v[104:107]
	v_mfma_f32_16x16x32_bf16 v[124:127], v[144:147], v[168:171], v[124:127]
	v_mfma_f32_16x16x32_bf16 v[116:119], v[144:147], v[176:179], v[116:119]
	v_mfma_f32_16x16x32_bf16 v[108:111], v[144:147], v[184:187], v[108:111]
	v_mfma_f32_16x16x32_bf16 v[100:103], v[144:147], v[192:195], v[100:103]
	v_mfma_f32_16x16x32_bf16 v[96:99], v[148:151], v[164:167], v[96:99]
	v_mfma_f32_16x16x32_bf16 v[88:91], v[148:151], v[172:175], v[88:91]
	v_mfma_f32_16x16x32_bf16 v[64:67], v[148:151], v[180:183], v[64:67]
	v_mfma_f32_16x16x32_bf16 v[32:35], v[148:151], v[188:191], v[32:35]
	v_mfma_f32_16x16x32_bf16 v[92:95], v[156:159], v[164:167], v[92:95]
	v_mfma_f32_16x16x32_bf16 v[80:83], v[156:159], v[172:175], v[80:83]
	v_mfma_f32_16x16x32_bf16 v[52:55], v[156:159], v[180:183], v[52:55]
	v_mfma_f32_16x16x32_bf16 v[20:23], v[156:159], v[188:191], v[20:23]
	v_mfma_f32_16x16x32_bf16 v[96:99], v[152:155], v[168:171], v[96:99]
	v_mfma_f32_16x16x32_bf16 v[88:91], v[152:155], v[176:179], v[88:91]
	v_mfma_f32_16x16x32_bf16 v[64:67], v[152:155], v[184:187], v[64:67]
	v_mfma_f32_16x16x32_bf16 v[32:35], v[152:155], v[192:195], v[32:35]
	v_mfma_f32_16x16x32_bf16 v[92:95], v[160:163], v[168:171], v[92:95]
	v_mfma_f32_16x16x32_bf16 v[80:83], v[160:163], v[176:179], v[80:83]
	v_mfma_f32_16x16x32_bf16 v[52:55], v[160:163], v[184:187], v[52:55]
	v_mfma_f32_16x16x32_bf16 v[20:23], v[160:163], v[192:195], v[20:23]
	s_barrier
; #define PG8_STAGE(bufoff, gbase, voff) do { _Pragma("unroll") for (int _i = 0; _i < 2; ++_i) \
;         __builtin_amdgcn_global_load_lds((const unsigned*)((const char*)(gbase) + (voff)[_i]), (LAS unsigned*)(lds + (bufoff) + ldsw + _i * 8192), 16, 0, 0); } while (0)
; #define PG8_LDA(dst, b, h) do { _Pragma("unroll") for (int m = 0; m < 4; ++m) _Pragma("unroll") for (int k = 0; k < 2; ++k) dst[m][k] = *(const LAS bf16x8*)(pA + PG8_SA(b, h) + m * 2048 + k * 1024); } while (0)
; #define PG8_MMA(ai, bj, At, Bt) do { __builtin_amdgcn_s_setprio(1); _Pragma("unroll") for (int m = 0; m < 4; ++m) _Pragma("unroll") for (int n = 0; n < 2; ++n) _Pragma("unroll") for (int k = 0; k < 2; ++k) \
;         acc[ai][bj][m][n] = __builtin_amdgcn_mfma_f32_16x16x32_bf16(Bt[n][k], At[m][k], acc[ai][bj][m][n], 0, 0, 0); __builtin_amdgcn_s_setprio(0); } while (0)
; #define PG8_WAIT_V(n) asm volatile("s_waitcnt vmcnt(" #n ")" ::: "memory")
; #define PG8_WAIT_L(n) asm volatile("s_waitcnt lgkmcnt(" #n ")" ::: "memory")
; #define PG8_BAR __builtin_amdgcn_s_barrier()
; #define PG8_SCHED __builtin_amdgcn_sched_barrier(0)
; template <class Desc, class Epi, bool ALIGN_EPI>
; __device__ __forceinline__ void gemm_phase(LAS unsigned char* lds, const Desc& D, const Epi& E, int G, int c) {
;     ...
;             PG8_LDA(At, 1, 1); PG8_STAGE(PG8_SB(1, 0), b3, voffB); PG8_STAGE(PG8_SB(1, 1), b3 + hstepB, voffB); PG8_STAGE(PG8_SA(1, 0), a3, voffA);
;             PG8_WAIT_V(8); PG8_WAIT_L(0); PG8_BAR; PG8_MMA(1, 0, At, B0); PG8_MMA(1, 1, At, B1); PG8_BAR; PG8_SCHED;
;         }
	s_mov_b32 m0, s64
	v_lshl_add_u64 v[196:197], v[196:197], 0, s[76:77]
	s_add_u32 s20, s20, 0x2b0080
	ds_read_b128 v[164:167], v247 offset:49152
	ds_read_b128 v[168:171], v247 offset:50176
	ds_read_b128 v[172:175], v247 offset:51200
	ds_read_b128 v[176:179], v247 offset:52224
	ds_read_b128 v[180:183], v247 offset:53248
	ds_read_b128 v[184:187], v247 offset:54272
	ds_read_b128 v[188:191], v247 offset:55296
	ds_read_b128 v[192:195], v247 offset:56320
	global_load_lds_dwordx4 v[196:197], off
	v_lshl_add_u64 v[196:197], v[198:199], 0, s[76:77]
	s_mov_b32 m0, s65
	s_addc_u32 s21, s21, 0
	global_load_lds_dwordx4 v[196:197], off
	v_lshl_add_u64 v[196:197], s[20:21], 0, v[202:203]
	s_mov_b32 m0, s69
	s_nop 0
	global_load_lds_dwordx4 v[196:197], off
	v_lshl_add_u64 v[196:197], s[20:21], 0, v[206:207]
	s_mov_b32 m0, s70
	s_nop 0
	global_load_lds_dwordx4 v[196:197], off
	v_lshl_add_u64 v[196:197], v[208:209], 0, s[76:77]
	s_mov_b32 m0, s66
	s_nop 0
	global_load_lds_dwordx4 v[196:197], off
	v_lshl_add_u64 v[196:197], v[210:211], 0, s[76:77]
	s_mov_b32 m0, s67
	s_nop 0
	global_load_lds_dwordx4 v[196:197], off
	s_waitcnt vmcnt(8)
	s_waitcnt lgkmcnt(0)
	s_barrier
	v_mfma_f32_16x16x32_bf16 v[84:87], v[132:135], v[164:167], v[84:87]
	v_mfma_f32_16x16x32_bf16 v[72:75], v[132:135], v[172:175], v[72:75]
	v_mfma_f32_16x16x32_bf16 v[60:63], v[132:135], v[180:183], v[60:63]
	v_mfma_f32_16x16x32_bf16 v[48:51], v[132:135], v[188:191], v[48:51]
	v_mfma_f32_16x16x32_bf16 v[76:79], v[140:143], v[164:167], v[76:79]
	v_mfma_f32_16x16x32_bf16 v[68:71], v[140:143], v[172:175], v[68:71]
	v_mfma_f32_16x16x32_bf16 v[56:59], v[140:143], v[180:183], v[56:59]
	v_mfma_f32_16x16x32_bf16 v[44:47], v[140:143], v[188:191], v[44:47]
	v_mfma_f32_16x16x32_bf16 v[84:87], v[136:139], v[168:171], v[84:87]
	v_mfma_f32_16x16x32_bf16 v[72:75], v[136:139], v[176:179], v[72:75]
	v_mfma_f32_16x16x32_bf16 v[60:63], v[136:139], v[184:187], v[60:63]
	v_mfma_f32_16x16x32_bf16 v[48:51], v[136:139], v[192:195], v[48:51]
	v_mfma_f32_16x16x32_bf16 v[76:79], v[144:147], v[168:171], v[76:79]
	v_mfma_f32_16x16x32_bf16 v[68:71], v[144:147], v[176:179], v[68:71]
	v_mfma_f32_16x16x32_bf16 v[56:59], v[144:147], v[184:187], v[56:59]
	v_mfma_f32_16x16x32_bf16 v[44:47], v[144:147], v[192:195], v[44:47]
	v_mfma_f32_16x16x32_bf16 v[40:43], v[148:151], v[164:167], v[40:43]
	v_mfma_f32_16x16x32_bf16 v[28:31], v[148:151], v[172:175], v[28:31]
	v_mfma_f32_16x16x32_bf16 v[16:19], v[148:151], v[180:183], v[16:19]
	v_mfma_f32_16x16x32_bf16 v[8:11], v[148:151], v[188:191], v[8:11]
	v_mfma_f32_16x16x32_bf16 v[36:39], v[156:159], v[164:167], v[36:39]
	v_mfma_f32_16x16x32_bf16 v[24:27], v[156:159], v[172:175], v[24:27]
	v_mfma_f32_16x16x32_bf16 v[12:15], v[156:159], v[180:183], v[12:15]
	v_mfma_f32_16x16x32_bf16 v[4:7], v[156:159], v[188:191], v[4:7]
	v_mfma_f32_16x16x32_bf16 v[40:43], v[152:155], v[168:171], v[40:43]
	v_mfma_f32_16x16x32_bf16 v[28:31], v[152:155], v[176:179], v[28:31]
	v_mfma_f32_16x16x32_bf16 v[16:19], v[152:155], v[184:187], v[16:19]
	v_mfma_f32_16x16x32_bf16 v[8:11], v[152:155], v[192:195], v[8:11]
	v_mfma_f32_16x16x32_bf16 v[36:39], v[160:163], v[168:171], v[36:39]
	v_mfma_f32_16x16x32_bf16 v[24:27], v[160:163], v[176:179], v[24:27]
	v_mfma_f32_16x16x32_bf16 v[12:15], v[160:163], v[184:187], v[12:15]
	v_mfma_f32_16x16x32_bf16 v[4:7], v[160:163], v[192:195], v[4:7]
	s_barrier
	s_cmp_ge_u32 s14, s24
	s_mov_b32 s39, s14
	s_cbranch_scc1 .LBB0_1776
